# more slot trims: m0 pad s_nop replaced by reordering the address add between s_mov m0 and the LDS-DMA load (29 sites); single vmcnt(0) ahead of the next-tile LDS writes in both attention loops
# baseline (speedup 1.0000x reference)
;     __device__ __forceinline__ unsigned* BAR() const { return (unsigned*)(ws + OFF_BAR); }
; #define STAGE(bufoff, gbase, voff) do { _Pragma("unroll") for (int _i = 0; _i < 2; ++_i) \
;         __builtin_amdgcn_global_load_lds((const unsigned*)((const char*)(gbase) + voff[_i]), (LAS unsigned*)(lds + (bufoff) + ldsw + _i * 8192), 16, 0, 0); } while (0)
; #define LDA(dst, b, h) do { _Pragma("unroll") for (int m = 0; m < 4; ++m) _Pragma("unroll") for (int k = 0; k < 2; ++k) dst[m][k] = *(const LAS bf16x8*)(lds + SA(b, h) + aoff + m * 2048 + k * 1024); } while (0)
; #define LDB(dst, b, h) do { _Pragma("unroll") for (int n = 0; n < 2; ++n) _Pragma("unroll") for (int k = 0; k < 2; ++k) dst[n][k] = *(const LAS bf16x8*)(lds + SB(b, h) + boff + n * 2048 + k * 1024); } while (0)
; #define MMA(ai, bj, At, Bx) do { __builtin_amdgcn_s_setprio(1); _Pragma("unroll") for (int m = 0; m < 4; ++m) _Pragma("unroll") for (int n = 0; n < 2; ++n) _Pragma("unroll") for (int k = 0; k < 2; ++k) \
;       acc[ai][bj][m][n] = __builtin_amdgcn_mfma_f32_16x16x32_bf16(At[m][k], Bx[n][k], acc[ai][bj][m][n], 0, 0, 0); \
;     __builtin_amdgcn_s_setprio(0); } while (0)
; #define WAIT_L(n) asm volatile("s_waitcnt lgkmcnt(" #n ")" ::: "memory")
; #define BAR __builtin_amdgcn_s_barrier()
; #define SCHED __builtin_amdgcn_sched_barrier(0)
;     ...
;         const char* a1 = pA(t + 1); const char* a2 = pA(t + 2); const char* a3 = pA(t + 3);
;         const char* b2 = pB(t + 2); const char* b3 = pB(t + 3);
;         LDB(B0, 0, 0); SCHED; LDA(At, 0, 0); STAGE(SA(1, 1), a1 + hstepA, voffA);
;         WAIT_L(8); BAR; WAIT_L(0); MMA(0, 0, At, B0); BAR; SCHED;
;         LDB(B1, 0, 1); STAGE(SB(0, 0), b2, voffB);
;         BAR; WAIT_L(0); MMA(0, 1, At, B1); BAR;
;         LDA(At, 0, 1); STAGE(SA(0, 0), a2, voffA);
;         BAR; WAIT_L(0); MMA(1, 0, At, B0); BAR; SCHED;
.LBB0_227:
	s_add_i32 s9, 0, 0x10000
	v_add_u32_e32 v138, s9, v143
	ds_read_b128 v[144:147], v138
	ds_read_b128 v[148:151], v138 offset:1024
	ds_read_b128 v[152:155], v138 offset:2048
	ds_read_b128 v[156:159], v138 offset:3072
	v_lshl_add_u64 v[138:139], s[4:5], 0, v[136:137]
	s_add_i32 s8, s12, 0xc000
	v_lshl_add_u64 v[214:215], v[138:139], 0, s[36:37]
	s_mov_b32 m0, s8
	v_lshl_add_u64 v[230:231], s[4:5], 0, v[140:141]
	s_add_i32 s7, s12, 0xe000
	ds_read_b128 v[160:163], v142
	ds_read_b128 v[164:167], v142 offset:1024
	ds_read_b128 v[190:193], v142 offset:2048
	ds_read_b128 v[194:197], v142 offset:3072
	ds_read_b128 v[198:201], v142 offset:4096
	ds_read_b128 v[202:205], v142 offset:5120
	ds_read_b128 v[206:209], v142 offset:6144
	ds_read_b128 v[210:213], v142 offset:7168
	global_load_lds_dwordx4 v[214:215], off
	s_mov_b32 m0, s7
	v_lshl_add_u64 v[214:215], v[230:231], 0, s[36:37]
	global_load_lds_dwordx4 v[214:215], off
	s_waitcnt lgkmcnt(8)
	s_barrier
	s_waitcnt lgkmcnt(0)
	v_mfma_f32_16x16x32_bf16 v[126:129], v[160:163], v[144:147], v[126:129]
	v_mfma_f32_16x16x32_bf16 v[122:125], v[160:163], v[152:155], v[122:125]
	v_mfma_f32_16x16x32_bf16 v[118:121], v[190:193], v[144:147], v[118:121]
	v_mfma_f32_16x16x32_bf16 v[114:117], v[190:193], v[152:155], v[114:117]
	v_mfma_f32_16x16x32_bf16 v[110:113], v[198:201], v[144:147], v[110:113]
	v_mfma_f32_16x16x32_bf16 v[106:109], v[198:201], v[152:155], v[106:109]
	v_mfma_f32_16x16x32_bf16 v[102:105], v[206:209], v[144:147], v[102:105]
	v_mfma_f32_16x16x32_bf16 v[98:101], v[206:209], v[152:155], v[98:101]
	v_mfma_f32_16x16x32_bf16 v[126:129], v[164:167], v[148:151], v[126:129]
	v_mfma_f32_16x16x32_bf16 v[122:125], v[164:167], v[156:159], v[122:125]
	v_mfma_f32_16x16x32_bf16 v[118:121], v[194:197], v[148:151], v[118:121]
	v_mfma_f32_16x16x32_bf16 v[114:117], v[194:197], v[156:159], v[114:117]
	v_mfma_f32_16x16x32_bf16 v[110:113], v[202:205], v[148:151], v[110:113]
	v_mfma_f32_16x16x32_bf16 v[106:109], v[202:205], v[156:159], v[106:109]
	v_mfma_f32_16x16x32_bf16 v[102:105], v[210:213], v[148:151], v[102:105]
	v_mfma_f32_16x16x32_bf16 v[98:101], v[210:213], v[156:159], v[98:101]
	s_barrier
	s_add_i32 s16, 0, 0x14000
	v_lshl_add_u64 v[232:233], s[4:5], 0, v[132:133]
	s_add_i32 s9, s9, s11
	v_add_u32_e32 v226, s16, v143
	v_lshl_add_u64 v[234:235], v[232:233], 0, s[38:39]
	s_mov_b32 m0, s9
	ds_read_b128 v[214:217], v226
	ds_read_b128 v[218:221], v226 offset:1024
	ds_read_b128 v[222:225], v226 offset:2048
	ds_read_b128 v[226:229], v226 offset:3072
	global_load_lds_dwordx4 v[234:235], off
	v_lshl_add_u64 v[234:235], s[4:5], 0, v[134:135]
	v_lshl_add_u64 v[236:237], v[234:235], 0, s[38:39]
	s_add_i32 m0, s9, 0x2000
	s_nop 0
	global_load_lds_dwordx4 v[236:237], off
	s_barrier
	s_waitcnt lgkmcnt(0)
	v_mfma_f32_16x16x32_bf16 v[94:97], v[160:163], v[214:217], v[94:97]
	v_mfma_f32_16x16x32_bf16 v[90:93], v[160:163], v[222:225], v[90:93]
	v_mfma_f32_16x16x32_bf16 v[86:89], v[190:193], v[214:217], v[86:89]
	v_mfma_f32_16x16x32_bf16 v[82:85], v[190:193], v[222:225], v[82:85]
	v_mfma_f32_16x16x32_bf16 v[78:81], v[198:201], v[214:217], v[78:81]
	v_mfma_f32_16x16x32_bf16 v[74:77], v[198:201], v[222:225], v[74:77]
	v_mfma_f32_16x16x32_bf16 v[70:73], v[206:209], v[214:217], v[70:73]
	v_mfma_f32_16x16x32_bf16 v[66:69], v[206:209], v[222:225], v[66:69]
	v_mfma_f32_16x16x32_bf16 v[94:97], v[164:167], v[218:221], v[94:97]
	v_mfma_f32_16x16x32_bf16 v[90:93], v[164:167], v[226:229], v[90:93]
	v_mfma_f32_16x16x32_bf16 v[86:89], v[194:197], v[218:221], v[86:89]
	v_mfma_f32_16x16x32_bf16 v[82:85], v[194:197], v[226:229], v[82:85]
	v_mfma_f32_16x16x32_bf16 v[78:81], v[202:205], v[218:221], v[78:81]
	v_mfma_f32_16x16x32_bf16 v[74:77], v[202:205], v[226:229], v[74:77]
	v_mfma_f32_16x16x32_bf16 v[70:73], v[210:213], v[218:221], v[70:73]
	v_mfma_f32_16x16x32_bf16 v[66:69], v[210:213], v[226:229], v[66:69]
	s_barrier
	s_mov_b32 m0, s12
	v_lshl_add_u64 v[236:237], v[138:139], 0, s[40:41]
	ds_read_b128 v[160:163], v142 offset:16384
	ds_read_b128 v[164:167], v142 offset:17408
	ds_read_b128 v[190:193], v142 offset:18432
	ds_read_b128 v[194:197], v142 offset:19456
	ds_read_b128 v[198:201], v142 offset:20480
	ds_read_b128 v[202:205], v142 offset:21504
	ds_read_b128 v[206:209], v142 offset:22528
	ds_read_b128 v[210:213], v142 offset:23552
	global_load_lds_dwordx4 v[236:237], off
	s_mov_b32 m0, s13
	v_lshl_add_u64 v[236:237], v[230:231], 0, s[40:41]
	global_load_lds_dwordx4 v[236:237], off
	s_barrier
	s_waitcnt lgkmcnt(0)
	v_mfma_f32_16x16x32_bf16 v[62:65], v[160:163], v[144:147], v[62:65]
	v_mfma_f32_16x16x32_bf16 v[58:61], v[160:163], v[152:155], v[58:61]
	v_mfma_f32_16x16x32_bf16 v[54:57], v[190:193], v[144:147], v[54:57]
	v_mfma_f32_16x16x32_bf16 v[50:53], v[190:193], v[152:155], v[50:53]
	v_mfma_f32_16x16x32_bf16 v[46:49], v[198:201], v[144:147], v[46:49]
	v_mfma_f32_16x16x32_bf16 v[42:45], v[198:201], v[152:155], v[42:45]
	v_mfma_f32_16x16x32_bf16 v[38:41], v[206:209], v[144:147], v[38:41]
	v_mfma_f32_16x16x32_bf16 v[34:37], v[206:209], v[152:155], v[34:37]
	v_mfma_f32_16x16x32_bf16 v[62:65], v[164:167], v[148:151], v[62:65]
	v_mfma_f32_16x16x32_bf16 v[58:61], v[164:167], v[156:159], v[58:61]
	v_mfma_f32_16x16x32_bf16 v[54:57], v[194:197], v[148:151], v[54:57]
	v_mfma_f32_16x16x32_bf16 v[50:53], v[194:197], v[156:159], v[50:53]
	v_mfma_f32_16x16x32_bf16 v[46:49], v[202:205], v[148:151], v[46:49]
	v_mfma_f32_16x16x32_bf16 v[42:45], v[202:205], v[156:159], v[42:45]
	v_mfma_f32_16x16x32_bf16 v[38:41], v[210:213], v[148:151], v[38:41]
	v_mfma_f32_16x16x32_bf16 v[34:37], v[210:213], v[156:159], v[34:37]
	s_barrier
;     __device__ __forceinline__ unsigned* BAR() const { return (unsigned*)(ws + OFF_BAR); }
; #define STAGE(bufoff, gbase, voff) do { _Pragma("unroll") for (int _i = 0; _i < 2; ++_i) \
;         __builtin_amdgcn_global_load_lds((const unsigned*)((const char*)(gbase) + voff[_i]), (LAS unsigned*)(lds + (bufoff) + ldsw + _i * 8192), 16, 0, 0); } while (0)
; #define LDA(dst, b, h) do { _Pragma("unroll") for (int m = 0; m < 4; ++m) _Pragma("unroll") for (int k = 0; k < 2; ++k) dst[m][k] = *(const LAS bf16x8*)(lds + SA(b, h) + aoff + m * 2048 + k * 1024); } while (0)
; #define LDB(dst, b, h) do { _Pragma("unroll") for (int n = 0; n < 2; ++n) _Pragma("unroll") for (int k = 0; k < 2; ++k) dst[n][k] = *(const LAS bf16x8*)(lds + SB(b, h) + boff + n * 2048 + k * 1024); } while (0)
; #define MMA(ai, bj, At, Bx) do { __builtin_amdgcn_s_setprio(1); _Pragma("unroll") for (int m = 0; m < 4; ++m) _Pragma("unroll") for (int n = 0; n < 2; ++n) _Pragma("unroll") for (int k = 0; k < 2; ++k) \
;       acc[ai][bj][m][n] = __builtin_amdgcn_mfma_f32_16x16x32_bf16(At[m][k], Bx[n][k], acc[ai][bj][m][n], 0, 0, 0); \
;     __builtin_amdgcn_s_setprio(0); } while (0)
; #define WAIT_V(n) asm volatile("s_waitcnt vmcnt(" #n ")" ::: "memory")
; #define WAIT_L(n) asm volatile("s_waitcnt lgkmcnt(" #n ")" ::: "memory")
; #define BAR __builtin_amdgcn_s_barrier()
; #define SCHED __builtin_amdgcn_sched_barrier(0)
;     ...
;         STAGE(SB(0, 1), b2 + hstepB, voffB);
;         WAIT_V(6); BAR; MMA(1, 1, At, B1); BAR;
;         LDB(B0, 1, 0); SCHED; LDA(At, 1, 0); STAGE(SA(0, 1), a2 + hstepA, voffA);
;         WAIT_L(8); BAR; WAIT_L(0); MMA(0, 0, At, B0); BAR; SCHED;
;         LDB(B1, 1, 1); STAGE(SB(1, 0), b3, voffB);
;         BAR; WAIT_L(0); MMA(0, 1, At, B1); BAR;
;         LDA(At, 1, 1); STAGE(SA(1, 0), a3, voffA);
;         BAR; WAIT_L(0); MMA(1, 0, At, B0); BAR; SCHED;
	s_add_i32 s9, s16, s11
	s_mov_b32 m0, s9
	v_lshl_add_u64 v[144:145], v[232:233], 0, s[44:45]
	global_load_lds_dwordx4 v[144:145], off
	v_lshl_add_u64 v[144:145], v[234:235], 0, s[44:45]
	s_add_i32 m0, s9, 0x2000
	s_nop 0
	global_load_lds_dwordx4 v[144:145], off
	s_waitcnt vmcnt(6)
	s_barrier
	v_mfma_f32_16x16x32_bf16 v[30:33], v[160:163], v[214:217], v[30:33]
	v_mfma_f32_16x16x32_bf16 v[26:29], v[160:163], v[222:225], v[26:29]
	v_mfma_f32_16x16x32_bf16 v[22:25], v[190:193], v[214:217], v[22:25]
	v_mfma_f32_16x16x32_bf16 v[18:21], v[190:193], v[222:225], v[18:21]
	v_mfma_f32_16x16x32_bf16 v[14:17], v[198:201], v[214:217], v[14:17]
	v_mfma_f32_16x16x32_bf16 v[10:13], v[198:201], v[222:225], v[10:13]
	v_mfma_f32_16x16x32_bf16 v[6:9], v[206:209], v[214:217], v[6:9]
	v_mfma_f32_16x16x32_bf16 v[2:5], v[206:209], v[222:225], v[2:5]
	v_mfma_f32_16x16x32_bf16 v[30:33], v[164:167], v[218:221], v[30:33]
	v_mfma_f32_16x16x32_bf16 v[26:29], v[164:167], v[226:229], v[26:29]
	v_mfma_f32_16x16x32_bf16 v[22:25], v[194:197], v[218:221], v[22:25]
	v_mfma_f32_16x16x32_bf16 v[18:21], v[194:197], v[226:229], v[18:21]
	v_mfma_f32_16x16x32_bf16 v[14:17], v[202:205], v[218:221], v[14:17]
	v_mfma_f32_16x16x32_bf16 v[10:13], v[202:205], v[226:229], v[10:13]
	v_mfma_f32_16x16x32_bf16 v[6:9], v[210:213], v[218:221], v[6:9]
	v_mfma_f32_16x16x32_bf16 v[2:5], v[210:213], v[226:229], v[2:5]
	s_barrier
	s_add_i32 s9, 0, 0x18000
	v_add_u32_e32 v156, s9, v143
	ds_read_b128 v[144:147], v156
	ds_read_b128 v[148:151], v156 offset:1024
	ds_read_b128 v[152:155], v156 offset:2048
	ds_read_b128 v[156:159], v156 offset:3072
	s_mov_b32 m0, s14
	v_lshl_add_u64 v[214:215], v[138:139], 0, s[46:47]
	ds_read_b128 v[160:163], v142 offset:32768
	ds_read_b128 v[164:167], v142 offset:33792
	ds_read_b128 v[190:193], v142 offset:34816
	ds_read_b128 v[194:197], v142 offset:35840
	ds_read_b128 v[198:201], v142 offset:36864
	ds_read_b128 v[202:205], v142 offset:37888
	ds_read_b128 v[206:209], v142 offset:38912
	ds_read_b128 v[210:213], v142 offset:39936
	global_load_lds_dwordx4 v[214:215], off
	s_mov_b32 m0, s15
	v_lshl_add_u64 v[214:215], v[230:231], 0, s[46:47]
	global_load_lds_dwordx4 v[214:215], off
	s_waitcnt lgkmcnt(8)
	s_barrier
	s_waitcnt lgkmcnt(0)
	v_mfma_f32_16x16x32_bf16 v[126:129], v[160:163], v[144:147], v[126:129]
	v_mfma_f32_16x16x32_bf16 v[122:125], v[160:163], v[152:155], v[122:125]
	v_mfma_f32_16x16x32_bf16 v[118:121], v[190:193], v[144:147], v[118:121]
	v_mfma_f32_16x16x32_bf16 v[114:117], v[190:193], v[152:155], v[114:117]
	v_mfma_f32_16x16x32_bf16 v[110:113], v[198:201], v[144:147], v[110:113]
	v_mfma_f32_16x16x32_bf16 v[106:109], v[198:201], v[152:155], v[106:109]
	v_mfma_f32_16x16x32_bf16 v[102:105], v[206:209], v[144:147], v[102:105]
	v_mfma_f32_16x16x32_bf16 v[98:101], v[206:209], v[152:155], v[98:101]
	v_mfma_f32_16x16x32_bf16 v[126:129], v[164:167], v[148:151], v[126:129]
	v_mfma_f32_16x16x32_bf16 v[122:125], v[164:167], v[156:159], v[122:125]
	v_mfma_f32_16x16x32_bf16 v[118:121], v[194:197], v[148:151], v[118:121]
	v_mfma_f32_16x16x32_bf16 v[114:117], v[194:197], v[156:159], v[114:117]
	v_mfma_f32_16x16x32_bf16 v[110:113], v[202:205], v[148:151], v[110:113]
	v_mfma_f32_16x16x32_bf16 v[106:109], v[202:205], v[156:159], v[106:109]
	v_mfma_f32_16x16x32_bf16 v[102:105], v[210:213], v[148:151], v[102:105]
	v_mfma_f32_16x16x32_bf16 v[98:101], v[210:213], v[156:159], v[98:101]
	s_barrier
	s_add_i32 s16, 0, 0x1c000
	s_add_i32 s9, s9, s11
	v_add_u32_e32 v226, s16, v143
	v_lshl_add_u64 v[236:237], v[232:233], 0, s[48:49]
	s_mov_b32 m0, s9
	ds_read_b128 v[214:217], v226
	ds_read_b128 v[218:221], v226 offset:1024
	ds_read_b128 v[222:225], v226 offset:2048
	ds_read_b128 v[226:229], v226 offset:3072
	global_load_lds_dwordx4 v[236:237], off
	v_lshl_add_u64 v[236:237], v[234:235], 0, s[48:49]
	s_add_i32 m0, s9, 0x2000
	s_nop 0
	global_load_lds_dwordx4 v[236:237], off
	s_barrier
	s_waitcnt lgkmcnt(0)
	v_mfma_f32_16x16x32_bf16 v[94:97], v[160:163], v[214:217], v[94:97]
	v_mfma_f32_16x16x32_bf16 v[90:93], v[160:163], v[222:225], v[90:93]
	v_mfma_f32_16x16x32_bf16 v[86:89], v[190:193], v[214:217], v[86:89]
	v_mfma_f32_16x16x32_bf16 v[82:85], v[190:193], v[222:225], v[82:85]
	v_mfma_f32_16x16x32_bf16 v[78:81], v[198:201], v[214:217], v[78:81]
	v_mfma_f32_16x16x32_bf16 v[74:77], v[198:201], v[222:225], v[74:77]
	v_mfma_f32_16x16x32_bf16 v[70:73], v[206:209], v[214:217], v[70:73]
	v_mfma_f32_16x16x32_bf16 v[66:69], v[206:209], v[222:225], v[66:69]
	v_mfma_f32_16x16x32_bf16 v[94:97], v[164:167], v[218:221], v[94:97]
	v_mfma_f32_16x16x32_bf16 v[90:93], v[164:167], v[226:229], v[90:93]
	v_mfma_f32_16x16x32_bf16 v[86:89], v[194:197], v[218:221], v[86:89]
	v_mfma_f32_16x16x32_bf16 v[82:85], v[194:197], v[226:229], v[82:85]
	v_mfma_f32_16x16x32_bf16 v[78:81], v[202:205], v[218:221], v[78:81]
	v_mfma_f32_16x16x32_bf16 v[74:77], v[202:205], v[226:229], v[74:77]
	v_mfma_f32_16x16x32_bf16 v[70:73], v[210:213], v[218:221], v[70:73]
	v_mfma_f32_16x16x32_bf16 v[66:69], v[210:213], v[226:229], v[66:69]
	s_barrier
	s_mov_b32 m0, s24
	v_lshl_add_u64 v[138:139], v[138:139], 0, s[42:43]
	ds_read_b128 v[160:163], v142 offset:49152
	ds_read_b128 v[164:167], v142 offset:50176
	ds_read_b128 v[190:193], v142 offset:51200
	ds_read_b128 v[194:197], v142 offset:52224
	ds_read_b128 v[198:201], v142 offset:53248
	ds_read_b128 v[202:205], v142 offset:54272
	ds_read_b128 v[206:209], v142 offset:55296
	ds_read_b128 v[210:213], v142 offset:56320
	global_load_lds_dwordx4 v[138:139], off
	s_mov_b32 m0, s30
	v_lshl_add_u64 v[138:139], v[230:231], 0, s[42:43]
	global_load_lds_dwordx4 v[138:139], off
	s_barrier
;     __device__ __forceinline__ unsigned* BAR() const { return (unsigned*)(ws + OFF_BAR); }
; #define STAGE(bufoff, gbase, voff) do { _Pragma("unroll") for (int _i = 0; _i < 2; ++_i) \
;         __builtin_amdgcn_global_load_lds((const unsigned*)((const char*)(gbase) + voff[_i]), (LAS unsigned*)(lds + (bufoff) + ldsw + _i * 8192), 16, 0, 0); } while (0)
; #define LDA(dst, b, h) do { _Pragma("unroll") for (int m = 0; m < 4; ++m) _Pragma("unroll") for (int k = 0; k < 2; ++k) dst[m][k] = *(const LAS bf16x8*)(lds + SA(b, h) + aoff + m * 2048 + k * 1024); } while (0)
; #define LDB(dst, b, h) do { _Pragma("unroll") for (int n = 0; n < 2; ++n) _Pragma("unroll") for (int k = 0; k < 2; ++k) dst[n][k] = *(const LAS bf16x8*)(lds + SB(b, h) + boff + n * 2048 + k * 1024); } while (0)
; #define MMA(ai, bj, At, Bx) do { __builtin_amdgcn_s_setprio(1); _Pragma("unroll") for (int m = 0; m < 4; ++m) _Pragma("unroll") for (int n = 0; n < 2; ++n) _Pragma("unroll") for (int k = 0; k < 2; ++k) \
;       acc[ai][bj][m][n] = __builtin_amdgcn_mfma_f32_16x16x32_bf16(At[m][k], Bx[n][k], acc[ai][bj][m][n], 0, 0, 0); \
;     __builtin_amdgcn_s_setprio(0); } while (0)
; #define WAIT_V(n) asm volatile("s_waitcnt vmcnt(" #n ")" ::: "memory")
; #define WAIT_L(n) asm volatile("s_waitcnt lgkmcnt(" #n ")" ::: "memory")
; #define BAR __builtin_amdgcn_s_barrier()
;     ...
;         STAGE(SB(1, 1), b3 + hstepB, voffB);
;         WAIT_V(6); BAR; MMA(1, 1, At, B1); BAR;
;     }
;     { LDB(B0, 0, 0); LDA(At, 0, 0); STAGE(SA(1, 1), pA(nt - 1) + hstepA, voffA);
;       BAR; WAIT_L(0); MMA(0, 0, At, B0); BAR;
;       LDB(B1, 0, 1); BAR; WAIT_L(0); MMA(0, 1, At, B1); BAR;
	s_waitcnt lgkmcnt(0)
	v_mfma_f32_16x16x32_bf16 v[62:65], v[160:163], v[144:147], v[62:65]
	v_mfma_f32_16x16x32_bf16 v[58:61], v[160:163], v[152:155], v[58:61]
	v_mfma_f32_16x16x32_bf16 v[54:57], v[190:193], v[144:147], v[54:57]
	v_mfma_f32_16x16x32_bf16 v[50:53], v[190:193], v[152:155], v[50:53]
	v_mfma_f32_16x16x32_bf16 v[46:49], v[198:201], v[144:147], v[46:49]
	v_mfma_f32_16x16x32_bf16 v[42:45], v[198:201], v[152:155], v[42:45]
	v_mfma_f32_16x16x32_bf16 v[38:41], v[206:209], v[144:147], v[38:41]
	v_mfma_f32_16x16x32_bf16 v[34:37], v[206:209], v[152:155], v[34:37]
	v_mfma_f32_16x16x32_bf16 v[62:65], v[164:167], v[148:151], v[62:65]
	v_mfma_f32_16x16x32_bf16 v[58:61], v[164:167], v[156:159], v[58:61]
	v_mfma_f32_16x16x32_bf16 v[54:57], v[194:197], v[148:151], v[54:57]
	v_mfma_f32_16x16x32_bf16 v[50:53], v[194:197], v[156:159], v[50:53]
	v_mfma_f32_16x16x32_bf16 v[46:49], v[202:205], v[148:151], v[46:49]
	v_mfma_f32_16x16x32_bf16 v[42:45], v[202:205], v[156:159], v[42:45]
	v_mfma_f32_16x16x32_bf16 v[38:41], v[210:213], v[148:151], v[38:41]
	v_mfma_f32_16x16x32_bf16 v[34:37], v[210:213], v[156:159], v[34:37]
	s_barrier
	s_add_i32 s9, s16, s11
	s_mov_b32 m0, s9
	v_lshl_add_u64 v[138:139], v[232:233], 0, s[50:51]
	global_load_lds_dwordx4 v[138:139], off
	v_lshl_add_u64 v[138:139], v[234:235], 0, s[50:51]
	s_add_i32 m0, s9, 0x2000
	s_nop 0
	global_load_lds_dwordx4 v[138:139], off
	s_waitcnt vmcnt(6)
	s_barrier
	v_mfma_f32_16x16x32_bf16 v[30:33], v[160:163], v[214:217], v[30:33]
	v_mfma_f32_16x16x32_bf16 v[26:29], v[160:163], v[222:225], v[26:29]
	v_mfma_f32_16x16x32_bf16 v[22:25], v[190:193], v[214:217], v[22:25]
	v_mfma_f32_16x16x32_bf16 v[18:21], v[190:193], v[222:225], v[18:21]
	v_mfma_f32_16x16x32_bf16 v[14:17], v[198:201], v[214:217], v[14:17]
	v_mfma_f32_16x16x32_bf16 v[10:13], v[198:201], v[222:225], v[10:13]
	v_mfma_f32_16x16x32_bf16 v[6:9], v[206:209], v[214:217], v[6:9]
	v_mfma_f32_16x16x32_bf16 v[2:5], v[206:209], v[222:225], v[2:5]
	v_mfma_f32_16x16x32_bf16 v[30:33], v[164:167], v[218:221], v[30:33]
	v_mfma_f32_16x16x32_bf16 v[26:29], v[164:167], v[226:229], v[26:29]
	v_mfma_f32_16x16x32_bf16 v[22:25], v[194:197], v[218:221], v[22:25]
	v_mfma_f32_16x16x32_bf16 v[18:21], v[194:197], v[226:229], v[18:21]
	v_mfma_f32_16x16x32_bf16 v[14:17], v[202:205], v[218:221], v[14:17]
	v_mfma_f32_16x16x32_bf16 v[10:13], v[202:205], v[226:229], v[10:13]
	v_mfma_f32_16x16x32_bf16 v[6:9], v[210:213], v[218:221], v[6:9]
	v_mfma_f32_16x16x32_bf16 v[2:5], v[210:213], v[226:229], v[2:5]
	s_barrier
	s_add_i32 s6, s6, 2
	s_add_u32 s4, s4, 0x100
	s_addc_u32 s5, s5, 0
	s_cmp_gt_u32 s6, 11
	s_cbranch_scc0 .LBB0_227
	v_add_u32_e32 v138, 0, v143
	s_add_u32 s0, s0, 0x40780
	v_add_u32_e32 v136, 0x10000, v138
	s_addc_u32 s1, s1, 0
	s_mov_b32 m0, s8
	ds_read_b128 v[132:135], v136
	ds_read_b128 v[144:147], v136 offset:1024
	ds_read_b128 v[148:151], v136 offset:2048
	ds_read_b128 v[152:155], v136 offset:3072
	ds_read_b128 v[156:159], v142
	ds_read_b128 v[160:163], v142 offset:1024
	ds_read_b128 v[164:167], v142 offset:2048
	ds_read_b128 v[190:193], v142 offset:3072
	ds_read_b128 v[194:197], v142 offset:4096
	ds_read_b128 v[198:201], v142 offset:5120
	ds_read_b128 v[202:205], v142 offset:6144
	ds_read_b128 v[206:209], v142 offset:7168
	v_lshl_add_u64 v[136:137], s[0:1], 0, v[0:1]
	global_load_lds_dwordx4 v[136:137], off
	s_mov_b32 m0, s7
	v_lshl_add_u64 v[130:131], s[0:1], 0, v[130:131]
	global_load_lds_dwordx4 v[130:131], off
	s_barrier
	s_waitcnt lgkmcnt(0)
	v_mfma_f32_16x16x32_bf16 v[126:129], v[156:159], v[132:135], v[126:129]
	v_mfma_f32_16x16x32_bf16 v[122:125], v[156:159], v[148:151], v[122:125]
	v_mfma_f32_16x16x32_bf16 v[118:121], v[164:167], v[132:135], v[118:121]
	v_mfma_f32_16x16x32_bf16 v[114:117], v[164:167], v[148:151], v[114:117]
	v_mfma_f32_16x16x32_bf16 v[98:101], v[202:205], v[148:151], v[98:101]
	v_mfma_f32_16x16x32_bf16 v[126:129], v[160:163], v[144:147], v[126:129]
	v_mfma_f32_16x16x32_bf16 v[122:125], v[160:163], v[152:155], v[122:125]
	v_mfma_f32_16x16x32_bf16 v[118:121], v[190:193], v[144:147], v[118:121]
	v_mfma_f32_16x16x32_bf16 v[114:117], v[190:193], v[152:155], v[114:117]
	v_mfma_f32_16x16x32_bf16 v[110:113], v[194:197], v[132:135], v[110:113]
	v_mfma_f32_16x16x32_bf16 v[106:109], v[194:197], v[148:151], v[106:109]
	v_mfma_f32_16x16x32_bf16 v[102:105], v[202:205], v[132:135], v[102:105]
	v_mfma_f32_16x16x32_bf16 v[98:101], v[206:209], v[152:155], v[98:101]
	v_mfma_f32_16x16x32_bf16 v[210:213], v[198:201], v[144:147], v[110:113]
	v_mfma_f32_16x16x32_bf16 v[214:217], v[198:201], v[152:155], v[106:109]
	v_mfma_f32_16x16x32_bf16 v[218:221], v[206:209], v[144:147], v[102:105]
	v_add_u32_e32 v0, 0x14000, v138
	s_barrier
	s_nop 0
	ds_read_b128 v[102:105], v0
	ds_read_b128 v[106:109], v0 offset:1024
	ds_read_b128 v[110:113], v0 offset:2048
	ds_read_b128 v[222:225], v0 offset:3072
	s_barrier
	s_waitcnt lgkmcnt(0)
	v_mfma_f32_16x16x32_bf16 v[94:97], v[156:159], v[102:105], v[94:97]
	v_mfma_f32_16x16x32_bf16 v[90:93], v[156:159], v[110:113], v[90:93]
	v_mfma_f32_16x16x32_bf16 v[86:89], v[164:167], v[102:105], v[86:89]
	v_mfma_f32_16x16x32_bf16 v[82:85], v[164:167], v[110:113], v[82:85]
	v_mfma_f32_16x16x32_bf16 v[66:69], v[202:205], v[110:113], v[66:69]
	v_mfma_f32_16x16x32_bf16 v[94:97], v[160:163], v[106:109], v[94:97]
	v_mfma_f32_16x16x32_bf16 v[90:93], v[160:163], v[222:225], v[90:93]
	v_mfma_f32_16x16x32_bf16 v[86:89], v[190:193], v[106:109], v[86:89]
	v_mfma_f32_16x16x32_bf16 v[82:85], v[190:193], v[222:225], v[82:85]
	v_mfma_f32_16x16x32_bf16 v[78:81], v[194:197], v[102:105], v[78:81]
	v_mfma_f32_16x16x32_bf16 v[74:77], v[194:197], v[110:113], v[74:77]
	v_mfma_f32_16x16x32_bf16 v[70:73], v[202:205], v[102:105], v[70:73]
	v_mfma_f32_16x16x32_bf16 v[66:69], v[206:209], v[222:225], v[66:69]
	v_mfma_f32_16x16x32_bf16 v[156:159], v[198:201], v[106:109], v[78:81]
	v_mfma_f32_16x16x32_bf16 v[160:163], v[198:201], v[222:225], v[74:77]
	v_mfma_f32_16x16x32_bf16 v[164:167], v[206:209], v[106:109], v[70:73]
	s_barrier
;     __device__ __forceinline__ unsigned* BAR() const { return (unsigned*)(ws + OFF_BAR); }
; #define LDA(dst, b, h) do { _Pragma("unroll") for (int m = 0; m < 4; ++m) _Pragma("unroll") for (int k = 0; k < 2; ++k) dst[m][k] = *(const LAS bf16x8*)(lds + SA(b, h) + aoff + m * 2048 + k * 1024); } while (0)
; #define LDB(dst, b, h) do { _Pragma("unroll") for (int n = 0; n < 2; ++n) _Pragma("unroll") for (int k = 0; k < 2; ++k) dst[n][k] = *(const LAS bf16x8*)(lds + SB(b, h) + boff + n * 2048 + k * 1024); } while (0)
; #define MMA(ai, bj, At, Bx) do { __builtin_amdgcn_s_setprio(1); _Pragma("unroll") for (int m = 0; m < 4; ++m) _Pragma("unroll") for (int n = 0; n < 2; ++n) _Pragma("unroll") for (int k = 0; k < 2; ++k) \
;       acc[ai][bj][m][n] = __builtin_amdgcn_mfma_f32_16x16x32_bf16(At[m][k], Bx[n][k], acc[ai][bj][m][n], 0, 0, 0); \
;     __builtin_amdgcn_s_setprio(0); } while (0)
; #define WAIT_V(n) asm volatile("s_waitcnt vmcnt(" #n ")" ::: "memory")
; #define WAIT_L(n) asm volatile("s_waitcnt lgkmcnt(" #n ")" ::: "memory")
; #define BAR __builtin_amdgcn_s_barrier()
;     ...
;       LDA(At, 0, 1); WAIT_V(4); BAR; WAIT_L(0); MMA(1, 0, At, B0); MMA(1, 1, At, B1); BAR; }
;     { LDB(B0, 1, 0); LDA(At, 1, 0); WAIT_V(2); BAR; WAIT_L(0); MMA(0, 0, At, B0); BAR;
	s_nop 1
	ds_read_b128 v[70:73], v142 offset:16384
	ds_read_b128 v[74:77], v142 offset:17408
	ds_read_b128 v[78:81], v142 offset:18432
	ds_read_b128 v[190:193], v142 offset:19456
	ds_read_b128 v[194:197], v142 offset:20480
	ds_read_b128 v[198:201], v142 offset:21504
	ds_read_b128 v[202:205], v142 offset:22528
	ds_read_b128 v[206:209], v142 offset:23552
	s_waitcnt vmcnt(4)
	s_barrier
	s_waitcnt lgkmcnt(0)
	v_mfma_f32_16x16x32_bf16 v[62:65], v[70:73], v[132:135], v[62:65]
	v_mfma_f32_16x16x32_bf16 v[58:61], v[70:73], v[148:151], v[58:61]
	v_mfma_f32_16x16x32_bf16 v[54:57], v[78:81], v[132:135], v[54:57]
	v_mfma_f32_16x16x32_bf16 v[50:53], v[78:81], v[148:151], v[50:53]
	v_mfma_f32_16x16x32_bf16 v[34:37], v[202:205], v[148:151], v[34:37]
	v_mfma_f32_16x16x32_bf16 v[62:65], v[74:77], v[144:147], v[62:65]
	v_mfma_f32_16x16x32_bf16 v[58:61], v[74:77], v[152:155], v[58:61]
	v_mfma_f32_16x16x32_bf16 v[54:57], v[190:193], v[144:147], v[54:57]
	v_mfma_f32_16x16x32_bf16 v[50:53], v[190:193], v[152:155], v[50:53]
	v_mfma_f32_16x16x32_bf16 v[46:49], v[194:197], v[132:135], v[46:49]
	v_mfma_f32_16x16x32_bf16 v[42:45], v[194:197], v[148:151], v[42:45]
	v_mfma_f32_16x16x32_bf16 v[38:41], v[202:205], v[132:135], v[38:41]
	v_mfma_f32_16x16x32_bf16 v[34:37], v[206:209], v[152:155], v[34:37]
	v_mfma_f32_16x16x32_bf16 v[226:229], v[198:201], v[144:147], v[46:49]
	v_mfma_f32_16x16x32_bf16 v[230:233], v[198:201], v[152:155], v[42:45]
	v_mfma_f32_16x16x32_bf16 v[130:133], v[206:209], v[144:147], v[38:41]
	v_mfma_f32_16x16x32_bf16 v[30:33], v[70:73], v[102:105], v[30:33]
	v_mfma_f32_16x16x32_bf16 v[26:29], v[70:73], v[110:113], v[26:29]
	v_mfma_f32_16x16x32_bf16 v[22:25], v[78:81], v[102:105], v[22:25]
	v_mfma_f32_16x16x32_bf16 v[18:21], v[78:81], v[110:113], v[18:21]
	v_mfma_f32_16x16x32_bf16 v[2:5], v[202:205], v[110:113], v[2:5]
	v_mfma_f32_16x16x32_bf16 v[30:33], v[74:77], v[106:109], v[30:33]
	v_mfma_f32_16x16x32_bf16 v[26:29], v[74:77], v[222:225], v[26:29]
	v_mfma_f32_16x16x32_bf16 v[22:25], v[190:193], v[106:109], v[22:25]
	v_mfma_f32_16x16x32_bf16 v[18:21], v[190:193], v[222:225], v[18:21]
	v_mfma_f32_16x16x32_bf16 v[14:17], v[194:197], v[102:105], v[14:17]
	v_mfma_f32_16x16x32_bf16 v[10:13], v[194:197], v[110:113], v[10:13]
	v_mfma_f32_16x16x32_bf16 v[6:9], v[202:205], v[102:105], v[6:9]
	v_mfma_f32_16x16x32_bf16 v[2:5], v[206:209], v[222:225], v[2:5]
	v_mfma_f32_16x16x32_bf16 v[134:137], v[198:201], v[106:109], v[14:17]
	v_mfma_f32_16x16x32_bf16 v[144:147], v[198:201], v[222:225], v[10:13]
	v_mfma_f32_16x16x32_bf16 v[148:151], v[206:209], v[106:109], v[6:9]
	v_add_u32_e32 v0, 0x18000, v138
	s_barrier
	s_nop 0
	ds_read_b128 v[6:9], v0
	ds_read_b128 v[10:13], v0 offset:1024
	ds_read_b128 v[14:17], v0 offset:2048
	ds_read_b128 v[152:155], v0 offset:3072
	ds_read_b128 v[38:41], v142 offset:32768
	ds_read_b128 v[42:45], v142 offset:33792
	ds_read_b128 v[46:49], v142 offset:34816
	ds_read_b128 v[70:73], v142 offset:35840
	ds_read_b128 v[190:193], v142 offset:36864
	ds_read_b128 v[194:197], v142 offset:37888
	ds_read_b128 v[198:201], v142 offset:38912
	ds_read_b128 v[202:205], v142 offset:39936
	s_waitcnt vmcnt(2)
	s_barrier
	s_waitcnt lgkmcnt(0)
	v_mfma_f32_16x16x32_bf16 v[74:77], v[38:41], v[6:9], v[126:129]
	v_mfma_f32_16x16x32_bf16 v[126:129], v[42:45], v[10:13], v[74:77]
	v_mfma_f32_16x16x32_bf16 v[74:77], v[38:41], v[14:17], v[122:125]
	v_mfma_f32_16x16x32_bf16 v[110:113], v[42:45], v[152:155], v[74:77]
	v_mfma_f32_16x16x32_bf16 v[74:77], v[46:49], v[6:9], v[118:121]
	v_mfma_f32_16x16x32_bf16 v[122:125], v[70:73], v[10:13], v[74:77]
	v_mfma_f32_16x16x32_bf16 v[74:77], v[46:49], v[14:17], v[114:117]
	v_mfma_f32_16x16x32_bf16 v[106:109], v[70:73], v[152:155], v[74:77]
	v_mfma_f32_16x16x32_bf16 v[74:77], v[190:193], v[6:9], v[210:213]
	v_mfma_f32_16x16x32_bf16 v[118:121], v[194:197], v[10:13], v[74:77]
	v_mfma_f32_16x16x32_bf16 v[74:77], v[190:193], v[14:17], v[214:217]
	v_mfma_f32_16x16x32_bf16 v[102:105], v[194:197], v[152:155], v[74:77]
	v_mfma_f32_16x16x32_bf16 v[74:77], v[198:201], v[6:9], v[218:221]
	v_mfma_f32_16x16x32_bf16 v[114:117], v[202:205], v[10:13], v[74:77]
	v_mfma_f32_16x16x32_bf16 v[74:77], v[198:201], v[14:17], v[98:101]
	v_mfma_f32_16x16x32_bf16 v[98:101], v[202:205], v[152:155], v[74:77]
	v_add_u32_e32 v0, 0x1c000, v138
	s_barrier
;     __device__ __forceinline__ unsigned* BAR() const { return (unsigned*)(ws + OFF_BAR); }
; #define LDA(dst, b, h) do { _Pragma("unroll") for (int m = 0; m < 4; ++m) _Pragma("unroll") for (int k = 0; k < 2; ++k) dst[m][k] = *(const LAS bf16x8*)(lds + SA(b, h) + aoff + m * 2048 + k * 1024); } while (0)
; #define LDB(dst, b, h) do { _Pragma("unroll") for (int n = 0; n < 2; ++n) _Pragma("unroll") for (int k = 0; k < 2; ++k) dst[n][k] = *(const LAS bf16x8*)(lds + SB(b, h) + boff + n * 2048 + k * 1024); } while (0)
; #define MMA(ai, bj, At, Bx) do { __builtin_amdgcn_s_setprio(1); _Pragma("unroll") for (int m = 0; m < 4; ++m) _Pragma("unroll") for (int n = 0; n < 2; ++n) _Pragma("unroll") for (int k = 0; k < 2; ++k) \
;       acc[ai][bj][m][n] = __builtin_amdgcn_mfma_f32_16x16x32_bf16(At[m][k], Bx[n][k], acc[ai][bj][m][n], 0, 0, 0); \
;     __builtin_amdgcn_s_setprio(0); } while (0)
; #define WAIT_V(n) asm volatile("s_waitcnt vmcnt(" #n ")" ::: "memory")
; #define WAIT_L(n) asm volatile("s_waitcnt lgkmcnt(" #n ")" ::: "memory")
; #define BAR __builtin_amdgcn_s_barrier()
;     ...
;       LDB(B1, 1, 1); WAIT_V(0); BAR; WAIT_L(0); MMA(0, 1, At, B1); BAR;
;       LDA(At, 1, 1); BAR; WAIT_L(0); MMA(1, 0, At, B0); MMA(1, 1, At, B1); BAR; }
;     if (wr == 0) BAR;
	ds_read_b128 v[206:209], v0
	ds_read_b128 v[210:213], v0 offset:1024
	ds_read_b128 v[214:217], v0 offset:2048
	ds_read_b128 v[218:221], v0 offset:3072
	s_waitcnt vmcnt(0)
	s_barrier
	s_waitcnt lgkmcnt(0)
	v_mfma_f32_16x16x32_bf16 v[74:77], v[38:41], v[206:209], v[94:97]
	v_mfma_f32_16x16x32_bf16 v[38:41], v[38:41], v[214:217], v[90:93]
	v_mfma_f32_16x16x32_bf16 v[78:81], v[42:45], v[218:221], v[38:41]
	v_mfma_f32_16x16x32_bf16 v[38:41], v[46:49], v[206:209], v[86:89]
	v_mfma_f32_16x16x32_bf16 v[90:93], v[70:73], v[210:213], v[38:41]
	v_mfma_f32_16x16x32_bf16 v[38:41], v[46:49], v[214:217], v[82:85]
	v_mfma_f32_16x16x32_bf16 v[94:97], v[42:45], v[210:213], v[74:77]
	v_mfma_f32_16x16x32_bf16 v[74:77], v[70:73], v[218:221], v[38:41]
	v_mfma_f32_16x16x32_bf16 v[38:41], v[190:193], v[206:209], v[156:159]
	v_mfma_f32_16x16x32_bf16 v[86:89], v[194:197], v[210:213], v[38:41]
	v_mfma_f32_16x16x32_bf16 v[38:41], v[190:193], v[214:217], v[160:163]
	v_mfma_f32_16x16x32_bf16 v[70:73], v[194:197], v[218:221], v[38:41]
	v_mfma_f32_16x16x32_bf16 v[38:41], v[198:201], v[206:209], v[164:167]
	v_mfma_f32_16x16x32_bf16 v[82:85], v[202:205], v[210:213], v[38:41]
	v_mfma_f32_16x16x32_bf16 v[38:41], v[198:201], v[214:217], v[66:69]
	v_mfma_f32_16x16x32_bf16 v[66:69], v[202:205], v[218:221], v[38:41]
	s_barrier
	ds_read_b128 v[156:159], v142 offset:49152
	ds_read_b128 v[160:163], v142 offset:50176
	ds_read_b128 v[164:167], v142 offset:51200
	ds_read_b128 v[190:193], v142 offset:52224
	ds_read_b128 v[194:197], v142 offset:53248
	ds_read_b128 v[198:201], v142 offset:54272
	ds_read_b128 v[202:205], v142 offset:55296
	ds_read_b128 v[140:143], v142 offset:56320
	s_barrier
	s_waitcnt lgkmcnt(0)
	v_mfma_f32_16x16x32_bf16 v[38:41], v[156:159], v[6:9], v[62:65]
	v_mfma_f32_16x16x32_bf16 v[62:65], v[160:163], v[10:13], v[38:41]
	v_mfma_f32_16x16x32_bf16 v[38:41], v[156:159], v[14:17], v[58:61]
	v_mfma_f32_16x16x32_bf16 v[46:49], v[160:163], v[152:155], v[38:41]
	v_mfma_f32_16x16x32_bf16 v[38:41], v[164:167], v[6:9], v[54:57]
	v_mfma_f32_16x16x32_bf16 v[58:61], v[190:193], v[10:13], v[38:41]
	v_mfma_f32_16x16x32_bf16 v[38:41], v[164:167], v[14:17], v[50:53]
	v_mfma_f32_16x16x32_bf16 v[42:45], v[190:193], v[152:155], v[38:41]
	v_mfma_f32_16x16x32_bf16 v[38:41], v[194:197], v[6:9], v[226:229]
	v_mfma_f32_16x16x32_bf16 v[6:9], v[202:205], v[6:9], v[130:133]
	v_mfma_f32_16x16x32_bf16 v[54:57], v[198:201], v[10:13], v[38:41]
	v_mfma_f32_16x16x32_bf16 v[38:41], v[194:197], v[14:17], v[230:233]
	v_mfma_f32_16x16x32_bf16 v[50:53], v[140:143], v[10:13], v[6:9]
	v_mfma_f32_16x16x32_bf16 v[6:9], v[202:205], v[14:17], v[34:37]
	v_mfma_f32_16x16x32_bf16 v[38:41], v[198:201], v[152:155], v[38:41]
	v_mfma_f32_16x16x32_bf16 v[34:37], v[140:143], v[152:155], v[6:9]
	v_mfma_f32_16x16x32_bf16 v[6:9], v[156:159], v[206:209], v[30:33]
	v_mfma_f32_16x16x32_bf16 v[30:33], v[160:163], v[210:213], v[6:9]
	v_mfma_f32_16x16x32_bf16 v[6:9], v[156:159], v[214:217], v[26:29]
	v_mfma_f32_16x16x32_bf16 v[14:17], v[160:163], v[218:221], v[6:9]
	v_mfma_f32_16x16x32_bf16 v[6:9], v[164:167], v[206:209], v[22:25]
	v_mfma_f32_16x16x32_bf16 v[26:29], v[190:193], v[210:213], v[6:9]
	v_mfma_f32_16x16x32_bf16 v[6:9], v[164:167], v[214:217], v[18:21]
	v_mfma_f32_16x16x32_bf16 v[10:13], v[190:193], v[218:221], v[6:9]
	v_mfma_f32_16x16x32_bf16 v[6:9], v[194:197], v[206:209], v[134:137]
	v_mfma_f32_16x16x32_bf16 v[22:25], v[198:201], v[210:213], v[6:9]
	v_mfma_f32_16x16x32_bf16 v[6:9], v[194:197], v[214:217], v[144:147]
	v_mfma_f32_16x16x32_bf16 v[18:21], v[202:205], v[206:209], v[148:151]
	v_mfma_f32_16x16x32_bf16 v[2:5], v[202:205], v[214:217], v[2:5]
	v_mfma_f32_16x16x32_bf16 v[6:9], v[198:201], v[218:221], v[6:9]
	v_mfma_f32_16x16x32_bf16 v[18:21], v[140:143], v[210:213], v[18:21]
	v_mfma_f32_16x16x32_bf16 v[2:5], v[140:143], v[218:221], v[2:5]
	s_cmpk_lt_u32 s10, 0x100
	s_barrier
	s_cbranch_scc0 .LBB0_230
	s_barrier

;     __device__ __forceinline__ unsigned* BAR() const { return (unsigned*)(ws + OFF_BAR); }
; #define STAGE(bufoff, gbase, voff) do { _Pragma("unroll") for (int _i = 0; _i < 2; ++_i) \
;         __builtin_amdgcn_global_load_lds((const unsigned*)((const char*)(gbase) + voff[_i]), (LAS unsigned*)(lds + (bufoff) + ldsw + _i * 8192), 16, 0, 0); } while (0)
; #define LDA(dst, b, h) do { _Pragma("unroll") for (int m = 0; m < 4; ++m) _Pragma("unroll") for (int k = 0; k < 2; ++k) dst[m][k] = *(const LAS bf16x8*)(lds + SA(b, h) + aoff + m * 2048 + k * 1024); } while (0)
; #define LDB(dst, b, h) do { _Pragma("unroll") for (int n = 0; n < 2; ++n) _Pragma("unroll") for (int k = 0; k < 2; ++k) dst[n][k] = *(const LAS bf16x8*)(lds + SB(b, h) + boff + n * 2048 + k * 1024); } while (0)
; #define MMA(ai, bj, At, Bx) do { __builtin_amdgcn_s_setprio(1); _Pragma("unroll") for (int m = 0; m < 4; ++m) _Pragma("unroll") for (int n = 0; n < 2; ++n) _Pragma("unroll") for (int k = 0; k < 2; ++k) \
;       acc[ai][bj][m][n] = __builtin_amdgcn_mfma_f32_16x16x32_bf16(At[m][k], Bx[n][k], acc[ai][bj][m][n], 0, 0, 0); \
;     __builtin_amdgcn_s_setprio(0); } while (0)
; #define WAIT_L(n) asm volatile("s_waitcnt lgkmcnt(" #n ")" ::: "memory")
; #define BAR __builtin_amdgcn_s_barrier()
; #define SCHED __builtin_amdgcn_sched_barrier(0)
;     ...
;         const char* a1 = pA(t + 1); const char* a2 = pA(t + 2); const char* a3 = pA(t + 3);
;         const char* b2 = pB(t + 2); const char* b3 = pB(t + 3);
;         LDB(B0, 0, 0); SCHED; LDA(At, 0, 0); STAGE(SA(1, 1), a1 + hstepA, voffA);
;         WAIT_L(8); BAR; WAIT_L(0); MMA(0, 0, At, B0); BAR; SCHED;
;         LDB(B1, 0, 1); STAGE(SB(0, 0), b2, voffB);
;         BAR; WAIT_L(0); MMA(0, 1, At, B1); BAR;
;         LDA(At, 0, 1); STAGE(SA(0, 0), a2, voffA);
;         BAR; WAIT_L(0); MMA(1, 0, At, B0); BAR; SCHED;
.LBB0_377:
	s_add_i32 s9, 0, 0x10000
	v_add_u32_e32 v138, s9, v143
	ds_read_b128 v[144:147], v138
	ds_read_b128 v[148:151], v138 offset:1024
	ds_read_b128 v[152:155], v138 offset:2048
	ds_read_b128 v[156:159], v138 offset:3072
	v_lshl_add_u64 v[138:139], s[20:21], 0, v[136:137]
	s_add_i32 s8, s13, 0xc000
	v_lshl_add_u64 v[214:215], v[138:139], 0, s[54:55]
	s_mov_b32 m0, s8
	v_lshl_add_u64 v[230:231], s[20:21], 0, v[140:141]
	s_add_i32 s7, s13, 0xe000
	ds_read_b128 v[160:163], v142
	ds_read_b128 v[164:167], v142 offset:1024
	ds_read_b128 v[190:193], v142 offset:2048
	ds_read_b128 v[194:197], v142 offset:3072
	ds_read_b128 v[198:201], v142 offset:4096
	ds_read_b128 v[202:205], v142 offset:5120
	ds_read_b128 v[206:209], v142 offset:6144
	ds_read_b128 v[210:213], v142 offset:7168
	global_load_lds_dwordx4 v[214:215], off
	s_mov_b32 m0, s7
	v_lshl_add_u64 v[214:215], v[230:231], 0, s[54:55]
	global_load_lds_dwordx4 v[214:215], off
	s_waitcnt lgkmcnt(8)
	s_barrier
	s_waitcnt lgkmcnt(0)
	v_mfma_f32_16x16x32_bf16 v[126:129], v[160:163], v[144:147], v[126:129]
	v_mfma_f32_16x16x32_bf16 v[122:125], v[160:163], v[152:155], v[122:125]
	v_mfma_f32_16x16x32_bf16 v[118:121], v[190:193], v[144:147], v[118:121]
	v_mfma_f32_16x16x32_bf16 v[114:117], v[190:193], v[152:155], v[114:117]
	v_mfma_f32_16x16x32_bf16 v[110:113], v[198:201], v[144:147], v[110:113]
	v_mfma_f32_16x16x32_bf16 v[106:109], v[198:201], v[152:155], v[106:109]
	v_mfma_f32_16x16x32_bf16 v[102:105], v[206:209], v[144:147], v[102:105]
	v_mfma_f32_16x16x32_bf16 v[98:101], v[206:209], v[152:155], v[98:101]
	v_mfma_f32_16x16x32_bf16 v[126:129], v[164:167], v[148:151], v[126:129]
	v_mfma_f32_16x16x32_bf16 v[122:125], v[164:167], v[156:159], v[122:125]
	v_mfma_f32_16x16x32_bf16 v[118:121], v[194:197], v[148:151], v[118:121]
	v_mfma_f32_16x16x32_bf16 v[114:117], v[194:197], v[156:159], v[114:117]
	v_mfma_f32_16x16x32_bf16 v[110:113], v[202:205], v[148:151], v[110:113]
	v_mfma_f32_16x16x32_bf16 v[106:109], v[202:205], v[156:159], v[106:109]
	v_mfma_f32_16x16x32_bf16 v[102:105], v[210:213], v[148:151], v[102:105]
	v_mfma_f32_16x16x32_bf16 v[98:101], v[210:213], v[156:159], v[98:101]
	s_barrier
	s_add_i32 s10, 0, 0x14000
	v_lshl_add_u64 v[232:233], s[20:21], 0, v[132:133]
	s_add_i32 s9, s9, s1
	v_add_u32_e32 v226, s10, v143
	v_lshl_add_u64 v[234:235], v[232:233], 0, s[40:41]
	s_mov_b32 m0, s9
	ds_read_b128 v[214:217], v226
	ds_read_b128 v[218:221], v226 offset:1024
	ds_read_b128 v[222:225], v226 offset:2048
	ds_read_b128 v[226:229], v226 offset:3072
	global_load_lds_dwordx4 v[234:235], off
	v_lshl_add_u64 v[234:235], s[20:21], 0, v[134:135]
	v_lshl_add_u64 v[236:237], v[234:235], 0, s[40:41]
	s_add_i32 m0, s9, 0x2000
	s_nop 0
	global_load_lds_dwordx4 v[236:237], off
	s_barrier
	s_waitcnt lgkmcnt(0)
	v_mfma_f32_16x16x32_bf16 v[94:97], v[160:163], v[214:217], v[94:97]
	v_mfma_f32_16x16x32_bf16 v[90:93], v[160:163], v[222:225], v[90:93]
	v_mfma_f32_16x16x32_bf16 v[86:89], v[190:193], v[214:217], v[86:89]
	v_mfma_f32_16x16x32_bf16 v[82:85], v[190:193], v[222:225], v[82:85]
	v_mfma_f32_16x16x32_bf16 v[78:81], v[198:201], v[214:217], v[78:81]
	v_mfma_f32_16x16x32_bf16 v[74:77], v[198:201], v[222:225], v[74:77]
	v_mfma_f32_16x16x32_bf16 v[70:73], v[206:209], v[214:217], v[70:73]
	v_mfma_f32_16x16x32_bf16 v[66:69], v[206:209], v[222:225], v[66:69]
	v_mfma_f32_16x16x32_bf16 v[94:97], v[164:167], v[218:221], v[94:97]
	v_mfma_f32_16x16x32_bf16 v[90:93], v[164:167], v[226:229], v[90:93]
	v_mfma_f32_16x16x32_bf16 v[86:89], v[194:197], v[218:221], v[86:89]
	v_mfma_f32_16x16x32_bf16 v[82:85], v[194:197], v[226:229], v[82:85]
	v_mfma_f32_16x16x32_bf16 v[78:81], v[202:205], v[218:221], v[78:81]
	v_mfma_f32_16x16x32_bf16 v[74:77], v[202:205], v[226:229], v[74:77]
	v_mfma_f32_16x16x32_bf16 v[70:73], v[210:213], v[218:221], v[70:73]
	v_mfma_f32_16x16x32_bf16 v[66:69], v[210:213], v[226:229], v[66:69]
	s_barrier
	s_mov_b32 m0, s13
	v_lshl_add_u64 v[236:237], v[138:139], 0, s[38:39]
	ds_read_b128 v[160:163], v142 offset:16384
	ds_read_b128 v[164:167], v142 offset:17408
	ds_read_b128 v[190:193], v142 offset:18432
	ds_read_b128 v[194:197], v142 offset:19456
	ds_read_b128 v[198:201], v142 offset:20480
	ds_read_b128 v[202:205], v142 offset:21504
	ds_read_b128 v[206:209], v142 offset:22528
	ds_read_b128 v[210:213], v142 offset:23552
	global_load_lds_dwordx4 v[236:237], off
	s_mov_b32 m0, s14
	v_lshl_add_u64 v[236:237], v[230:231], 0, s[38:39]
	global_load_lds_dwordx4 v[236:237], off
	s_barrier
	s_waitcnt lgkmcnt(0)
	v_mfma_f32_16x16x32_bf16 v[62:65], v[160:163], v[144:147], v[62:65]
	v_mfma_f32_16x16x32_bf16 v[58:61], v[160:163], v[152:155], v[58:61]
	v_mfma_f32_16x16x32_bf16 v[54:57], v[190:193], v[144:147], v[54:57]
	v_mfma_f32_16x16x32_bf16 v[50:53], v[190:193], v[152:155], v[50:53]
	v_mfma_f32_16x16x32_bf16 v[46:49], v[198:201], v[144:147], v[46:49]
	v_mfma_f32_16x16x32_bf16 v[42:45], v[198:201], v[152:155], v[42:45]
	v_mfma_f32_16x16x32_bf16 v[38:41], v[206:209], v[144:147], v[38:41]
	v_mfma_f32_16x16x32_bf16 v[34:37], v[206:209], v[152:155], v[34:37]
	v_mfma_f32_16x16x32_bf16 v[62:65], v[164:167], v[148:151], v[62:65]
	v_mfma_f32_16x16x32_bf16 v[58:61], v[164:167], v[156:159], v[58:61]
	v_mfma_f32_16x16x32_bf16 v[54:57], v[194:197], v[148:151], v[54:57]
	v_mfma_f32_16x16x32_bf16 v[50:53], v[194:197], v[156:159], v[50:53]
	v_mfma_f32_16x16x32_bf16 v[46:49], v[202:205], v[148:151], v[46:49]
	v_mfma_f32_16x16x32_bf16 v[42:45], v[202:205], v[156:159], v[42:45]
	v_mfma_f32_16x16x32_bf16 v[38:41], v[210:213], v[148:151], v[38:41]
	v_mfma_f32_16x16x32_bf16 v[34:37], v[210:213], v[156:159], v[34:37]
	s_barrier
;     __device__ __forceinline__ unsigned* BAR() const { return (unsigned*)(ws + OFF_BAR); }
; #define STAGE(bufoff, gbase, voff) do { _Pragma("unroll") for (int _i = 0; _i < 2; ++_i) \
;         __builtin_amdgcn_global_load_lds((const unsigned*)((const char*)(gbase) + voff[_i]), (LAS unsigned*)(lds + (bufoff) + ldsw + _i * 8192), 16, 0, 0); } while (0)
; #define LDA(dst, b, h) do { _Pragma("unroll") for (int m = 0; m < 4; ++m) _Pragma("unroll") for (int k = 0; k < 2; ++k) dst[m][k] = *(const LAS bf16x8*)(lds + SA(b, h) + aoff + m * 2048 + k * 1024); } while (0)
; #define LDB(dst, b, h) do { _Pragma("unroll") for (int n = 0; n < 2; ++n) _Pragma("unroll") for (int k = 0; k < 2; ++k) dst[n][k] = *(const LAS bf16x8*)(lds + SB(b, h) + boff + n * 2048 + k * 1024); } while (0)
; #define MMA(ai, bj, At, Bx) do { __builtin_amdgcn_s_setprio(1); _Pragma("unroll") for (int m = 0; m < 4; ++m) _Pragma("unroll") for (int n = 0; n < 2; ++n) _Pragma("unroll") for (int k = 0; k < 2; ++k) \
;       acc[ai][bj][m][n] = __builtin_amdgcn_mfma_f32_16x16x32_bf16(At[m][k], Bx[n][k], acc[ai][bj][m][n], 0, 0, 0); \
;     __builtin_amdgcn_s_setprio(0); } while (0)
; #define WAIT_V(n) asm volatile("s_waitcnt vmcnt(" #n ")" ::: "memory")
; #define WAIT_L(n) asm volatile("s_waitcnt lgkmcnt(" #n ")" ::: "memory")
; #define BAR __builtin_amdgcn_s_barrier()
; #define SCHED __builtin_amdgcn_sched_barrier(0)
;     ...
;         STAGE(SB(0, 1), b2 + hstepB, voffB);
;         WAIT_V(6); BAR; MMA(1, 1, At, B1); BAR;
;         LDB(B0, 1, 0); SCHED; LDA(At, 1, 0); STAGE(SA(0, 1), a2 + hstepA, voffA);
;         WAIT_L(8); BAR; WAIT_L(0); MMA(0, 0, At, B0); BAR; SCHED;
;         LDB(B1, 1, 1); STAGE(SB(1, 0), b3, voffB);
;         BAR; WAIT_L(0); MMA(0, 1, At, B1); BAR;
;         LDA(At, 1, 1); STAGE(SA(1, 0), a3, voffA);
;         BAR; WAIT_L(0); MMA(1, 0, At, B0); BAR; SCHED;
	s_add_i32 s9, s10, s1
	s_mov_b32 m0, s9
	v_lshl_add_u64 v[144:145], v[232:233], 0, s[46:47]
	global_load_lds_dwordx4 v[144:145], off
	v_lshl_add_u64 v[144:145], v[234:235], 0, s[46:47]
	s_add_i32 m0, s9, 0x2000
	s_nop 0
	global_load_lds_dwordx4 v[144:145], off
	s_waitcnt vmcnt(6)
	s_barrier
	v_mfma_f32_16x16x32_bf16 v[30:33], v[160:163], v[214:217], v[30:33]
	v_mfma_f32_16x16x32_bf16 v[26:29], v[160:163], v[222:225], v[26:29]
	v_mfma_f32_16x16x32_bf16 v[22:25], v[190:193], v[214:217], v[22:25]
	v_mfma_f32_16x16x32_bf16 v[18:21], v[190:193], v[222:225], v[18:21]
	v_mfma_f32_16x16x32_bf16 v[14:17], v[198:201], v[214:217], v[14:17]
	v_mfma_f32_16x16x32_bf16 v[10:13], v[198:201], v[222:225], v[10:13]
	v_mfma_f32_16x16x32_bf16 v[6:9], v[206:209], v[214:217], v[6:9]
	v_mfma_f32_16x16x32_bf16 v[2:5], v[206:209], v[222:225], v[2:5]
	v_mfma_f32_16x16x32_bf16 v[30:33], v[164:167], v[218:221], v[30:33]
	v_mfma_f32_16x16x32_bf16 v[26:29], v[164:167], v[226:229], v[26:29]
	v_mfma_f32_16x16x32_bf16 v[22:25], v[194:197], v[218:221], v[22:25]
	v_mfma_f32_16x16x32_bf16 v[18:21], v[194:197], v[226:229], v[18:21]
	v_mfma_f32_16x16x32_bf16 v[14:17], v[202:205], v[218:221], v[14:17]
	v_mfma_f32_16x16x32_bf16 v[10:13], v[202:205], v[226:229], v[10:13]
	v_mfma_f32_16x16x32_bf16 v[6:9], v[210:213], v[218:221], v[6:9]
	v_mfma_f32_16x16x32_bf16 v[2:5], v[210:213], v[226:229], v[2:5]
	s_barrier
	s_add_i32 s9, 0, 0x18000
	v_add_u32_e32 v156, s9, v143
	ds_read_b128 v[144:147], v156
	ds_read_b128 v[148:151], v156 offset:1024
	ds_read_b128 v[152:155], v156 offset:2048
	ds_read_b128 v[156:159], v156 offset:3072
	s_mov_b32 m0, s15
	v_lshl_add_u64 v[214:215], v[138:139], 0, s[44:45]
	ds_read_b128 v[160:163], v142 offset:32768
	ds_read_b128 v[164:167], v142 offset:33792
	ds_read_b128 v[190:193], v142 offset:34816
	ds_read_b128 v[194:197], v142 offset:35840
	ds_read_b128 v[198:201], v142 offset:36864
	ds_read_b128 v[202:205], v142 offset:37888
	ds_read_b128 v[206:209], v142 offset:38912
	ds_read_b128 v[210:213], v142 offset:39936
	global_load_lds_dwordx4 v[214:215], off
	s_mov_b32 m0, s30
	v_lshl_add_u64 v[214:215], v[230:231], 0, s[44:45]
	global_load_lds_dwordx4 v[214:215], off
	s_waitcnt lgkmcnt(8)
	s_barrier
	s_waitcnt lgkmcnt(0)
	v_mfma_f32_16x16x32_bf16 v[126:129], v[160:163], v[144:147], v[126:129]
	v_mfma_f32_16x16x32_bf16 v[122:125], v[160:163], v[152:155], v[122:125]
	v_mfma_f32_16x16x32_bf16 v[118:121], v[190:193], v[144:147], v[118:121]
	v_mfma_f32_16x16x32_bf16 v[114:117], v[190:193], v[152:155], v[114:117]
	v_mfma_f32_16x16x32_bf16 v[110:113], v[198:201], v[144:147], v[110:113]
	v_mfma_f32_16x16x32_bf16 v[106:109], v[198:201], v[152:155], v[106:109]
	v_mfma_f32_16x16x32_bf16 v[102:105], v[206:209], v[144:147], v[102:105]
	v_mfma_f32_16x16x32_bf16 v[98:101], v[206:209], v[152:155], v[98:101]
	v_mfma_f32_16x16x32_bf16 v[126:129], v[164:167], v[148:151], v[126:129]
	v_mfma_f32_16x16x32_bf16 v[122:125], v[164:167], v[156:159], v[122:125]
	v_mfma_f32_16x16x32_bf16 v[118:121], v[194:197], v[148:151], v[118:121]
	v_mfma_f32_16x16x32_bf16 v[114:117], v[194:197], v[156:159], v[114:117]
	v_mfma_f32_16x16x32_bf16 v[110:113], v[202:205], v[148:151], v[110:113]
	v_mfma_f32_16x16x32_bf16 v[106:109], v[202:205], v[156:159], v[106:109]
	v_mfma_f32_16x16x32_bf16 v[102:105], v[210:213], v[148:151], v[102:105]
	v_mfma_f32_16x16x32_bf16 v[98:101], v[210:213], v[156:159], v[98:101]
	s_barrier
	s_add_i32 s10, 0, 0x1c000
	s_add_i32 s9, s9, s1
	v_add_u32_e32 v226, s10, v143
	v_lshl_add_u64 v[236:237], v[232:233], 0, s[64:65]
	s_mov_b32 m0, s9
	ds_read_b128 v[214:217], v226
	ds_read_b128 v[218:221], v226 offset:1024
	ds_read_b128 v[222:225], v226 offset:2048
	ds_read_b128 v[226:229], v226 offset:3072
	global_load_lds_dwordx4 v[236:237], off
	v_lshl_add_u64 v[236:237], v[234:235], 0, s[64:65]
	s_add_i32 m0, s9, 0x2000
	s_nop 0
	global_load_lds_dwordx4 v[236:237], off
	s_barrier
	s_waitcnt lgkmcnt(0)
	v_mfma_f32_16x16x32_bf16 v[94:97], v[160:163], v[214:217], v[94:97]
	v_mfma_f32_16x16x32_bf16 v[90:93], v[160:163], v[222:225], v[90:93]
	v_mfma_f32_16x16x32_bf16 v[86:89], v[190:193], v[214:217], v[86:89]
	v_mfma_f32_16x16x32_bf16 v[82:85], v[190:193], v[222:225], v[82:85]
	v_mfma_f32_16x16x32_bf16 v[78:81], v[198:201], v[214:217], v[78:81]
	v_mfma_f32_16x16x32_bf16 v[74:77], v[198:201], v[222:225], v[74:77]
	v_mfma_f32_16x16x32_bf16 v[70:73], v[206:209], v[214:217], v[70:73]
	v_mfma_f32_16x16x32_bf16 v[66:69], v[206:209], v[222:225], v[66:69]
	v_mfma_f32_16x16x32_bf16 v[94:97], v[164:167], v[218:221], v[94:97]
	v_mfma_f32_16x16x32_bf16 v[90:93], v[164:167], v[226:229], v[90:93]
	v_mfma_f32_16x16x32_bf16 v[86:89], v[194:197], v[218:221], v[86:89]
	v_mfma_f32_16x16x32_bf16 v[82:85], v[194:197], v[226:229], v[82:85]
	v_mfma_f32_16x16x32_bf16 v[78:81], v[202:205], v[218:221], v[78:81]
	v_mfma_f32_16x16x32_bf16 v[74:77], v[202:205], v[226:229], v[74:77]
	v_mfma_f32_16x16x32_bf16 v[70:73], v[210:213], v[218:221], v[70:73]
	v_mfma_f32_16x16x32_bf16 v[66:69], v[210:213], v[226:229], v[66:69]
	s_barrier
	s_mov_b32 m0, s31
	v_lshl_add_u64 v[138:139], v[138:139], 0, s[48:49]
	ds_read_b128 v[160:163], v142 offset:49152
	ds_read_b128 v[164:167], v142 offset:50176
	ds_read_b128 v[190:193], v142 offset:51200
	ds_read_b128 v[194:197], v142 offset:52224
	ds_read_b128 v[198:201], v142 offset:53248
	ds_read_b128 v[202:205], v142 offset:54272
	ds_read_b128 v[206:209], v142 offset:55296
	ds_read_b128 v[210:213], v142 offset:56320
	global_load_lds_dwordx4 v[138:139], off
	s_mov_b32 m0, s42
	v_lshl_add_u64 v[138:139], v[230:231], 0, s[48:49]
	global_load_lds_dwordx4 v[138:139], off
	s_barrier
;     __device__ __forceinline__ unsigned* BAR() const { return (unsigned*)(ws + OFF_BAR); }
; #define STAGE(bufoff, gbase, voff) do { _Pragma("unroll") for (int _i = 0; _i < 2; ++_i) \
;         __builtin_amdgcn_global_load_lds((const unsigned*)((const char*)(gbase) + voff[_i]), (LAS unsigned*)(lds + (bufoff) + ldsw + _i * 8192), 16, 0, 0); } while (0)
; #define LDA(dst, b, h) do { _Pragma("unroll") for (int m = 0; m < 4; ++m) _Pragma("unroll") for (int k = 0; k < 2; ++k) dst[m][k] = *(const LAS bf16x8*)(lds + SA(b, h) + aoff + m * 2048 + k * 1024); } while (0)
; #define LDB(dst, b, h) do { _Pragma("unroll") for (int n = 0; n < 2; ++n) _Pragma("unroll") for (int k = 0; k < 2; ++k) dst[n][k] = *(const LAS bf16x8*)(lds + SB(b, h) + boff + n * 2048 + k * 1024); } while (0)
; #define MMA(ai, bj, At, Bx) do { __builtin_amdgcn_s_setprio(1); _Pragma("unroll") for (int m = 0; m < 4; ++m) _Pragma("unroll") for (int n = 0; n < 2; ++n) _Pragma("unroll") for (int k = 0; k < 2; ++k) \
;       acc[ai][bj][m][n] = __builtin_amdgcn_mfma_f32_16x16x32_bf16(At[m][k], Bx[n][k], acc[ai][bj][m][n], 0, 0, 0); \
;     __builtin_amdgcn_s_setprio(0); } while (0)
; #define WAIT_V(n) asm volatile("s_waitcnt vmcnt(" #n ")" ::: "memory")
; #define WAIT_L(n) asm volatile("s_waitcnt lgkmcnt(" #n ")" ::: "memory")
; #define BAR __builtin_amdgcn_s_barrier()
;     ...
;         STAGE(SB(1, 1), b3 + hstepB, voffB);
;         WAIT_V(6); BAR; MMA(1, 1, At, B1); BAR;
;     }
;     { LDB(B0, 0, 0); LDA(At, 0, 0); STAGE(SA(1, 1), pA(nt - 1) + hstepA, voffA);
;       BAR; WAIT_L(0); MMA(0, 0, At, B0); BAR;
;       LDB(B1, 0, 1); BAR; WAIT_L(0); MMA(0, 1, At, B1); BAR;
	s_waitcnt lgkmcnt(0)
	v_mfma_f32_16x16x32_bf16 v[62:65], v[160:163], v[144:147], v[62:65]
	v_mfma_f32_16x16x32_bf16 v[58:61], v[160:163], v[152:155], v[58:61]
	v_mfma_f32_16x16x32_bf16 v[54:57], v[190:193], v[144:147], v[54:57]
	v_mfma_f32_16x16x32_bf16 v[50:53], v[190:193], v[152:155], v[50:53]
	v_mfma_f32_16x16x32_bf16 v[46:49], v[198:201], v[144:147], v[46:49]
	v_mfma_f32_16x16x32_bf16 v[42:45], v[198:201], v[152:155], v[42:45]
	v_mfma_f32_16x16x32_bf16 v[38:41], v[206:209], v[144:147], v[38:41]
	v_mfma_f32_16x16x32_bf16 v[34:37], v[206:209], v[152:155], v[34:37]
	v_mfma_f32_16x16x32_bf16 v[62:65], v[164:167], v[148:151], v[62:65]
	v_mfma_f32_16x16x32_bf16 v[58:61], v[164:167], v[156:159], v[58:61]
	v_mfma_f32_16x16x32_bf16 v[54:57], v[194:197], v[148:151], v[54:57]
	v_mfma_f32_16x16x32_bf16 v[50:53], v[194:197], v[156:159], v[50:53]
	v_mfma_f32_16x16x32_bf16 v[46:49], v[202:205], v[148:151], v[46:49]
	v_mfma_f32_16x16x32_bf16 v[42:45], v[202:205], v[156:159], v[42:45]
	v_mfma_f32_16x16x32_bf16 v[38:41], v[210:213], v[148:151], v[38:41]
	v_mfma_f32_16x16x32_bf16 v[34:37], v[210:213], v[156:159], v[34:37]
	s_barrier
	s_add_i32 s9, s10, s1
	s_mov_b32 m0, s9
	v_lshl_add_u64 v[138:139], v[232:233], 0, s[56:57]
	global_load_lds_dwordx4 v[138:139], off
	v_lshl_add_u64 v[138:139], v[234:235], 0, s[56:57]
	s_add_i32 m0, s9, 0x2000
	s_nop 0
	global_load_lds_dwordx4 v[138:139], off
	s_waitcnt vmcnt(6)
	s_barrier
	v_mfma_f32_16x16x32_bf16 v[30:33], v[160:163], v[214:217], v[30:33]
	v_mfma_f32_16x16x32_bf16 v[26:29], v[160:163], v[222:225], v[26:29]
	v_mfma_f32_16x16x32_bf16 v[22:25], v[190:193], v[214:217], v[22:25]
	v_mfma_f32_16x16x32_bf16 v[18:21], v[190:193], v[222:225], v[18:21]
	v_mfma_f32_16x16x32_bf16 v[14:17], v[198:201], v[214:217], v[14:17]
	v_mfma_f32_16x16x32_bf16 v[10:13], v[198:201], v[222:225], v[10:13]
	v_mfma_f32_16x16x32_bf16 v[6:9], v[206:209], v[214:217], v[6:9]
	v_mfma_f32_16x16x32_bf16 v[2:5], v[206:209], v[222:225], v[2:5]
	v_mfma_f32_16x16x32_bf16 v[30:33], v[164:167], v[218:221], v[30:33]
	v_mfma_f32_16x16x32_bf16 v[26:29], v[164:167], v[226:229], v[26:29]
	v_mfma_f32_16x16x32_bf16 v[22:25], v[194:197], v[218:221], v[22:25]
	v_mfma_f32_16x16x32_bf16 v[18:21], v[194:197], v[226:229], v[18:21]
	v_mfma_f32_16x16x32_bf16 v[14:17], v[202:205], v[218:221], v[14:17]
	v_mfma_f32_16x16x32_bf16 v[10:13], v[202:205], v[226:229], v[10:13]
	v_mfma_f32_16x16x32_bf16 v[6:9], v[210:213], v[218:221], v[6:9]
	v_mfma_f32_16x16x32_bf16 v[2:5], v[210:213], v[226:229], v[2:5]
	s_barrier
	s_add_i32 s6, s6, 2
	v_lshl_add_u64 v[132:133], v[132:133], 0, s[40:41]
	v_lshl_add_u64 v[134:135], v[134:135], 0, s[40:41]
	v_lshl_add_u64 v[136:137], v[136:137], 0, s[40:41]
	s_cmp_gt_u32 s6, 11
	v_lshl_add_u64 v[140:141], v[140:141], 0, s[40:41]
	s_cbranch_scc0 .LBB0_377
	v_add_u32_e32 v138, 0, v143
	s_add_u32 s4, s4, 0x40780
	v_add_u32_e32 v136, 0x10000, v138
	s_addc_u32 s5, s5, 0
	s_mov_b32 m0, s8
	ds_read_b128 v[132:135], v136
	ds_read_b128 v[144:147], v136 offset:1024
	ds_read_b128 v[148:151], v136 offset:2048
	ds_read_b128 v[152:155], v136 offset:3072
	ds_read_b128 v[156:159], v142
	ds_read_b128 v[160:163], v142 offset:1024
	ds_read_b128 v[164:167], v142 offset:2048
	ds_read_b128 v[190:193], v142 offset:3072
	ds_read_b128 v[194:197], v142 offset:4096
	ds_read_b128 v[198:201], v142 offset:5120
	ds_read_b128 v[202:205], v142 offset:6144
	ds_read_b128 v[206:209], v142 offset:7168
	v_lshl_add_u64 v[136:137], s[4:5], 0, v[0:1]
	global_load_lds_dwordx4 v[136:137], off
	s_mov_b32 m0, s7
	v_lshl_add_u64 v[130:131], s[4:5], 0, v[130:131]
	global_load_lds_dwordx4 v[130:131], off
	s_barrier
	s_waitcnt lgkmcnt(0)
	v_mfma_f32_16x16x32_bf16 v[126:129], v[156:159], v[132:135], v[126:129]
	v_mfma_f32_16x16x32_bf16 v[122:125], v[156:159], v[148:151], v[122:125]
	v_mfma_f32_16x16x32_bf16 v[118:121], v[164:167], v[132:135], v[118:121]
	v_mfma_f32_16x16x32_bf16 v[110:113], v[194:197], v[132:135], v[110:113]
	v_mfma_f32_16x16x32_bf16 v[106:109], v[194:197], v[148:151], v[106:109]
	v_mfma_f32_16x16x32_bf16 v[102:105], v[202:205], v[132:135], v[102:105]
	v_mfma_f32_16x16x32_bf16 v[98:101], v[202:205], v[148:151], v[98:101]
	v_mfma_f32_16x16x32_bf16 v[126:129], v[160:163], v[144:147], v[126:129]
	v_mfma_f32_16x16x32_bf16 v[122:125], v[160:163], v[152:155], v[122:125]
	v_mfma_f32_16x16x32_bf16 v[118:121], v[190:193], v[144:147], v[118:121]
	v_mfma_f32_16x16x32_bf16 v[114:117], v[164:167], v[148:151], v[114:117]
	v_mfma_f32_16x16x32_bf16 v[110:113], v[198:201], v[144:147], v[110:113]
	v_mfma_f32_16x16x32_bf16 v[106:109], v[198:201], v[152:155], v[106:109]
	v_mfma_f32_16x16x32_bf16 v[102:105], v[206:209], v[144:147], v[102:105]
	v_mfma_f32_16x16x32_bf16 v[98:101], v[206:209], v[152:155], v[98:101]
	v_mfma_f32_16x16x32_bf16 v[210:213], v[190:193], v[152:155], v[114:117]
	v_add_u32_e32 v0, 0x14000, v138
	s_barrier
	ds_read_b128 v[114:117], v0
	ds_read_b128 v[214:217], v0 offset:1024
	ds_read_b128 v[218:221], v0 offset:2048
	ds_read_b128 v[222:225], v0 offset:3072
	s_barrier
	s_waitcnt lgkmcnt(0)
	v_mfma_f32_16x16x32_bf16 v[78:81], v[194:197], v[114:117], v[78:81]
	v_mfma_f32_16x16x32_bf16 v[74:77], v[194:197], v[218:221], v[74:77]
	v_mfma_f32_16x16x32_bf16 v[70:73], v[202:205], v[114:117], v[70:73]
	v_mfma_f32_16x16x32_bf16 v[66:69], v[202:205], v[218:221], v[66:69]
	v_mfma_f32_16x16x32_bf16 v[94:97], v[156:159], v[114:117], v[94:97]
	v_mfma_f32_16x16x32_bf16 v[90:93], v[156:159], v[218:221], v[90:93]
	v_mfma_f32_16x16x32_bf16 v[86:89], v[164:167], v[114:117], v[86:89]
	v_mfma_f32_16x16x32_bf16 v[82:85], v[164:167], v[218:221], v[82:85]
	v_mfma_f32_16x16x32_bf16 v[78:81], v[198:201], v[214:217], v[78:81]
	v_mfma_f32_16x16x32_bf16 v[74:77], v[198:201], v[222:225], v[74:77]
	v_mfma_f32_16x16x32_bf16 v[70:73], v[206:209], v[214:217], v[70:73]
	v_mfma_f32_16x16x32_bf16 v[66:69], v[206:209], v[222:225], v[66:69]
	v_mfma_f32_16x16x32_bf16 v[226:229], v[160:163], v[214:217], v[94:97]
	v_mfma_f32_16x16x32_bf16 v[156:159], v[160:163], v[222:225], v[90:93]
	v_mfma_f32_16x16x32_bf16 v[160:163], v[190:193], v[214:217], v[86:89]
	v_mfma_f32_16x16x32_bf16 v[164:167], v[190:193], v[222:225], v[82:85]
	s_barrier
;     __device__ __forceinline__ unsigned* BAR() const { return (unsigned*)(ws + OFF_BAR); }
; #define LDA(dst, b, h) do { _Pragma("unroll") for (int m = 0; m < 4; ++m) _Pragma("unroll") for (int k = 0; k < 2; ++k) dst[m][k] = *(const LAS bf16x8*)(lds + SA(b, h) + aoff + m * 2048 + k * 1024); } while (0)
; #define LDB(dst, b, h) do { _Pragma("unroll") for (int n = 0; n < 2; ++n) _Pragma("unroll") for (int k = 0; k < 2; ++k) dst[n][k] = *(const LAS bf16x8*)(lds + SB(b, h) + boff + n * 2048 + k * 1024); } while (0)
; #define MMA(ai, bj, At, Bx) do { __builtin_amdgcn_s_setprio(1); _Pragma("unroll") for (int m = 0; m < 4; ++m) _Pragma("unroll") for (int n = 0; n < 2; ++n) _Pragma("unroll") for (int k = 0; k < 2; ++k) \
;       acc[ai][bj][m][n] = __builtin_amdgcn_mfma_f32_16x16x32_bf16(At[m][k], Bx[n][k], acc[ai][bj][m][n], 0, 0, 0); \
;     __builtin_amdgcn_s_setprio(0); } while (0)
; #define WAIT_V(n) asm volatile("s_waitcnt vmcnt(" #n ")" ::: "memory")
; #define WAIT_L(n) asm volatile("s_waitcnt lgkmcnt(" #n ")" ::: "memory")
; #define BAR __builtin_amdgcn_s_barrier()
;     ...
;       LDA(At, 0, 1); WAIT_V(4); BAR; WAIT_L(0); MMA(1, 0, At, B0); MMA(1, 1, At, B1); BAR; }
;     { LDB(B0, 1, 0); LDA(At, 1, 0); WAIT_V(2); BAR; WAIT_L(0); MMA(0, 0, At, B0); BAR;
	s_nop 0
	ds_read_b128 v[82:85], v142 offset:16384
	ds_read_b128 v[86:89], v142 offset:17408
	ds_read_b128 v[90:93], v142 offset:18432
	ds_read_b128 v[94:97], v142 offset:19456
	ds_read_b128 v[190:193], v142 offset:20480
	ds_read_b128 v[194:197], v142 offset:21504
	ds_read_b128 v[198:201], v142 offset:22528
	ds_read_b128 v[202:205], v142 offset:23552
	s_waitcnt vmcnt(4)
	s_barrier
	s_waitcnt lgkmcnt(0)
	v_mfma_f32_16x16x32_bf16 v[46:49], v[190:193], v[132:135], v[46:49]
	v_mfma_f32_16x16x32_bf16 v[42:45], v[190:193], v[148:151], v[42:45]
	v_mfma_f32_16x16x32_bf16 v[38:41], v[198:201], v[132:135], v[38:41]
	v_mfma_f32_16x16x32_bf16 v[34:37], v[198:201], v[148:151], v[34:37]
	v_mfma_f32_16x16x32_bf16 v[62:65], v[82:85], v[132:135], v[62:65]
	v_mfma_f32_16x16x32_bf16 v[58:61], v[82:85], v[148:151], v[58:61]
	v_mfma_f32_16x16x32_bf16 v[54:57], v[90:93], v[132:135], v[54:57]
	v_mfma_f32_16x16x32_bf16 v[50:53], v[90:93], v[148:151], v[50:53]
	v_mfma_f32_16x16x32_bf16 v[46:49], v[194:197], v[144:147], v[46:49]
	v_mfma_f32_16x16x32_bf16 v[42:45], v[194:197], v[152:155], v[42:45]
	v_mfma_f32_16x16x32_bf16 v[38:41], v[202:205], v[144:147], v[38:41]
	v_mfma_f32_16x16x32_bf16 v[34:37], v[202:205], v[152:155], v[34:37]
	v_mfma_f32_16x16x32_bf16 v[206:209], v[86:89], v[144:147], v[62:65]
	v_mfma_f32_16x16x32_bf16 v[230:233], v[86:89], v[152:155], v[58:61]
	v_mfma_f32_16x16x32_bf16 v[234:237], v[94:97], v[144:147], v[54:57]
	v_mfma_f32_16x16x32_bf16 v[238:241], v[94:97], v[152:155], v[50:53]
	v_mfma_f32_16x16x32_bf16 v[2:5], v[198:201], v[218:221], v[2:5]
	v_mfma_f32_16x16x32_bf16 v[30:33], v[82:85], v[114:117], v[30:33]
	v_mfma_f32_16x16x32_bf16 v[26:29], v[82:85], v[218:221], v[26:29]
	v_mfma_f32_16x16x32_bf16 v[22:25], v[90:93], v[114:117], v[22:25]
	v_mfma_f32_16x16x32_bf16 v[18:21], v[90:93], v[218:221], v[18:21]
	v_mfma_f32_16x16x32_bf16 v[14:17], v[190:193], v[114:117], v[14:17]
	v_mfma_f32_16x16x32_bf16 v[10:13], v[190:193], v[218:221], v[10:13]
	v_mfma_f32_16x16x32_bf16 v[6:9], v[198:201], v[114:117], v[6:9]
	v_mfma_f32_16x16x32_bf16 v[2:5], v[202:205], v[222:225], v[2:5]
	v_mfma_f32_16x16x32_bf16 v[130:133], v[86:89], v[214:217], v[30:33]
	v_mfma_f32_16x16x32_bf16 v[134:137], v[86:89], v[222:225], v[26:29]
	v_mfma_f32_16x16x32_bf16 v[144:147], v[94:97], v[214:217], v[22:25]
	v_mfma_f32_16x16x32_bf16 v[148:151], v[94:97], v[222:225], v[18:21]
	v_mfma_f32_16x16x32_bf16 v[152:155], v[194:197], v[214:217], v[14:17]
	v_mfma_f32_16x16x32_bf16 v[190:193], v[194:197], v[222:225], v[10:13]
	v_mfma_f32_16x16x32_bf16 v[194:197], v[202:205], v[214:217], v[6:9]
	v_add_u32_e32 v0, 0x18000, v138
	s_barrier
	ds_read_b128 v[6:9], v0
	ds_read_b128 v[10:13], v0 offset:1024
	ds_read_b128 v[14:17], v0 offset:2048
	ds_read_b128 v[198:201], v0 offset:3072
	ds_read_b128 v[18:21], v142 offset:32768
	ds_read_b128 v[22:25], v142 offset:33792
	ds_read_b128 v[26:29], v142 offset:34816
	ds_read_b128 v[50:53], v142 offset:35840
	ds_read_b128 v[202:205], v142 offset:36864
	ds_read_b128 v[214:217], v142 offset:37888
	ds_read_b128 v[218:221], v142 offset:38912
	ds_read_b128 v[222:225], v142 offset:39936
	s_waitcnt vmcnt(2)
	s_barrier
	s_waitcnt lgkmcnt(0)
	v_mfma_f32_16x16x32_bf16 v[30:33], v[18:21], v[6:9], v[126:129]
	v_mfma_f32_16x16x32_bf16 v[114:117], v[22:25], v[10:13], v[30:33]
	v_mfma_f32_16x16x32_bf16 v[30:33], v[18:21], v[14:17], v[122:125]
	v_mfma_f32_16x16x32_bf16 v[94:97], v[22:25], v[198:201], v[30:33]
	v_mfma_f32_16x16x32_bf16 v[30:33], v[26:29], v[6:9], v[118:121]
	v_mfma_f32_16x16x32_bf16 v[118:121], v[50:53], v[10:13], v[30:33]
	v_mfma_f32_16x16x32_bf16 v[30:33], v[26:29], v[14:17], v[210:213]
	v_mfma_f32_16x16x32_bf16 v[90:93], v[50:53], v[198:201], v[30:33]
	v_mfma_f32_16x16x32_bf16 v[30:33], v[202:205], v[6:9], v[110:113]
	v_mfma_f32_16x16x32_bf16 v[122:125], v[214:217], v[10:13], v[30:33]
	v_mfma_f32_16x16x32_bf16 v[30:33], v[202:205], v[14:17], v[106:109]
	v_mfma_f32_16x16x32_bf16 v[86:89], v[214:217], v[198:201], v[30:33]
	v_mfma_f32_16x16x32_bf16 v[30:33], v[218:221], v[6:9], v[102:105]
	v_mfma_f32_16x16x32_bf16 v[126:129], v[222:225], v[10:13], v[30:33]
	v_mfma_f32_16x16x32_bf16 v[30:33], v[218:221], v[14:17], v[98:101]
	v_mfma_f32_16x16x32_bf16 v[82:85], v[222:225], v[198:201], v[30:33]
	v_add_u32_e32 v0, 0x1c000, v138
	s_barrier
;     __device__ __forceinline__ unsigned* BAR() const { return (unsigned*)(ws + OFF_BAR); }
; #define LDA(dst, b, h) do { _Pragma("unroll") for (int m = 0; m < 4; ++m) _Pragma("unroll") for (int k = 0; k < 2; ++k) dst[m][k] = *(const LAS bf16x8*)(lds + SA(b, h) + aoff + m * 2048 + k * 1024); } while (0)
; #define LDB(dst, b, h) do { _Pragma("unroll") for (int n = 0; n < 2; ++n) _Pragma("unroll") for (int k = 0; k < 2; ++k) dst[n][k] = *(const LAS bf16x8*)(lds + SB(b, h) + boff + n * 2048 + k * 1024); } while (0)
; #define MMA(ai, bj, At, Bx) do { __builtin_amdgcn_s_setprio(1); _Pragma("unroll") for (int m = 0; m < 4; ++m) _Pragma("unroll") for (int n = 0; n < 2; ++n) _Pragma("unroll") for (int k = 0; k < 2; ++k) \
;       acc[ai][bj][m][n] = __builtin_amdgcn_mfma_f32_16x16x32_bf16(At[m][k], Bx[n][k], acc[ai][bj][m][n], 0, 0, 0); \
;     __builtin_amdgcn_s_setprio(0); } while (0)
; #define WAIT_V(n) asm volatile("s_waitcnt vmcnt(" #n ")" ::: "memory")
; #define WAIT_L(n) asm volatile("s_waitcnt lgkmcnt(" #n ")" ::: "memory")
; #define BAR __builtin_amdgcn_s_barrier()
;     ...
;       LDB(B1, 1, 1); WAIT_V(0); BAR; WAIT_L(0); MMA(0, 1, At, B1); BAR;
;       LDA(At, 1, 1); BAR; WAIT_L(0); MMA(1, 0, At, B0); MMA(1, 1, At, B1); BAR; }
;     if (wr == 0) BAR;
	ds_read_b128 v[210:213], v0
	ds_read_b128 v[242:245], v0 offset:1024
	ds_read_b128 v[246:249], v0 offset:2048
	ds_read_b128 v[138:141], v0 offset:3072
	s_waitcnt vmcnt(0)
	s_barrier
	s_waitcnt lgkmcnt(0)
	v_mfma_f32_16x16x32_bf16 v[30:33], v[18:21], v[210:213], v[226:229]
	v_mfma_f32_16x16x32_bf16 v[18:21], v[18:21], v[246:249], v[156:159]
	v_mfma_f32_16x16x32_bf16 v[62:65], v[22:25], v[242:245], v[30:33]
	v_mfma_f32_16x16x32_bf16 v[30:33], v[22:25], v[138:141], v[18:21]
	v_mfma_f32_16x16x32_bf16 v[18:21], v[26:29], v[210:213], v[160:163]
	v_mfma_f32_16x16x32_bf16 v[58:61], v[50:53], v[242:245], v[18:21]
	v_mfma_f32_16x16x32_bf16 v[18:21], v[26:29], v[246:249], v[164:167]
	v_mfma_f32_16x16x32_bf16 v[26:29], v[50:53], v[138:141], v[18:21]
	v_mfma_f32_16x16x32_bf16 v[18:21], v[202:205], v[210:213], v[78:81]
	v_mfma_f32_16x16x32_bf16 v[54:57], v[214:217], v[242:245], v[18:21]
	v_mfma_f32_16x16x32_bf16 v[18:21], v[202:205], v[246:249], v[74:77]
	v_mfma_f32_16x16x32_bf16 v[22:25], v[214:217], v[138:141], v[18:21]
	v_mfma_f32_16x16x32_bf16 v[18:21], v[218:221], v[210:213], v[70:73]
	v_mfma_f32_16x16x32_bf16 v[50:53], v[222:225], v[242:245], v[18:21]
	v_mfma_f32_16x16x32_bf16 v[18:21], v[218:221], v[246:249], v[66:69]
	v_mfma_f32_16x16x32_bf16 v[18:21], v[222:225], v[138:141], v[18:21]
	s_barrier
	ds_read_b128 v[156:159], v142 offset:49152
	ds_read_b128 v[160:163], v142 offset:50176
	ds_read_b128 v[164:167], v142 offset:51200
	ds_read_b128 v[202:205], v142 offset:52224
	ds_read_b128 v[214:217], v142 offset:53248
	ds_read_b128 v[218:221], v142 offset:54272
	ds_read_b128 v[222:225], v142 offset:55296
	ds_read_b128 v[226:229], v142 offset:56320
	s_barrier
	s_waitcnt lgkmcnt(0)
	v_mfma_f32_16x16x32_bf16 v[66:69], v[156:159], v[6:9], v[206:209]
	v_mfma_f32_16x16x32_bf16 v[110:113], v[160:163], v[10:13], v[66:69]
	v_mfma_f32_16x16x32_bf16 v[66:69], v[156:159], v[14:17], v[230:233]
	v_mfma_f32_16x16x32_bf16 v[78:81], v[160:163], v[198:201], v[66:69]
	v_mfma_f32_16x16x32_bf16 v[66:69], v[164:167], v[6:9], v[234:237]
	v_mfma_f32_16x16x32_bf16 v[46:49], v[214:217], v[6:9], v[46:49]
	v_mfma_f32_16x16x32_bf16 v[6:9], v[222:225], v[6:9], v[38:41]
	v_mfma_f32_16x16x32_bf16 v[106:109], v[202:205], v[10:13], v[66:69]
	v_mfma_f32_16x16x32_bf16 v[66:69], v[164:167], v[14:17], v[238:241]
	v_mfma_f32_16x16x32_bf16 v[42:45], v[214:217], v[14:17], v[42:45]
	v_mfma_f32_16x16x32_bf16 v[98:101], v[226:229], v[10:13], v[6:9]
	v_mfma_f32_16x16x32_bf16 v[6:9], v[222:225], v[14:17], v[34:37]
	v_mfma_f32_16x16x32_bf16 v[74:77], v[202:205], v[198:201], v[66:69]
	v_mfma_f32_16x16x32_bf16 v[102:105], v[218:221], v[10:13], v[46:49]
	v_mfma_f32_16x16x32_bf16 v[70:73], v[218:221], v[198:201], v[42:45]
	v_mfma_f32_16x16x32_bf16 v[66:69], v[226:229], v[198:201], v[6:9]
	v_mfma_f32_16x16x32_bf16 v[6:9], v[156:159], v[210:213], v[130:133]
	v_mfma_f32_16x16x32_bf16 v[46:49], v[160:163], v[242:245], v[6:9]
	v_mfma_f32_16x16x32_bf16 v[6:9], v[156:159], v[246:249], v[134:137]
	v_mfma_f32_16x16x32_bf16 v[14:17], v[160:163], v[138:141], v[6:9]
	v_mfma_f32_16x16x32_bf16 v[6:9], v[164:167], v[210:213], v[144:147]
	v_mfma_f32_16x16x32_bf16 v[42:45], v[202:205], v[242:245], v[6:9]
	v_mfma_f32_16x16x32_bf16 v[6:9], v[164:167], v[246:249], v[148:151]
	v_mfma_f32_16x16x32_bf16 v[10:13], v[202:205], v[138:141], v[6:9]
	v_mfma_f32_16x16x32_bf16 v[6:9], v[214:217], v[210:213], v[152:155]
	v_mfma_f32_16x16x32_bf16 v[38:41], v[218:221], v[242:245], v[6:9]
	v_mfma_f32_16x16x32_bf16 v[6:9], v[214:217], v[246:249], v[190:193]
	v_mfma_f32_16x16x32_bf16 v[34:37], v[222:225], v[210:213], v[194:197]
	v_mfma_f32_16x16x32_bf16 v[2:5], v[222:225], v[246:249], v[2:5]
	v_mfma_f32_16x16x32_bf16 v[6:9], v[218:221], v[138:141], v[6:9]
	v_mfma_f32_16x16x32_bf16 v[34:37], v[226:229], v[242:245], v[34:37]
	v_mfma_f32_16x16x32_bf16 v[2:5], v[226:229], v[138:141], v[2:5]
	s_cmpk_lt_u32 s12, 0x100
	s_barrier
	s_cbranch_scc0 .LBB0_206
	s_barrier
	s_branch .LBB0_206

; #define MFMA(a, b, c) __builtin_amdgcn_mfma_f32_32x32x16_bf16((a), (b), (c), 0, 0, 0)
; __device__ __forceinline__ unsigned pk2(float lo, float hi) { const f32x2_t f = {lo, hi}; const bf16x2_t b = __builtin_convertvector(f, bf16x2_t); return __builtin_bit_cast(unsigned, b); }
; template <int DV> ...
;     ...
;     float ps = 0.f;
; #pragma unroll
;     for (int sub = 0; sub < 2; sub++)
; #pragma unroll
;         for (int r = 0; r < 16; r++) { S[sub][r] = __builtin_amdgcn_exp2f(S[sub][r]); ps += S[sub][r]; }
;     l += ps;
; #pragma unroll
;     for (int sub = 0; sub < 2; sub++)
; #pragma unroll
;         for (int s = 0; s < 2; s++) {
;             u32x4 cv;
;             cv[0] = pk2(S[sub][8 * s + 0], S[sub][8 * s + 1]); cv[1] = pk2(S[sub][8 * s + 2], S[sub][8 * s + 3]);
;             cv[2] = pk2(S[sub][8 * s + 4], S[sub][8 * s + 5]); cv[3] = pk2(S[sub][8 * s + 6], S[sub][8 * s + 7]);
;             const bf16x8 pb = __builtin_bit_cast(bf16x8, cv);
; #pragma unroll
;             for (int dt = 0; dt < DV / 32; dt++) {
;                 const bf16x8 vf = *(const bf16x8*)(Vl + (dt * 32 + l31) * LROW + (sub * 4 + s * 2 + hh) * 16);
;                 O[dt] = MFMA(vf, pb, O[dt]);
;             }
;         }
; template <bool DIFF>
; __device__ __forceinline__ void attn_unit(const Params& p, int layer, int mode, int bl, int hidx, int qblk, bool isctx, unsigned char* lds) {
;     ...
;         if (more) {
;             unsigned char* wb = lds + ((it + 1) & 1) * BUFB + lr * LROW + lc * 16;
; #pragma unroll
;             for (int i = 0; i < NKM; i++) *(u32x4*)(wb + i * 9216) = kr[i];
; #pragma unroll
;             for (int i = 0; i < DV / 64; i++) *(u32x4*)(wb + KBYTES + i * 64 * LROW) = vr[i];
;         }
.LBB0_488:
	v_exp_f32_e32 v66, v66
	v_exp_f32_e32 v67, v67
	v_exp_f32_e32 v68, v68
	v_exp_f32_e32 v69, v69
	v_exp_f32_e32 v70, v70
	v_exp_f32_e32 v71, v71
	v_exp_f32_e32 v72, v72
	v_exp_f32_e32 v73, v73
	v_cvt_pk_bf16_f32 v142, v66, v67
	v_cvt_pk_bf16_f32 v143, v68, v69
	v_add_f32_e32 v150, v67, v66
	v_cvt_pk_bf16_f32 v144, v70, v71
	v_add_f32_e32 v150, v68, v150
	v_cvt_pk_bf16_f32 v145, v72, v73
	v_add_f32_e32 v150, v69, v150
	v_add_f32_e32 v150, v70, v150
	s_waitcnt lgkmcnt(0)
	v_mfma_f32_32x32x16_bf16 v[18:33], v[224:227], v[142:145], v[18:33]
	v_exp_f32_e32 v74, v74
	v_exp_f32_e32 v75, v75
	v_exp_f32_e32 v76, v76
	v_exp_f32_e32 v77, v77
	v_add_f32_e32 v150, v71, v150
	v_mfma_f32_32x32x16_bf16 v[2:17], v[228:231], v[142:145], v[2:17]
	v_exp_f32_e32 v78, v78
	v_exp_f32_e32 v79, v79
	v_exp_f32_e32 v80, v80
	v_exp_f32_e32 v81, v81
	v_add_f32_e32 v150, v72, v150
	v_add_f32_e32 v150, v73, v150
	v_cvt_pk_bf16_f32 v146, v74, v75
	v_cvt_pk_bf16_f32 v147, v76, v77
	v_cvt_pk_bf16_f32 v148, v78, v79
	v_cvt_pk_bf16_f32 v149, v80, v81
	v_add_f32_e32 v150, v74, v150
	v_add_f32_e32 v150, v75, v150
	v_mfma_f32_32x32x16_bf16 v[2:17], v[232:235], v[146:149], v[2:17]
	v_exp_f32_e32 v50, v50
	v_exp_f32_e32 v51, v51
	v_exp_f32_e32 v52, v52
	v_exp_f32_e32 v53, v53
	v_add_f32_e32 v150, v76, v150
	v_add_f32_e32 v150, v77, v150
	v_mfma_f32_32x32x16_bf16 v[18:33], v[236:239], v[146:149], v[18:33]
	v_exp_f32_e32 v54, v54
	v_exp_f32_e32 v55, v55
	v_exp_f32_e32 v56, v56
	v_exp_f32_e32 v57, v57
	v_add_f32_e32 v150, v78, v150
	v_add_f32_e32 v150, v79, v150
	v_add_f32_e32 v150, v80, v150
	v_add_f32_e32 v150, v81, v150
	v_cvt_pk_bf16_f32 v142, v50, v51
	v_cvt_pk_bf16_f32 v143, v52, v53
	v_cvt_pk_bf16_f32 v144, v54, v55
	v_cvt_pk_bf16_f32 v145, v56, v57
	v_add_f32_e32 v150, v50, v150
	v_add_f32_e32 v150, v51, v150
	v_mfma_f32_32x32x16_bf16 v[18:33], v[240:243], v[142:145], v[18:33]
	v_exp_f32_e32 v58, v58
	v_exp_f32_e32 v59, v59
	v_exp_f32_e32 v60, v60
	v_exp_f32_e32 v61, v61
	v_add_f32_e32 v150, v52, v150
	v_add_f32_e32 v150, v53, v150
	v_mfma_f32_32x32x16_bf16 v[2:17], v[244:247], v[142:145], v[2:17]
	v_exp_f32_e32 v62, v62
	v_exp_f32_e32 v63, v63
	v_exp_f32_e32 v64, v64
	v_exp_f32_e32 v65, v65
	v_add_f32_e32 v150, v54, v150
	v_add_f32_e32 v150, v55, v150
	v_add_f32_e32 v150, v56, v150
	v_add_f32_e32 v150, v57, v150
	v_cvt_pk_bf16_f32 v146, v58, v59
	v_cvt_pk_bf16_f32 v147, v60, v61
	v_cvt_pk_bf16_f32 v148, v62, v63
	v_cvt_pk_bf16_f32 v149, v64, v65
	v_add_f32_e32 v150, v58, v150
	v_add_f32_e32 v150, v59, v150
	v_mfma_f32_32x32x16_bf16 v[18:33], v[134:137], v[146:149], v[18:33]
	v_add_f32_e32 v150, v60, v150
	v_add_f32_e32 v150, v61, v150
	v_add_f32_e32 v150, v62, v150
	v_mfma_f32_32x32x16_bf16 v[2:17], v[138:141], v[146:149], v[2:17]
	v_add_f32_e32 v150, v63, v150
	v_add_f32_e32 v150, v64, v150
	v_add_f32_e32 v150, v65, v150
	s_andn2_b64 vcc, exec, s[42:43]
	s_cbranch_vccnz .LBB0_490
	s_bitcmp1_b32 s31, 0
	s_cselect_b32 s16, 0x4800, 0
	v_add_u32_e32 v120, s16, v115
	s_waitcnt vmcnt(0)
	ds_write_b128 v120, v[98:101]
	ds_write_b128 v120, v[102:105] offset:9216

; #define MFMA(a, b, c) __builtin_amdgcn_mfma_f32_32x32x16_bf16((a), (b), (c), 0, 0, 0)
; __device__ __forceinline__ unsigned pk2(float lo, float hi) { const f32x2_t f = {lo, hi}; const bf16x2_t b = __builtin_convertvector(f, bf16x2_t); return __builtin_bit_cast(unsigned, b); }
; template <int DV>
; __device__ __forceinline__ void attn_tile(const unsigned char* Kl, const unsigned char* Vl, const bf16x8 (&qf)[4], f32x16 (&O)[DV / 32], float& m, float& l,
;                                           int l31, int hh, bool domask, int qpos, int kpos0) {
;     ...
;     float ps = 0.f;
; #pragma unroll
;     for (int sub = 0; sub < 2; sub++)
; #pragma unroll
;         for (int r = 0; r < 16; r++) { S[sub][r] = __builtin_amdgcn_exp2f(__builtin_fmaf(S[sub][r], SL2, -m)); ps += S[sub][r]; }
;     l += ps;
;     bf16x8 pb[2][2];
; #pragma unroll
;     for (int sub = 0; sub < 2; sub++)
; #pragma unroll
;         for (int s = 0; s < 2; s++) {
;             u32x4 cv;
;             cv[0] = pk2(S[sub][8 * s + 0], S[sub][8 * s + 1]); cv[1] = pk2(S[sub][8 * s + 2], S[sub][8 * s + 3]);
;             cv[2] = pk2(S[sub][8 * s + 4], S[sub][8 * s + 5]); cv[3] = pk2(S[sub][8 * s + 6], S[sub][8 * s + 7]);
;             pb[sub][s] = __builtin_bit_cast(bf16x8, cv);
;         }
; #pragma unroll
;     for (int sub = 0; sub < 2; sub++)
; #pragma unroll
;         for (int s = 0; s < 2; s++)
; #pragma unroll
;             for (int dt = 0; dt < DV / 32; dt++) {
;                 const bf16x8 vf = *(const bf16x8*)(Vl + (dt * 32 + l31) * LROW + (sub * 4 + s * 2 + hh) * 16);
;                 O[dt] = MFMA(vf, pb[sub][s], O[dt]);
;             }
; template <bool DIFF>
; __device__ __forceinline__ void attn_unit(const Params& p, int layer, int mode, int bl, int hidx, int qblk, bool isctx, unsigned char* lds) {
;     ...
;         if (more) {
;             unsigned char* wb = lds + ((it + 1) & 1) * BUFB + lr * LROW + lc * 16;
; #pragma unroll
;             for (int i = 0; i < NKM; i++) *(u32x4*)(wb + i * 9216) = kr[i];
; #pragma unroll
;             for (int i = 0; i < DV / 64; i++) *(u32x4*)(wb + KBYTES + i * 64 * LROW) = vr[i];
;         }
;         __syncthreads();
.LBB0_498:
	v_exp_f32_e32 v96, v96
	v_exp_f32_e32 v97, v97
	v_exp_f32_e32 v98, v98
	v_exp_f32_e32 v99, v99
	v_exp_f32_e32 v100, v100
	v_exp_f32_e32 v101, v101
	v_exp_f32_e32 v102, v102
	v_exp_f32_e32 v103, v103
	v_cvt_pk_bf16_f32 v164, v96, v97
	v_cvt_pk_bf16_f32 v165, v98, v99
	v_add_f32_e32 v14, v97, v96
	v_cvt_pk_bf16_f32 v166, v100, v101
	v_add_f32_e32 v14, v98, v14
	v_add_f32_e32 v14, v99, v14
	v_cvt_pk_bf16_f32 v167, v102, v103
	v_add_f32_e32 v14, v100, v14
	v_add_f32_e32 v14, v101, v14
	s_waitcnt lgkmcnt(0)
	v_mfma_f32_32x32x16_bf16 v[64:79], v[226:229], v[164:167], v[64:79]
	ds_read_b128 v[226:229], v193 offset:18528
	v_exp_f32_e32 v104, v104
	v_exp_f32_e32 v105, v105
	v_exp_f32_e32 v106, v106
	v_exp_f32_e32 v107, v107
	v_mfma_f32_32x32x16_bf16 v[48:63], v[230:233], v[164:167], v[48:63]
	ds_read_b128 v[230:233], v193 offset:23136
	v_exp_f32_e32 v108, v108
	v_exp_f32_e32 v109, v109
	v_exp_f32_e32 v110, v110
	v_exp_f32_e32 v111, v111
	v_add_f32_e32 v14, v102, v14
	v_mfma_f32_32x32x16_bf16 v[32:47], v[156:159], v[164:167], v[32:47]
	ds_read_b128 v[156:159], v193 offset:27744
	v_add_f32_e32 v14, v103, v14
	v_cvt_pk_bf16_f32 v96, v104, v105
	v_cvt_pk_bf16_f32 v97, v106, v107
	v_add_f32_e32 v14, v104, v14
	v_mfma_f32_32x32x16_bf16 v[16:31], v[160:163], v[164:167], v[16:31]
	ds_read_b128 v[160:163], v193 offset:32352
	v_add_f32_e32 v14, v105, v14
	v_cvt_pk_bf16_f32 v98, v108, v109
	v_add_f32_e32 v14, v106, v14
	v_cvt_pk_bf16_f32 v99, v110, v111
	v_add_f32_e32 v14, v107, v14
	v_add_f32_e32 v14, v108, v14
	v_add_f32_e32 v14, v109, v14
	v_mfma_f32_32x32x16_bf16 v[64:79], v[194:197], v[96:99], v[64:79]
	v_exp_f32_e32 v80, v80
	v_exp_f32_e32 v81, v81
	v_exp_f32_e32 v82, v82
	v_exp_f32_e32 v83, v83
	v_mfma_f32_32x32x16_bf16 v[48:63], v[198:201], v[96:99], v[48:63]
	v_exp_f32_e32 v84, v84
	v_exp_f32_e32 v85, v85
	v_exp_f32_e32 v86, v86
	v_exp_f32_e32 v87, v87
	v_add_f32_e32 v14, v110, v14
	v_mfma_f32_32x32x16_bf16 v[32:47], v[202:205], v[96:99], v[32:47]
	v_add_f32_e32 v14, v111, v14
	v_cvt_pk_bf16_f32 v100, v80, v81
	v_cvt_pk_bf16_f32 v101, v82, v83
	v_add_f32_e32 v14, v80, v14
	v_mfma_f32_32x32x16_bf16 v[16:31], v[206:209], v[96:99], v[16:31]
	v_add_f32_e32 v14, v81, v14
	v_cvt_pk_bf16_f32 v102, v84, v85
	v_add_f32_e32 v14, v82, v14
	v_cvt_pk_bf16_f32 v103, v86, v87
	v_add_f32_e32 v14, v83, v14
	v_add_f32_e32 v14, v84, v14
	v_add_f32_e32 v14, v85, v14
	v_mfma_f32_32x32x16_bf16 v[64:79], v[210:213], v[100:103], v[64:79]
	v_exp_f32_e32 v88, v88
	v_exp_f32_e32 v89, v89
	v_exp_f32_e32 v90, v90
	v_exp_f32_e32 v91, v91
	v_mfma_f32_32x32x16_bf16 v[48:63], v[214:217], v[100:103], v[48:63]
	v_exp_f32_e32 v92, v92
	v_exp_f32_e32 v93, v93
	v_exp_f32_e32 v94, v94
	v_exp_f32_e32 v95, v95
	v_add_f32_e32 v14, v86, v14
	v_mfma_f32_32x32x16_bf16 v[32:47], v[218:221], v[100:103], v[32:47]
	v_add_f32_e32 v14, v87, v14
	v_cvt_pk_bf16_f32 v104, v88, v89
	v_cvt_pk_bf16_f32 v105, v90, v91
	v_add_f32_e32 v14, v88, v14
	v_mfma_f32_32x32x16_bf16 v[16:31], v[222:225], v[100:103], v[16:31]
	v_add_f32_e32 v14, v89, v14
	v_cvt_pk_bf16_f32 v106, v92, v93
	v_add_f32_e32 v14, v90, v14
	v_cvt_pk_bf16_f32 v107, v94, v95
	v_add_f32_e32 v14, v91, v14
	v_add_f32_e32 v14, v92, v14
	v_add_f32_e32 v14, v93, v14
	s_waitcnt lgkmcnt(3)
	v_mfma_f32_32x32x16_bf16 v[64:79], v[226:229], v[104:107], v[64:79]
	v_add_f32_e32 v14, v94, v14
	s_add_i32 s24, s24, 1
	v_add_f32_e32 v14, v95, v14
	s_bitcmp1_b32 s24, 0
	s_cselect_b32 s8, 0x9000, 0
	s_add_i32 s1, s1, 64
	s_waitcnt lgkmcnt(2)
	v_mfma_f32_32x32x16_bf16 v[48:63], v[230:233], v[104:107], v[48:63]
	v_add_f32_e32 v145, v145, v14
	v_add_u32_e32 v0, s8, v147
	s_waitcnt vmcnt(0)
	ds_write_b128 v0, v[2:5]
	ds_write_b128 v0, v[6:9] offset:9216
	ds_write_b128 v0, v[10:13] offset:18432
	ds_write_b128 v0, v[128:131] offset:27648
	s_cmp_eq_u32 s0, s24
	s_waitcnt lgkmcnt(0)
	s_barrier
	v_mfma_f32_32x32x16_bf16 v[32:47], v[156:159], v[104:107], v[32:47]
	v_mfma_f32_32x32x16_bf16 v[16:31], v[160:163], v[104:107], v[16:31]
	s_cbranch_scc1 .LBB0_501

;     __device__ __forceinline__ unsigned* BAR() const { return (unsigned*)(ws + OFF_BAR); }
; #define STAGE(bufoff, gbase, voff) do { _Pragma("unroll") for (int _i = 0; _i < 2; ++_i) \
;         __builtin_amdgcn_global_load_lds((const unsigned*)((const char*)(gbase) + voff[_i]), (LAS unsigned*)(lds + (bufoff) + ldsw + _i * 8192), 16, 0, 0); } while (0)
; #define LDA(dst, b, h) do { _Pragma("unroll") for (int m = 0; m < 4; ++m) _Pragma("unroll") for (int k = 0; k < 2; ++k) dst[m][k] = *(const LAS bf16x8*)(lds + SA(b, h) + aoff + m * 2048 + k * 1024); } while (0)
; #define LDB(dst, b, h) do { _Pragma("unroll") for (int n = 0; n < 2; ++n) _Pragma("unroll") for (int k = 0; k < 2; ++k) dst[n][k] = *(const LAS bf16x8*)(lds + SB(b, h) + boff + n * 2048 + k * 1024); } while (0)
; #define MMA(ai, bj, At, Bx) do { __builtin_amdgcn_s_setprio(1); _Pragma("unroll") for (int m = 0; m < 4; ++m) _Pragma("unroll") for (int n = 0; n < 2; ++n) _Pragma("unroll") for (int k = 0; k < 2; ++k) \
;       acc[ai][bj][m][n] = __builtin_amdgcn_mfma_f32_16x16x32_bf16(At[m][k], Bx[n][k], acc[ai][bj][m][n], 0, 0, 0); \
;     __builtin_amdgcn_s_setprio(0); } while (0)
; #define WAIT_V(n) asm volatile("s_waitcnt vmcnt(" #n ")" ::: "memory")
; #define WAIT_L(n) asm volatile("s_waitcnt lgkmcnt(" #n ")" ::: "memory")
; #define BAR __builtin_amdgcn_s_barrier()
; #define SCHED __builtin_amdgcn_sched_barrier(0)
;     ...
;     auto pA = [&](int T) -> const char* { return KSEG ? cA + (size_t)(T / (KSEG ? KSEG : 1)) * segA + (size_t)(T % (KSEG ? KSEG : 1)) * kstep : cA + (size_t)T * kstep; };
;     auto pB = [&](int T) -> const char* { return KSEG ? cB + (size_t)(T / (KSEG ? KSEG : 1)) * segB + (size_t)(T % (KSEG ? KSEG : 1)) * kstep : cB + (size_t)T * kstep; };
;     ...
;         const char* a1 = pA(t + 1); const char* a2 = pA(t + 2); const char* a3 = pA(t + 3);
;         const char* b2 = pB(t + 2); const char* b3 = pB(t + 3);
;         LDB(B0, 0, 0); SCHED; LDA(At, 0, 0); STAGE(SA(1, 1), a1 + hstepA, voffA);
;         WAIT_L(8); BAR; WAIT_L(0); MMA(0, 0, At, B0); BAR; SCHED;
;         LDB(B1, 0, 1); STAGE(SB(0, 0), b2, voffB);
;         BAR; WAIT_L(0); MMA(0, 1, At, B1); BAR;
;         LDA(At, 0, 1); STAGE(SA(0, 0), a2, voffA);
;         BAR; WAIT_L(0); MMA(1, 0, At, B0); BAR; SCHED;
;         STAGE(SB(0, 1), b2 + hstepB, voffB);
;         WAIT_V(6); BAR; MMA(1, 1, At, B1); BAR;
.LBB0_574:
	s_add_i32 s10, s12, 4
	s_lshr_b32 s24, s10, 3
	s_and_b32 s17, s43, 0x300000
	s_and_b32 vcc_lo, s8, 0x300
	s_lshl_b64 s[14:15], s[24:25], 20
	s_add_u32 s10, s8, 0x100
	s_addc_u32 s11, s9, 0
	s_add_i32 s9, s12, 5
	s_lshr_b32 s12, s9, 3
	s_mov_b32 s13, s25
	s_addk_i32 s8, 0x180
	s_and_b32 s94, s10, 0x300
	s_lshl_b64 s[92:93], s[12:13], 20
	s_and_b32 vcc_hi, s8, 0x380
	s_mul_i32 s9, s24, 0x1200000
	s_mul_hi_u32 s8, s24, 0x1200000
	s_add_u32 s9, s6, s9
	s_addc_u32 s8, s7, s8
	s_mul_hi_u32 s13, s12, 0x1200000
	s_mul_i32 s12, s12, 0x1200000
	s_add_u32 s55, s6, s12
	s_addc_u32 s16, s7, s13
	s_add_i32 s45, 0, 0x10000
	v_add_u32_e32 v138, s45, v143
	ds_read_b128 v[130:133], v138
	ds_read_b128 v[134:137], v138 offset:1024
	ds_read_b128 v[144:147], v138 offset:2048
	ds_read_b128 v[148:151], v138 offset:3072
	s_add_u32 s12, s4, s17
	s_addc_u32 s13, s5, 0
	s_add_u32 s17, s4, s14
	s_addc_u32 s23, s5, s15
	s_add_u32 s24, s4, s92
	s_addc_u32 s92, s5, s93
	s_add_u32 s14, s9, s94
	s_addc_u32 s15, s8, 0
	s_add_u32 s12, s12, vcc_lo
	s_addc_u32 s13, s13, 0
	s_add_u32 s8, s24, vcc_hi
	s_addc_u32 s9, s92, 0
	s_add_u32 s12, s12, 0x20080
	s_addc_u32 s13, s13, 0
	s_add_i32 vcc_lo, s75, 0xc000
	v_lshl_add_u64 v[138:139], s[12:13], 0, v[0:1]
	s_mov_b32 m0, vcc_lo
	s_add_i32 s24, s75, 0xe000
	ds_read_b128 v[152:155], v142
	ds_read_b128 v[156:159], v142 offset:1024
	ds_read_b128 v[160:163], v142 offset:2048
	ds_read_b128 v[164:167], v142 offset:3072
	ds_read_b128 v[190:193], v142 offset:4096
	ds_read_b128 v[194:197], v142 offset:5120
	ds_read_b128 v[198:201], v142 offset:6144
	ds_read_b128 v[202:205], v142 offset:7168
	global_load_lds_dwordx4 v[138:139], off
	v_lshl_add_u64 v[138:139], s[12:13], 0, v[140:141]
	s_mov_b32 m0, s24
	s_add_u32 s12, s17, s94
	global_load_lds_dwordx4 v[138:139], off
	s_waitcnt lgkmcnt(8)
	s_barrier
	s_waitcnt lgkmcnt(0)
	s_addc_u32 s13, s23, 0
	s_waitcnt lgkmcnt(0)
	v_mfma_f32_16x16x32_bf16 v[126:129], v[152:155], v[130:133], v[126:129]
	v_mfma_f32_16x16x32_bf16 v[122:125], v[152:155], v[144:147], v[122:125]
	v_mfma_f32_16x16x32_bf16 v[118:121], v[160:163], v[130:133], v[118:121]
	v_mfma_f32_16x16x32_bf16 v[114:117], v[160:163], v[144:147], v[114:117]
	v_mfma_f32_16x16x32_bf16 v[110:113], v[190:193], v[130:133], v[110:113]
	v_mfma_f32_16x16x32_bf16 v[106:109], v[190:193], v[144:147], v[106:109]
	v_mfma_f32_16x16x32_bf16 v[102:105], v[198:201], v[130:133], v[102:105]
	v_mfma_f32_16x16x32_bf16 v[98:101], v[198:201], v[144:147], v[98:101]
	v_mfma_f32_16x16x32_bf16 v[126:129], v[156:159], v[134:137], v[126:129]
	v_mfma_f32_16x16x32_bf16 v[122:125], v[156:159], v[148:151], v[122:125]
	v_mfma_f32_16x16x32_bf16 v[118:121], v[164:167], v[134:137], v[118:121]
	v_mfma_f32_16x16x32_bf16 v[114:117], v[164:167], v[148:151], v[114:117]
	v_mfma_f32_16x16x32_bf16 v[110:113], v[194:197], v[134:137], v[110:113]
	v_mfma_f32_16x16x32_bf16 v[106:109], v[194:197], v[148:151], v[106:109]
	v_mfma_f32_16x16x32_bf16 v[102:105], v[202:205], v[134:137], v[102:105]
	v_mfma_f32_16x16x32_bf16 v[98:101], v[202:205], v[148:151], v[98:101]
	s_barrier
	s_add_i32 s17, 0, 0x14000
	v_add_u32_e32 v138, s17, v143
	s_add_i32 s23, s45, s1
	ds_read_b128 v[206:209], v138
	ds_read_b128 v[210:213], v138 offset:1024
	ds_read_b128 v[214:217], v138 offset:2048
	ds_read_b128 v[218:221], v138 offset:3072
	s_mov_b32 m0, s23
	v_lshl_add_u64 v[138:139], s[14:15], 0, v[0:1]
	global_load_lds_dwordx4 v[138:139], off
	v_lshl_add_u64 v[138:139], s[14:15], 0, v[140:141]
	s_add_i32 m0, s23, 0x2000
	s_nop 0
	global_load_lds_dwordx4 v[138:139], off
	s_barrier
	s_waitcnt lgkmcnt(0)
	v_mfma_f32_16x16x32_bf16 v[94:97], v[152:155], v[206:209], v[94:97]
	v_mfma_f32_16x16x32_bf16 v[90:93], v[152:155], v[214:217], v[90:93]
	v_mfma_f32_16x16x32_bf16 v[86:89], v[160:163], v[206:209], v[86:89]
	v_mfma_f32_16x16x32_bf16 v[82:85], v[160:163], v[214:217], v[82:85]
	v_mfma_f32_16x16x32_bf16 v[78:81], v[190:193], v[206:209], v[78:81]
	v_mfma_f32_16x16x32_bf16 v[74:77], v[190:193], v[214:217], v[74:77]
	v_mfma_f32_16x16x32_bf16 v[70:73], v[198:201], v[206:209], v[70:73]
	v_mfma_f32_16x16x32_bf16 v[66:69], v[198:201], v[214:217], v[66:69]
	v_mfma_f32_16x16x32_bf16 v[94:97], v[156:159], v[210:213], v[94:97]
	v_mfma_f32_16x16x32_bf16 v[90:93], v[156:159], v[218:221], v[90:93]
	v_mfma_f32_16x16x32_bf16 v[86:89], v[164:167], v[210:213], v[86:89]
	v_mfma_f32_16x16x32_bf16 v[82:85], v[164:167], v[218:221], v[82:85]
	v_mfma_f32_16x16x32_bf16 v[78:81], v[194:197], v[210:213], v[78:81]
	v_mfma_f32_16x16x32_bf16 v[74:77], v[194:197], v[218:221], v[74:77]
	v_mfma_f32_16x16x32_bf16 v[70:73], v[202:205], v[210:213], v[70:73]
	v_mfma_f32_16x16x32_bf16 v[66:69], v[202:205], v[218:221], v[66:69]
	s_barrier
	s_mov_b32 m0, s75
	v_lshl_add_u64 v[138:139], s[12:13], 0, v[0:1]
	ds_read_b128 v[152:155], v142 offset:16384
	ds_read_b128 v[156:159], v142 offset:17408
	ds_read_b128 v[160:163], v142 offset:18432
	ds_read_b128 v[164:167], v142 offset:19456
	ds_read_b128 v[190:193], v142 offset:20480
	ds_read_b128 v[194:197], v142 offset:21504
	ds_read_b128 v[198:201], v142 offset:22528
	ds_read_b128 v[202:205], v142 offset:23552
	global_load_lds_dwordx4 v[138:139], off
	s_mov_b32 m0, s76
	v_lshl_add_u64 v[138:139], s[12:13], 0, v[140:141]
	global_load_lds_dwordx4 v[138:139], off
	s_barrier
;     __device__ __forceinline__ unsigned* BAR() const { return (unsigned*)(ws + OFF_BAR); }
; #define STAGE(bufoff, gbase, voff) do { _Pragma("unroll") for (int _i = 0; _i < 2; ++_i) \
;         __builtin_amdgcn_global_load_lds((const unsigned*)((const char*)(gbase) + voff[_i]), (LAS unsigned*)(lds + (bufoff) + ldsw + _i * 8192), 16, 0, 0); } while (0)
; #define LDA(dst, b, h) do { _Pragma("unroll") for (int m = 0; m < 4; ++m) _Pragma("unroll") for (int k = 0; k < 2; ++k) dst[m][k] = *(const LAS bf16x8*)(lds + SA(b, h) + aoff + m * 2048 + k * 1024); } while (0)
; #define LDB(dst, b, h) do { _Pragma("unroll") for (int n = 0; n < 2; ++n) _Pragma("unroll") for (int k = 0; k < 2; ++k) dst[n][k] = *(const LAS bf16x8*)(lds + SB(b, h) + boff + n * 2048 + k * 1024); } while (0)
; #define MMA(ai, bj, At, Bx) do { __builtin_amdgcn_s_setprio(1); _Pragma("unroll") for (int m = 0; m < 4; ++m) _Pragma("unroll") for (int n = 0; n < 2; ++n) _Pragma("unroll") for (int k = 0; k < 2; ++k) \
;       acc[ai][bj][m][n] = __builtin_amdgcn_mfma_f32_16x16x32_bf16(At[m][k], Bx[n][k], acc[ai][bj][m][n], 0, 0, 0); \
;     __builtin_amdgcn_s_setprio(0); } while (0)
; #define WAIT_V(n) asm volatile("s_waitcnt vmcnt(" #n ")" ::: "memory")
; #define WAIT_L(n) asm volatile("s_waitcnt lgkmcnt(" #n ")" ::: "memory")
; #define BAR __builtin_amdgcn_s_barrier()
; #define SCHED __builtin_amdgcn_sched_barrier(0)
;     ...
;         STAGE(SB(0, 1), b2 + hstepB, voffB);
;         WAIT_V(6); BAR; MMA(1, 1, At, B1); BAR;
;         LDB(B0, 1, 0); SCHED; LDA(At, 1, 0); STAGE(SA(0, 1), a2 + hstepA, voffA);
;         WAIT_L(8); BAR; WAIT_L(0); MMA(0, 0, At, B0); BAR; SCHED;
;         LDB(B1, 1, 1); STAGE(SB(1, 0), b3, voffB);
;         BAR; WAIT_L(0); MMA(0, 1, At, B1); BAR;
;         LDA(At, 1, 1); STAGE(SA(1, 0), a3, voffA);
;         BAR; WAIT_L(0); MMA(1, 0, At, B0); BAR; SCHED;
	s_waitcnt lgkmcnt(0)
	v_mfma_f32_16x16x32_bf16 v[62:65], v[152:155], v[130:133], v[62:65]
	v_mfma_f32_16x16x32_bf16 v[58:61], v[152:155], v[144:147], v[58:61]
	v_mfma_f32_16x16x32_bf16 v[54:57], v[160:163], v[130:133], v[54:57]
	v_mfma_f32_16x16x32_bf16 v[50:53], v[160:163], v[144:147], v[50:53]
	v_mfma_f32_16x16x32_bf16 v[46:49], v[190:193], v[130:133], v[46:49]
	v_mfma_f32_16x16x32_bf16 v[42:45], v[190:193], v[144:147], v[42:45]
	v_mfma_f32_16x16x32_bf16 v[38:41], v[198:201], v[130:133], v[38:41]
	v_mfma_f32_16x16x32_bf16 v[34:37], v[198:201], v[144:147], v[34:37]
	v_mfma_f32_16x16x32_bf16 v[62:65], v[156:159], v[134:137], v[62:65]
	v_mfma_f32_16x16x32_bf16 v[58:61], v[156:159], v[148:151], v[58:61]
	v_mfma_f32_16x16x32_bf16 v[54:57], v[164:167], v[134:137], v[54:57]
	v_mfma_f32_16x16x32_bf16 v[50:53], v[164:167], v[148:151], v[50:53]
	v_mfma_f32_16x16x32_bf16 v[46:49], v[194:197], v[134:137], v[46:49]
	v_mfma_f32_16x16x32_bf16 v[42:45], v[194:197], v[148:151], v[42:45]
	v_mfma_f32_16x16x32_bf16 v[38:41], v[202:205], v[134:137], v[38:41]
	v_mfma_f32_16x16x32_bf16 v[34:37], v[202:205], v[148:151], v[34:37]
	s_barrier
	s_add_u32 s14, s14, 0x20000
	s_addc_u32 s15, s15, 0
	s_add_i32 s17, s17, s1
	s_mov_b32 m0, s17
	v_lshl_add_u64 v[130:131], s[14:15], 0, v[0:1]
	global_load_lds_dwordx4 v[130:131], off
	v_lshl_add_u64 v[130:131], s[14:15], 0, v[140:141]
	s_add_i32 m0, s17, 0x2000
	s_nop 0
	global_load_lds_dwordx4 v[130:131], off
	s_waitcnt vmcnt(6)
	s_barrier
	v_mfma_f32_16x16x32_bf16 v[30:33], v[152:155], v[206:209], v[30:33]
	v_mfma_f32_16x16x32_bf16 v[26:29], v[152:155], v[214:217], v[26:29]
	v_mfma_f32_16x16x32_bf16 v[22:25], v[160:163], v[206:209], v[22:25]
	v_mfma_f32_16x16x32_bf16 v[18:21], v[160:163], v[214:217], v[18:21]
	v_mfma_f32_16x16x32_bf16 v[14:17], v[190:193], v[206:209], v[14:17]
	v_mfma_f32_16x16x32_bf16 v[10:13], v[190:193], v[214:217], v[10:13]
	v_mfma_f32_16x16x32_bf16 v[6:9], v[198:201], v[206:209], v[6:9]
	v_mfma_f32_16x16x32_bf16 v[2:5], v[198:201], v[214:217], v[2:5]
	v_mfma_f32_16x16x32_bf16 v[30:33], v[156:159], v[210:213], v[30:33]
	v_mfma_f32_16x16x32_bf16 v[26:29], v[156:159], v[218:221], v[26:29]
	v_mfma_f32_16x16x32_bf16 v[22:25], v[164:167], v[210:213], v[22:25]
	v_mfma_f32_16x16x32_bf16 v[18:21], v[164:167], v[218:221], v[18:21]
	v_mfma_f32_16x16x32_bf16 v[14:17], v[194:197], v[210:213], v[14:17]
	v_mfma_f32_16x16x32_bf16 v[10:13], v[194:197], v[218:221], v[10:13]
	v_mfma_f32_16x16x32_bf16 v[6:9], v[202:205], v[210:213], v[6:9]
	v_mfma_f32_16x16x32_bf16 v[2:5], v[202:205], v[218:221], v[2:5]
	s_barrier
	s_add_i32 s14, 0, 0x18000
	v_add_u32_e32 v138, s14, v143
	ds_read_b128 v[130:133], v138
	ds_read_b128 v[134:137], v138 offset:1024
	ds_read_b128 v[144:147], v138 offset:2048
	ds_read_b128 v[148:151], v138 offset:3072
	s_add_u32 s12, s12, 0x20000
	s_addc_u32 s13, s13, 0
	s_mov_b32 m0, s77
	v_lshl_add_u64 v[138:139], s[12:13], 0, v[0:1]
	ds_read_b128 v[152:155], v142 offset:32768
	ds_read_b128 v[156:159], v142 offset:33792
	ds_read_b128 v[160:163], v142 offset:34816
	ds_read_b128 v[164:167], v142 offset:35840
	ds_read_b128 v[190:193], v142 offset:36864
	ds_read_b128 v[194:197], v142 offset:37888
	ds_read_b128 v[198:201], v142 offset:38912
	ds_read_b128 v[202:205], v142 offset:39936
	global_load_lds_dwordx4 v[138:139], off
	s_mov_b32 m0, s88
	v_lshl_add_u64 v[138:139], s[12:13], 0, v[140:141]
	global_load_lds_dwordx4 v[138:139], off
	s_waitcnt lgkmcnt(8)
	s_barrier
	s_waitcnt lgkmcnt(0)
	v_mfma_f32_16x16x32_bf16 v[126:129], v[152:155], v[130:133], v[126:129]
	v_mfma_f32_16x16x32_bf16 v[122:125], v[152:155], v[144:147], v[122:125]
	v_mfma_f32_16x16x32_bf16 v[118:121], v[160:163], v[130:133], v[118:121]
	v_mfma_f32_16x16x32_bf16 v[114:117], v[160:163], v[144:147], v[114:117]
	v_mfma_f32_16x16x32_bf16 v[110:113], v[190:193], v[130:133], v[110:113]
	v_mfma_f32_16x16x32_bf16 v[106:109], v[190:193], v[144:147], v[106:109]
	v_mfma_f32_16x16x32_bf16 v[102:105], v[198:201], v[130:133], v[102:105]
	v_mfma_f32_16x16x32_bf16 v[98:101], v[198:201], v[144:147], v[98:101]
	v_mfma_f32_16x16x32_bf16 v[126:129], v[156:159], v[134:137], v[126:129]
	v_mfma_f32_16x16x32_bf16 v[122:125], v[156:159], v[148:151], v[122:125]
	v_mfma_f32_16x16x32_bf16 v[118:121], v[164:167], v[134:137], v[118:121]
	v_mfma_f32_16x16x32_bf16 v[114:117], v[164:167], v[148:151], v[114:117]
	v_mfma_f32_16x16x32_bf16 v[110:113], v[194:197], v[134:137], v[110:113]
	v_mfma_f32_16x16x32_bf16 v[106:109], v[194:197], v[148:151], v[106:109]
	v_mfma_f32_16x16x32_bf16 v[102:105], v[202:205], v[134:137], v[102:105]
	v_mfma_f32_16x16x32_bf16 v[98:101], v[202:205], v[148:151], v[98:101]
	s_barrier
	s_add_i32 s15, 0, 0x1c000
	s_add_u32 s12, s55, vcc_hi
	v_add_u32_e32 v138, s15, v143
	s_addc_u32 s13, s16, 0
	s_add_i32 s14, s14, s1
	ds_read_b128 v[206:209], v138
	ds_read_b128 v[210:213], v138 offset:1024
	ds_read_b128 v[214:217], v138 offset:2048
	ds_read_b128 v[218:221], v138 offset:3072
	s_mov_b32 m0, s14
	v_lshl_add_u64 v[138:139], s[12:13], 0, v[0:1]
	global_load_lds_dwordx4 v[138:139], off
	v_lshl_add_u64 v[138:139], s[12:13], 0, v[140:141]
	s_add_i32 m0, s14, 0x2000
	s_nop 0
	global_load_lds_dwordx4 v[138:139], off
	s_barrier
;     __device__ __forceinline__ unsigned* BAR() const { return (unsigned*)(ws + OFF_BAR); }
; #define STAGE(bufoff, gbase, voff) do { _Pragma("unroll") for (int _i = 0; _i < 2; ++_i) \
;         __builtin_amdgcn_global_load_lds((const unsigned*)((const char*)(gbase) + voff[_i]), (LAS unsigned*)(lds + (bufoff) + ldsw + _i * 8192), 16, 0, 0); } while (0)
; #define LDA(dst, b, h) do { _Pragma("unroll") for (int m = 0; m < 4; ++m) _Pragma("unroll") for (int k = 0; k < 2; ++k) dst[m][k] = *(const LAS bf16x8*)(lds + SA(b, h) + aoff + m * 2048 + k * 1024); } while (0)
; #define MMA(ai, bj, At, Bx) do { __builtin_amdgcn_s_setprio(1); _Pragma("unroll") for (int m = 0; m < 4; ++m) _Pragma("unroll") for (int n = 0; n < 2; ++n) _Pragma("unroll") for (int k = 0; k < 2; ++k) \
;       acc[ai][bj][m][n] = __builtin_amdgcn_mfma_f32_16x16x32_bf16(At[m][k], Bx[n][k], acc[ai][bj][m][n], 0, 0, 0); \
;     __builtin_amdgcn_s_setprio(0); } while (0)
; #define WAIT_V(n) asm volatile("s_waitcnt vmcnt(" #n ")" ::: "memory")
; #define WAIT_L(n) asm volatile("s_waitcnt lgkmcnt(" #n ")" ::: "memory")
; #define BAR __builtin_amdgcn_s_barrier()
; #define SCHED __builtin_amdgcn_sched_barrier(0)
;     ...
;         BAR; WAIT_L(0); MMA(0, 1, At, B1); BAR;
;         LDA(At, 1, 1); STAGE(SA(1, 0), a3, voffA);
;         BAR; WAIT_L(0); MMA(1, 0, At, B0); BAR; SCHED;
;         STAGE(SB(1, 1), b3 + hstepB, voffB);
;         WAIT_V(6); BAR; MMA(1, 1, At, B1); BAR;
;     }
	s_waitcnt lgkmcnt(0)
	v_mfma_f32_16x16x32_bf16 v[94:97], v[152:155], v[206:209], v[94:97]
	v_mfma_f32_16x16x32_bf16 v[90:93], v[152:155], v[214:217], v[90:93]
	v_mfma_f32_16x16x32_bf16 v[86:89], v[160:163], v[206:209], v[86:89]
	v_mfma_f32_16x16x32_bf16 v[82:85], v[160:163], v[214:217], v[82:85]
	v_mfma_f32_16x16x32_bf16 v[78:81], v[190:193], v[206:209], v[78:81]
	v_mfma_f32_16x16x32_bf16 v[74:77], v[190:193], v[214:217], v[74:77]
	v_mfma_f32_16x16x32_bf16 v[70:73], v[198:201], v[206:209], v[70:73]
	v_mfma_f32_16x16x32_bf16 v[66:69], v[198:201], v[214:217], v[66:69]
	v_mfma_f32_16x16x32_bf16 v[94:97], v[156:159], v[210:213], v[94:97]
	v_mfma_f32_16x16x32_bf16 v[90:93], v[156:159], v[218:221], v[90:93]
	v_mfma_f32_16x16x32_bf16 v[86:89], v[164:167], v[210:213], v[86:89]
	v_mfma_f32_16x16x32_bf16 v[82:85], v[164:167], v[218:221], v[82:85]
	v_mfma_f32_16x16x32_bf16 v[78:81], v[194:197], v[210:213], v[78:81]
	v_mfma_f32_16x16x32_bf16 v[74:77], v[194:197], v[218:221], v[74:77]
	v_mfma_f32_16x16x32_bf16 v[70:73], v[202:205], v[210:213], v[70:73]
	v_mfma_f32_16x16x32_bf16 v[66:69], v[202:205], v[218:221], v[66:69]
	s_barrier
	s_mov_b32 m0, s31
	v_lshl_add_u64 v[138:139], s[8:9], 0, v[0:1]
	ds_read_b128 v[152:155], v142 offset:49152
	ds_read_b128 v[156:159], v142 offset:50176
	ds_read_b128 v[160:163], v142 offset:51200
	ds_read_b128 v[164:167], v142 offset:52224
	ds_read_b128 v[190:193], v142 offset:53248
	ds_read_b128 v[194:197], v142 offset:54272
	ds_read_b128 v[198:201], v142 offset:55296
	ds_read_b128 v[202:205], v142 offset:56320
	global_load_lds_dwordx4 v[138:139], off
	s_mov_b32 m0, s27
	v_lshl_add_u64 v[138:139], s[8:9], 0, v[140:141]
	global_load_lds_dwordx4 v[138:139], off
	s_barrier
	s_waitcnt lgkmcnt(0)
	v_mfma_f32_16x16x32_bf16 v[62:65], v[152:155], v[130:133], v[62:65]
	v_mfma_f32_16x16x32_bf16 v[58:61], v[152:155], v[144:147], v[58:61]
	v_mfma_f32_16x16x32_bf16 v[54:57], v[160:163], v[130:133], v[54:57]
	v_mfma_f32_16x16x32_bf16 v[50:53], v[160:163], v[144:147], v[50:53]
	v_mfma_f32_16x16x32_bf16 v[46:49], v[190:193], v[130:133], v[46:49]
	v_mfma_f32_16x16x32_bf16 v[42:45], v[190:193], v[144:147], v[42:45]
	v_mfma_f32_16x16x32_bf16 v[38:41], v[198:201], v[130:133], v[38:41]
	v_mfma_f32_16x16x32_bf16 v[34:37], v[198:201], v[144:147], v[34:37]
	v_mfma_f32_16x16x32_bf16 v[62:65], v[156:159], v[134:137], v[62:65]
	v_mfma_f32_16x16x32_bf16 v[58:61], v[156:159], v[148:151], v[58:61]
	v_mfma_f32_16x16x32_bf16 v[54:57], v[164:167], v[134:137], v[54:57]
	v_mfma_f32_16x16x32_bf16 v[50:53], v[164:167], v[148:151], v[50:53]
	v_mfma_f32_16x16x32_bf16 v[46:49], v[194:197], v[134:137], v[46:49]
	v_mfma_f32_16x16x32_bf16 v[42:45], v[194:197], v[148:151], v[42:45]
	v_mfma_f32_16x16x32_bf16 v[38:41], v[202:205], v[134:137], v[38:41]
	v_mfma_f32_16x16x32_bf16 v[34:37], v[202:205], v[148:151], v[34:37]
	s_barrier
	s_add_u32 s8, s12, 0x20000
	s_addc_u32 s9, s13, 0
	s_add_i32 s12, s15, s1
	s_mov_b32 m0, s12
	v_lshl_add_u64 v[130:131], s[8:9], 0, v[0:1]
	global_load_lds_dwordx4 v[130:131], off
	v_lshl_add_u64 v[130:131], s[8:9], 0, v[140:141]
	s_add_i32 m0, s12, 0x2000
	s_nop 0
	global_load_lds_dwordx4 v[130:131], off
	s_waitcnt vmcnt(6)
	s_barrier
	v_mfma_f32_16x16x32_bf16 v[30:33], v[152:155], v[206:209], v[30:33]
	v_mfma_f32_16x16x32_bf16 v[26:29], v[152:155], v[214:217], v[26:29]
	v_mfma_f32_16x16x32_bf16 v[22:25], v[160:163], v[206:209], v[22:25]
	v_mfma_f32_16x16x32_bf16 v[18:21], v[160:163], v[214:217], v[18:21]
	v_mfma_f32_16x16x32_bf16 v[14:17], v[190:193], v[206:209], v[14:17]
	v_mfma_f32_16x16x32_bf16 v[10:13], v[190:193], v[214:217], v[10:13]
	v_mfma_f32_16x16x32_bf16 v[6:9], v[198:201], v[206:209], v[6:9]
	v_mfma_f32_16x16x32_bf16 v[2:5], v[198:201], v[214:217], v[2:5]
	v_mfma_f32_16x16x32_bf16 v[30:33], v[156:159], v[210:213], v[30:33]
	v_mfma_f32_16x16x32_bf16 v[26:29], v[156:159], v[218:221], v[26:29]
	v_mfma_f32_16x16x32_bf16 v[22:25], v[164:167], v[210:213], v[22:25]
	v_mfma_f32_16x16x32_bf16 v[18:21], v[164:167], v[218:221], v[18:21]
	v_mfma_f32_16x16x32_bf16 v[14:17], v[194:197], v[210:213], v[14:17]
	v_mfma_f32_16x16x32_bf16 v[10:13], v[194:197], v[218:221], v[10:13]
	v_mfma_f32_16x16x32_bf16 v[6:9], v[202:205], v[210:213], v[6:9]
	v_mfma_f32_16x16x32_bf16 v[2:5], v[202:205], v[218:221], v[2:5]
	s_barrier
	s_add_i32 s43, s43, 0x40000
	s_cmp_gt_u32 s54, 19
	s_cbranch_scc1 .LBB0_576
	s_mov_b32 s12, s54
	s_mov_b64 s[8:9], s[10:11]
	s_branch .LBB0_572
;     __device__ __forceinline__ unsigned* BAR() const { return (unsigned*)(ws + OFF_BAR); }
; #define STAGE(bufoff, gbase, voff) do { _Pragma("unroll") for (int _i = 0; _i < 2; ++_i) \
;         __builtin_amdgcn_global_load_lds((const unsigned*)((const char*)(gbase) + voff[_i]), (LAS unsigned*)(lds + (bufoff) + ldsw + _i * 8192), 16, 0, 0); } while (0)
; #define LDA(dst, b, h) do { _Pragma("unroll") for (int m = 0; m < 4; ++m) _Pragma("unroll") for (int k = 0; k < 2; ++k) dst[m][k] = *(const LAS bf16x8*)(lds + SA(b, h) + aoff + m * 2048 + k * 1024); } while (0)
; #define LDB(dst, b, h) do { _Pragma("unroll") for (int n = 0; n < 2; ++n) _Pragma("unroll") for (int k = 0; k < 2; ++k) dst[n][k] = *(const LAS bf16x8*)(lds + SB(b, h) + boff + n * 2048 + k * 1024); } while (0)
; #define MMA(ai, bj, At, Bx) do { __builtin_amdgcn_s_setprio(1); _Pragma("unroll") for (int m = 0; m < 4; ++m) _Pragma("unroll") for (int n = 0; n < 2; ++n) _Pragma("unroll") for (int k = 0; k < 2; ++k) \
;       acc[ai][bj][m][n] = __builtin_amdgcn_mfma_f32_16x16x32_bf16(At[m][k], Bx[n][k], acc[ai][bj][m][n], 0, 0, 0); \
;     __builtin_amdgcn_s_setprio(0); } while (0)
; #define WAIT_V(n) asm volatile("s_waitcnt vmcnt(" #n ")" ::: "memory")
; #define WAIT_L(n) asm volatile("s_waitcnt lgkmcnt(" #n ")" ::: "memory")
; #define BAR __builtin_amdgcn_s_barrier()
;     ...
;     { LDB(B0, 0, 0); LDA(At, 0, 0); STAGE(SA(1, 1), pA(nt - 1) + hstepA, voffA);
;       BAR; WAIT_L(0); MMA(0, 0, At, B0); BAR;
;       LDB(B1, 0, 1); BAR; WAIT_L(0); MMA(0, 1, At, B1); BAR;
;       LDA(At, 0, 1); WAIT_V(4); BAR; WAIT_L(0); MMA(1, 0, At, B0); MMA(1, 1, At, B1); BAR; }
;     { LDB(B0, 1, 0); LDA(At, 1, 0); WAIT_V(2); BAR; WAIT_L(0); MMA(0, 0, At, B0); BAR;
.LBB0_576:
	v_add_u32_e32 v143, 0, v143
	s_add_u32 s4, s4, 0x220380
	v_add_u32_e32 v138, 0x10000, v143
	s_addc_u32 s5, s5, 0
	s_mov_b32 m0, vcc_lo
	ds_read_b128 v[130:133], v138
	ds_read_b128 v[134:137], v138 offset:1024
	ds_read_b128 v[144:147], v138 offset:2048
	ds_read_b128 v[148:151], v138 offset:3072
	ds_read_b128 v[152:155], v142
	ds_read_b128 v[156:159], v142 offset:1024
	ds_read_b128 v[160:163], v142 offset:2048
	ds_read_b128 v[164:167], v142 offset:3072
	ds_read_b128 v[190:193], v142 offset:4096
	ds_read_b128 v[194:197], v142 offset:5120
	ds_read_b128 v[198:201], v142 offset:6144
	ds_read_b128 v[202:205], v142 offset:7168
	v_lshl_add_u64 v[138:139], s[4:5], 0, v[0:1]
	global_load_lds_dwordx4 v[138:139], off
	s_mov_b32 m0, s24
	v_lshl_add_u64 v[138:139], s[4:5], 0, v[140:141]
	global_load_lds_dwordx4 v[138:139], off
	s_barrier
	s_waitcnt lgkmcnt(0)
	v_mfma_f32_16x16x32_bf16 v[126:129], v[152:155], v[130:133], v[126:129]
	v_mfma_f32_16x16x32_bf16 v[122:125], v[152:155], v[144:147], v[122:125]
	v_mfma_f32_16x16x32_bf16 v[118:121], v[160:163], v[130:133], v[118:121]
	v_mfma_f32_16x16x32_bf16 v[114:117], v[160:163], v[144:147], v[114:117]
	v_mfma_f32_16x16x32_bf16 v[98:101], v[198:201], v[144:147], v[98:101]
	v_mfma_f32_16x16x32_bf16 v[126:129], v[156:159], v[134:137], v[126:129]
	v_mfma_f32_16x16x32_bf16 v[122:125], v[156:159], v[148:151], v[122:125]
	v_mfma_f32_16x16x32_bf16 v[118:121], v[164:167], v[134:137], v[118:121]
	v_mfma_f32_16x16x32_bf16 v[114:117], v[164:167], v[148:151], v[114:117]
	v_mfma_f32_16x16x32_bf16 v[110:113], v[190:193], v[130:133], v[110:113]
	v_mfma_f32_16x16x32_bf16 v[106:109], v[190:193], v[144:147], v[106:109]
	v_mfma_f32_16x16x32_bf16 v[102:105], v[198:201], v[130:133], v[102:105]
	v_mfma_f32_16x16x32_bf16 v[98:101], v[202:205], v[148:151], v[98:101]
	v_mfma_f32_16x16x32_bf16 v[138:141], v[194:197], v[134:137], v[110:113]
	v_mfma_f32_16x16x32_bf16 v[206:209], v[194:197], v[148:151], v[106:109]
	v_mfma_f32_16x16x32_bf16 v[210:213], v[202:205], v[134:137], v[102:105]
	v_add_u32_e32 v0, 0x14000, v143
	s_barrier
	s_nop 0
	ds_read_b128 v[102:105], v0
	ds_read_b128 v[106:109], v0 offset:1024
	ds_read_b128 v[110:113], v0 offset:2048
	ds_read_b128 v[214:217], v0 offset:3072
	s_barrier
	s_waitcnt lgkmcnt(0)
	v_mfma_f32_16x16x32_bf16 v[94:97], v[152:155], v[102:105], v[94:97]
	v_mfma_f32_16x16x32_bf16 v[90:93], v[152:155], v[110:113], v[90:93]
	v_mfma_f32_16x16x32_bf16 v[86:89], v[160:163], v[102:105], v[86:89]
	v_mfma_f32_16x16x32_bf16 v[82:85], v[160:163], v[110:113], v[82:85]
	v_mfma_f32_16x16x32_bf16 v[66:69], v[198:201], v[110:113], v[66:69]
	v_mfma_f32_16x16x32_bf16 v[94:97], v[156:159], v[106:109], v[94:97]
	v_mfma_f32_16x16x32_bf16 v[90:93], v[156:159], v[214:217], v[90:93]
	v_mfma_f32_16x16x32_bf16 v[86:89], v[164:167], v[106:109], v[86:89]
	v_mfma_f32_16x16x32_bf16 v[82:85], v[164:167], v[214:217], v[82:85]
	v_mfma_f32_16x16x32_bf16 v[78:81], v[190:193], v[102:105], v[78:81]
	v_mfma_f32_16x16x32_bf16 v[74:77], v[190:193], v[110:113], v[74:77]
	v_mfma_f32_16x16x32_bf16 v[70:73], v[198:201], v[102:105], v[70:73]
	v_mfma_f32_16x16x32_bf16 v[66:69], v[202:205], v[214:217], v[66:69]
	v_mfma_f32_16x16x32_bf16 v[152:155], v[194:197], v[106:109], v[78:81]
	v_mfma_f32_16x16x32_bf16 v[156:159], v[194:197], v[214:217], v[74:77]
	v_mfma_f32_16x16x32_bf16 v[160:163], v[202:205], v[106:109], v[70:73]
	s_barrier
	s_nop 1
	ds_read_b128 v[70:73], v142 offset:16384
	ds_read_b128 v[74:77], v142 offset:17408
	ds_read_b128 v[78:81], v142 offset:18432
	ds_read_b128 v[164:167], v142 offset:19456
	ds_read_b128 v[190:193], v142 offset:20480
	ds_read_b128 v[194:197], v142 offset:21504
	ds_read_b128 v[198:201], v142 offset:22528
	ds_read_b128 v[202:205], v142 offset:23552
	s_waitcnt vmcnt(4)
	s_barrier
	s_waitcnt lgkmcnt(0)
	v_mfma_f32_16x16x32_bf16 v[62:65], v[70:73], v[130:133], v[62:65]
	v_mfma_f32_16x16x32_bf16 v[58:61], v[70:73], v[144:147], v[58:61]
	v_mfma_f32_16x16x32_bf16 v[54:57], v[78:81], v[130:133], v[54:57]
	v_mfma_f32_16x16x32_bf16 v[50:53], v[78:81], v[144:147], v[50:53]
	v_mfma_f32_16x16x32_bf16 v[34:37], v[198:201], v[144:147], v[34:37]
	v_mfma_f32_16x16x32_bf16 v[62:65], v[74:77], v[134:137], v[62:65]
	v_mfma_f32_16x16x32_bf16 v[58:61], v[74:77], v[148:151], v[58:61]
	v_mfma_f32_16x16x32_bf16 v[54:57], v[164:167], v[134:137], v[54:57]
	v_mfma_f32_16x16x32_bf16 v[50:53], v[164:167], v[148:151], v[50:53]
	v_mfma_f32_16x16x32_bf16 v[46:49], v[190:193], v[130:133], v[46:49]
	v_mfma_f32_16x16x32_bf16 v[42:45], v[190:193], v[144:147], v[42:45]
	v_mfma_f32_16x16x32_bf16 v[38:41], v[198:201], v[130:133], v[38:41]
	v_mfma_f32_16x16x32_bf16 v[34:37], v[202:205], v[148:151], v[34:37]
	v_mfma_f32_16x16x32_bf16 v[218:221], v[194:197], v[134:137], v[46:49]
	v_mfma_f32_16x16x32_bf16 v[222:225], v[194:197], v[148:151], v[42:45]
	v_mfma_f32_16x16x32_bf16 v[130:133], v[202:205], v[134:137], v[38:41]
	v_mfma_f32_16x16x32_bf16 v[30:33], v[70:73], v[102:105], v[30:33]
	v_mfma_f32_16x16x32_bf16 v[26:29], v[70:73], v[110:113], v[26:29]
	v_mfma_f32_16x16x32_bf16 v[22:25], v[78:81], v[102:105], v[22:25]
	v_mfma_f32_16x16x32_bf16 v[18:21], v[78:81], v[110:113], v[18:21]
	v_mfma_f32_16x16x32_bf16 v[2:5], v[198:201], v[110:113], v[2:5]
	v_mfma_f32_16x16x32_bf16 v[30:33], v[74:77], v[106:109], v[30:33]
	v_mfma_f32_16x16x32_bf16 v[26:29], v[74:77], v[214:217], v[26:29]
	v_mfma_f32_16x16x32_bf16 v[22:25], v[164:167], v[106:109], v[22:25]
	v_mfma_f32_16x16x32_bf16 v[18:21], v[164:167], v[214:217], v[18:21]
	v_mfma_f32_16x16x32_bf16 v[14:17], v[190:193], v[102:105], v[14:17]
	v_mfma_f32_16x16x32_bf16 v[10:13], v[190:193], v[110:113], v[10:13]
	v_mfma_f32_16x16x32_bf16 v[6:9], v[198:201], v[102:105], v[6:9]
	v_mfma_f32_16x16x32_bf16 v[2:5], v[202:205], v[214:217], v[2:5]
	v_mfma_f32_16x16x32_bf16 v[134:137], v[194:197], v[106:109], v[14:17]
	v_mfma_f32_16x16x32_bf16 v[144:147], v[194:197], v[214:217], v[10:13]
	v_mfma_f32_16x16x32_bf16 v[148:151], v[202:205], v[106:109], v[6:9]
	v_add_u32_e32 v0, 0x18000, v143
	s_barrier
;     __device__ __forceinline__ unsigned* BAR() const { return (unsigned*)(ws + OFF_BAR); }
; #define LDA(dst, b, h) do { _Pragma("unroll") for (int m = 0; m < 4; ++m) _Pragma("unroll") for (int k = 0; k < 2; ++k) dst[m][k] = *(const LAS bf16x8*)(lds + SA(b, h) + aoff + m * 2048 + k * 1024); } while (0)
; #define LDB(dst, b, h) do { _Pragma("unroll") for (int n = 0; n < 2; ++n) _Pragma("unroll") for (int k = 0; k < 2; ++k) dst[n][k] = *(const LAS bf16x8*)(lds + SB(b, h) + boff + n * 2048 + k * 1024); } while (0)
; #define MMA(ai, bj, At, Bx) do { __builtin_amdgcn_s_setprio(1); _Pragma("unroll") for (int m = 0; m < 4; ++m) _Pragma("unroll") for (int n = 0; n < 2; ++n) _Pragma("unroll") for (int k = 0; k < 2; ++k) \
;       acc[ai][bj][m][n] = __builtin_amdgcn_mfma_f32_16x16x32_bf16(At[m][k], Bx[n][k], acc[ai][bj][m][n], 0, 0, 0); \
;     __builtin_amdgcn_s_setprio(0); } while (0)
; #define WAIT_V(n) asm volatile("s_waitcnt vmcnt(" #n ")" ::: "memory")
; #define WAIT_L(n) asm volatile("s_waitcnt lgkmcnt(" #n ")" ::: "memory")
; #define BAR __builtin_amdgcn_s_barrier()
;     ...
;     { LDB(B0, 1, 0); LDA(At, 1, 0); WAIT_V(2); BAR; WAIT_L(0); MMA(0, 0, At, B0); BAR;
;       LDB(B1, 1, 1); WAIT_V(0); BAR; WAIT_L(0); MMA(0, 1, At, B1); BAR;
;       LDA(At, 1, 1); BAR; WAIT_L(0); MMA(1, 0, At, B0); MMA(1, 1, At, B1); BAR; }
;     if (wr == 0) BAR;
	s_nop 0
	ds_read_b128 v[6:9], v0
	ds_read_b128 v[10:13], v0 offset:1024
	ds_read_b128 v[14:17], v0 offset:2048
	ds_read_b128 v[164:167], v0 offset:3072
	ds_read_b128 v[38:41], v142 offset:32768
	ds_read_b128 v[42:45], v142 offset:33792
	ds_read_b128 v[46:49], v142 offset:34816
	ds_read_b128 v[70:73], v142 offset:35840
	ds_read_b128 v[190:193], v142 offset:36864
	ds_read_b128 v[194:197], v142 offset:37888
	ds_read_b128 v[198:201], v142 offset:38912
	ds_read_b128 v[202:205], v142 offset:39936
	s_waitcnt vmcnt(2)
	s_barrier
	s_waitcnt lgkmcnt(0)
	v_mfma_f32_16x16x32_bf16 v[74:77], v[38:41], v[6:9], v[126:129]
	v_mfma_f32_16x16x32_bf16 v[126:129], v[42:45], v[10:13], v[74:77]
	v_mfma_f32_16x16x32_bf16 v[74:77], v[38:41], v[14:17], v[122:125]
	v_mfma_f32_16x16x32_bf16 v[110:113], v[42:45], v[164:167], v[74:77]
	v_mfma_f32_16x16x32_bf16 v[74:77], v[46:49], v[6:9], v[118:121]
	v_mfma_f32_16x16x32_bf16 v[122:125], v[70:73], v[10:13], v[74:77]
	v_mfma_f32_16x16x32_bf16 v[74:77], v[46:49], v[14:17], v[114:117]
	v_mfma_f32_16x16x32_bf16 v[106:109], v[70:73], v[164:167], v[74:77]
	v_mfma_f32_16x16x32_bf16 v[74:77], v[190:193], v[6:9], v[138:141]
	v_mfma_f32_16x16x32_bf16 v[118:121], v[194:197], v[10:13], v[74:77]
	v_mfma_f32_16x16x32_bf16 v[74:77], v[190:193], v[14:17], v[206:209]
	v_mfma_f32_16x16x32_bf16 v[102:105], v[194:197], v[164:167], v[74:77]
	v_mfma_f32_16x16x32_bf16 v[74:77], v[198:201], v[6:9], v[210:213]
	v_mfma_f32_16x16x32_bf16 v[114:117], v[202:205], v[10:13], v[74:77]
	v_mfma_f32_16x16x32_bf16 v[74:77], v[198:201], v[14:17], v[98:101]
	v_mfma_f32_16x16x32_bf16 v[98:101], v[202:205], v[164:167], v[74:77]
	v_add_u32_e32 v0, 0x1c000, v143
	s_barrier
	ds_read_b128 v[138:141], v0
	ds_read_b128 v[206:209], v0 offset:1024
	ds_read_b128 v[210:213], v0 offset:2048
	ds_read_b128 v[214:217], v0 offset:3072
	s_waitcnt vmcnt(0)
	s_barrier
	s_waitcnt lgkmcnt(0)
	v_mfma_f32_16x16x32_bf16 v[74:77], v[38:41], v[138:141], v[94:97]
	v_mfma_f32_16x16x32_bf16 v[38:41], v[38:41], v[210:213], v[90:93]
	v_mfma_f32_16x16x32_bf16 v[78:81], v[42:45], v[214:217], v[38:41]
	v_mfma_f32_16x16x32_bf16 v[38:41], v[46:49], v[138:141], v[86:89]
	v_mfma_f32_16x16x32_bf16 v[90:93], v[70:73], v[206:209], v[38:41]
	v_mfma_f32_16x16x32_bf16 v[38:41], v[46:49], v[210:213], v[82:85]
	v_mfma_f32_16x16x32_bf16 v[94:97], v[42:45], v[206:209], v[74:77]
	v_mfma_f32_16x16x32_bf16 v[74:77], v[70:73], v[214:217], v[38:41]
	v_mfma_f32_16x16x32_bf16 v[38:41], v[190:193], v[138:141], v[152:155]
	v_mfma_f32_16x16x32_bf16 v[86:89], v[194:197], v[206:209], v[38:41]
	v_mfma_f32_16x16x32_bf16 v[38:41], v[190:193], v[210:213], v[156:159]
	v_mfma_f32_16x16x32_bf16 v[70:73], v[194:197], v[214:217], v[38:41]
	v_mfma_f32_16x16x32_bf16 v[38:41], v[198:201], v[138:141], v[160:163]
	v_mfma_f32_16x16x32_bf16 v[82:85], v[202:205], v[206:209], v[38:41]
	v_mfma_f32_16x16x32_bf16 v[38:41], v[198:201], v[210:213], v[66:69]
	v_mfma_f32_16x16x32_bf16 v[66:69], v[202:205], v[214:217], v[38:41]
	s_barrier
	ds_read_b128 v[152:155], v142 offset:49152
	ds_read_b128 v[156:159], v142 offset:50176
	ds_read_b128 v[160:163], v142 offset:51200
	ds_read_b128 v[190:193], v142 offset:52224
	ds_read_b128 v[194:197], v142 offset:53248
	ds_read_b128 v[198:201], v142 offset:54272
	ds_read_b128 v[202:205], v142 offset:55296
	ds_read_b128 v[226:229], v142 offset:56320
	s_barrier
	s_waitcnt lgkmcnt(0)
	v_mfma_f32_16x16x32_bf16 v[38:41], v[152:155], v[6:9], v[62:65]
	v_mfma_f32_16x16x32_bf16 v[62:65], v[156:159], v[10:13], v[38:41]
	v_mfma_f32_16x16x32_bf16 v[38:41], v[152:155], v[14:17], v[58:61]
	v_mfma_f32_16x16x32_bf16 v[46:49], v[156:159], v[164:167], v[38:41]
	v_mfma_f32_16x16x32_bf16 v[38:41], v[160:163], v[6:9], v[54:57]
	v_mfma_f32_16x16x32_bf16 v[58:61], v[190:193], v[10:13], v[38:41]
	v_mfma_f32_16x16x32_bf16 v[38:41], v[160:163], v[14:17], v[50:53]
	v_mfma_f32_16x16x32_bf16 v[42:45], v[190:193], v[164:167], v[38:41]
	v_mfma_f32_16x16x32_bf16 v[38:41], v[194:197], v[6:9], v[218:221]
	v_mfma_f32_16x16x32_bf16 v[6:9], v[202:205], v[6:9], v[130:133]
	v_mfma_f32_16x16x32_bf16 v[54:57], v[198:201], v[10:13], v[38:41]
	v_mfma_f32_16x16x32_bf16 v[38:41], v[194:197], v[14:17], v[222:225]
	v_mfma_f32_16x16x32_bf16 v[50:53], v[226:229], v[10:13], v[6:9]
	v_mfma_f32_16x16x32_bf16 v[6:9], v[202:205], v[14:17], v[34:37]
	v_mfma_f32_16x16x32_bf16 v[38:41], v[198:201], v[164:167], v[38:41]
	v_mfma_f32_16x16x32_bf16 v[34:37], v[226:229], v[164:167], v[6:9]
	v_mfma_f32_16x16x32_bf16 v[6:9], v[152:155], v[138:141], v[30:33]
	v_mfma_f32_16x16x32_bf16 v[30:33], v[156:159], v[206:209], v[6:9]
	v_mfma_f32_16x16x32_bf16 v[6:9], v[152:155], v[210:213], v[26:29]
	v_mfma_f32_16x16x32_bf16 v[14:17], v[156:159], v[214:217], v[6:9]
	v_mfma_f32_16x16x32_bf16 v[6:9], v[160:163], v[138:141], v[22:25]
	v_mfma_f32_16x16x32_bf16 v[26:29], v[190:193], v[206:209], v[6:9]
	v_mfma_f32_16x16x32_bf16 v[6:9], v[160:163], v[210:213], v[18:21]
	v_mfma_f32_16x16x32_bf16 v[10:13], v[190:193], v[214:217], v[6:9]
	v_mfma_f32_16x16x32_bf16 v[6:9], v[194:197], v[138:141], v[134:137]
	v_mfma_f32_16x16x32_bf16 v[22:25], v[198:201], v[206:209], v[6:9]
	v_mfma_f32_16x16x32_bf16 v[6:9], v[194:197], v[210:213], v[144:147]
	v_mfma_f32_16x16x32_bf16 v[18:21], v[202:205], v[138:141], v[148:151]
	v_mfma_f32_16x16x32_bf16 v[2:5], v[202:205], v[210:213], v[2:5]
	v_mfma_f32_16x16x32_bf16 v[6:9], v[198:201], v[214:217], v[6:9]
	v_mfma_f32_16x16x32_bf16 v[18:21], v[226:229], v[206:209], v[18:21]
	v_mfma_f32_16x16x32_bf16 v[2:5], v[226:229], v[214:217], v[2:5]
	s_cmpk_lt_u32 s74, 0x100
	s_barrier
	s_cbranch_scc0 .LBB0_578
	s_barrier

;     __device__ __forceinline__ unsigned* BAR() const { return (unsigned*)(ws + OFF_BAR); }
; #define STAGE(bufoff, gbase, voff) do { _Pragma("unroll") for (int _i = 0; _i < 2; ++_i) \
;         __builtin_amdgcn_global_load_lds((const unsigned*)((const char*)(gbase) + voff[_i]), (LAS unsigned*)(lds + (bufoff) + ldsw + _i * 8192), 16, 0, 0); } while (0)
; #define LDA(dst, b, h) do { _Pragma("unroll") for (int m = 0; m < 4; ++m) _Pragma("unroll") for (int k = 0; k < 2; ++k) dst[m][k] = *(const LAS bf16x8*)(lds + SA(b, h) + aoff + m * 2048 + k * 1024); } while (0)
; #define LDB(dst, b, h) do { _Pragma("unroll") for (int n = 0; n < 2; ++n) _Pragma("unroll") for (int k = 0; k < 2; ++k) dst[n][k] = *(const LAS bf16x8*)(lds + SB(b, h) + boff + n * 2048 + k * 1024); } while (0)
; #define MMA(ai, bj, At, Bx) do { __builtin_amdgcn_s_setprio(1); _Pragma("unroll") for (int m = 0; m < 4; ++m) _Pragma("unroll") for (int n = 0; n < 2; ++n) _Pragma("unroll") for (int k = 0; k < 2; ++k) \
;       acc[ai][bj][m][n] = __builtin_amdgcn_mfma_f32_16x16x32_bf16(At[m][k], Bx[n][k], acc[ai][bj][m][n], 0, 0, 0); \
;     __builtin_amdgcn_s_setprio(0); } while (0)
; #define WAIT_V(n) asm volatile("s_waitcnt vmcnt(" #n ")" ::: "memory")
; #define WAIT_L(n) asm volatile("s_waitcnt lgkmcnt(" #n ")" ::: "memory")
; #define BAR __builtin_amdgcn_s_barrier()
; #define SCHED __builtin_amdgcn_sched_barrier(0)
;     ...
;         const char* a1 = pA(t + 1); const char* a2 = pA(t + 2); const char* a3 = pA(t + 3);
;         const char* b2 = pB(t + 2); const char* b3 = pB(t + 3);
;         LDB(B0, 0, 0); SCHED; LDA(At, 0, 0); STAGE(SA(1, 1), a1 + hstepA, voffA);
;         WAIT_L(8); BAR; WAIT_L(0); MMA(0, 0, At, B0); BAR; SCHED;
;         LDB(B1, 0, 1); STAGE(SB(0, 0), b2, voffB);
;         BAR; WAIT_L(0); MMA(0, 1, At, B1); BAR;
;         LDA(At, 0, 1); STAGE(SA(0, 0), a2, voffA);
;         BAR; WAIT_L(0); MMA(1, 0, At, B0); BAR; SCHED;
;         STAGE(SB(0, 1), b2 + hstepB, voffB);
;         WAIT_V(6); BAR; MMA(1, 1, At, B1); BAR;
.LBB0_617:
	s_add_i32 s16, 0, 0x10000
	v_add_u32_e32 v138, s16, v143
	ds_read_b128 v[144:147], v138
	ds_read_b128 v[148:151], v138 offset:1024
	ds_read_b128 v[152:155], v138 offset:2048
	ds_read_b128 v[156:159], v138 offset:3072
	v_lshl_add_u64 v[138:139], s[8:9], 0, v[136:137]
	s_add_i32 s88, s42, 0xc000
	v_lshl_add_u64 v[214:215], v[138:139], 0, s[84:85]
	s_mov_b32 m0, s88
	v_lshl_add_u64 v[230:231], s[8:9], 0, v[140:141]
	s_add_i32 s11, s42, 0xe000
	ds_read_b128 v[160:163], v142
	ds_read_b128 v[164:167], v142 offset:1024
	ds_read_b128 v[190:193], v142 offset:2048
	ds_read_b128 v[194:197], v142 offset:3072
	ds_read_b128 v[198:201], v142 offset:4096
	ds_read_b128 v[202:205], v142 offset:5120
	ds_read_b128 v[206:209], v142 offset:6144
	ds_read_b128 v[210:213], v142 offset:7168
	global_load_lds_dwordx4 v[214:215], off
	s_mov_b32 m0, s11
	v_lshl_add_u64 v[214:215], v[230:231], 0, s[84:85]
	global_load_lds_dwordx4 v[214:215], off
	s_waitcnt lgkmcnt(8)
	s_barrier
	s_waitcnt lgkmcnt(0)
	v_mfma_f32_16x16x32_bf16 v[126:129], v[160:163], v[144:147], v[126:129]
	v_mfma_f32_16x16x32_bf16 v[122:125], v[160:163], v[152:155], v[122:125]
	v_mfma_f32_16x16x32_bf16 v[118:121], v[190:193], v[144:147], v[118:121]
	v_mfma_f32_16x16x32_bf16 v[114:117], v[190:193], v[152:155], v[114:117]
	v_mfma_f32_16x16x32_bf16 v[110:113], v[198:201], v[144:147], v[110:113]
	v_mfma_f32_16x16x32_bf16 v[106:109], v[198:201], v[152:155], v[106:109]
	v_mfma_f32_16x16x32_bf16 v[102:105], v[206:209], v[144:147], v[102:105]
	v_mfma_f32_16x16x32_bf16 v[98:101], v[206:209], v[152:155], v[98:101]
	v_mfma_f32_16x16x32_bf16 v[126:129], v[164:167], v[148:151], v[126:129]
	v_mfma_f32_16x16x32_bf16 v[122:125], v[164:167], v[156:159], v[122:125]
	v_mfma_f32_16x16x32_bf16 v[118:121], v[194:197], v[148:151], v[118:121]
	v_mfma_f32_16x16x32_bf16 v[114:117], v[194:197], v[156:159], v[114:117]
	v_mfma_f32_16x16x32_bf16 v[110:113], v[202:205], v[148:151], v[110:113]
	v_mfma_f32_16x16x32_bf16 v[106:109], v[202:205], v[156:159], v[106:109]
	v_mfma_f32_16x16x32_bf16 v[102:105], v[210:213], v[148:151], v[102:105]
	v_mfma_f32_16x16x32_bf16 v[98:101], v[210:213], v[156:159], v[98:101]
	s_barrier
	s_add_i32 s17, 0, 0x14000
	v_lshl_add_u64 v[232:233], s[8:9], 0, v[132:133]
	s_add_i32 s16, s16, s15
	v_add_u32_e32 v226, s17, v143
	v_lshl_add_u64 v[234:235], v[232:233], 0, s[52:53]
	s_mov_b32 m0, s16
	ds_read_b128 v[214:217], v226
	ds_read_b128 v[218:221], v226 offset:1024
	ds_read_b128 v[222:225], v226 offset:2048
	ds_read_b128 v[226:229], v226 offset:3072
	global_load_lds_dwordx4 v[234:235], off
	v_lshl_add_u64 v[234:235], s[8:9], 0, v[134:135]
	v_lshl_add_u64 v[236:237], v[234:235], 0, s[52:53]
	s_add_i32 m0, s16, 0x2000
	s_nop 0
	global_load_lds_dwordx4 v[236:237], off
	s_barrier
	s_waitcnt lgkmcnt(0)
	v_mfma_f32_16x16x32_bf16 v[94:97], v[160:163], v[214:217], v[94:97]
	v_mfma_f32_16x16x32_bf16 v[90:93], v[160:163], v[222:225], v[90:93]
	v_mfma_f32_16x16x32_bf16 v[86:89], v[190:193], v[214:217], v[86:89]
	v_mfma_f32_16x16x32_bf16 v[82:85], v[190:193], v[222:225], v[82:85]
	v_mfma_f32_16x16x32_bf16 v[78:81], v[198:201], v[214:217], v[78:81]
	v_mfma_f32_16x16x32_bf16 v[74:77], v[198:201], v[222:225], v[74:77]
	v_mfma_f32_16x16x32_bf16 v[70:73], v[206:209], v[214:217], v[70:73]
	v_mfma_f32_16x16x32_bf16 v[66:69], v[206:209], v[222:225], v[66:69]
	v_mfma_f32_16x16x32_bf16 v[94:97], v[164:167], v[218:221], v[94:97]
	v_mfma_f32_16x16x32_bf16 v[90:93], v[164:167], v[226:229], v[90:93]
	v_mfma_f32_16x16x32_bf16 v[86:89], v[194:197], v[218:221], v[86:89]
	v_mfma_f32_16x16x32_bf16 v[82:85], v[194:197], v[226:229], v[82:85]
	v_mfma_f32_16x16x32_bf16 v[78:81], v[202:205], v[218:221], v[78:81]
	v_mfma_f32_16x16x32_bf16 v[74:77], v[202:205], v[226:229], v[74:77]
	v_mfma_f32_16x16x32_bf16 v[70:73], v[210:213], v[218:221], v[70:73]
	v_mfma_f32_16x16x32_bf16 v[66:69], v[210:213], v[226:229], v[66:69]
	s_barrier
	s_mov_b32 m0, s42
	v_lshl_add_u64 v[236:237], v[138:139], 0, s[58:59]
	ds_read_b128 v[160:163], v142 offset:16384
	ds_read_b128 v[164:167], v142 offset:17408
	ds_read_b128 v[190:193], v142 offset:18432
	ds_read_b128 v[194:197], v142 offset:19456
	ds_read_b128 v[198:201], v142 offset:20480
	ds_read_b128 v[202:205], v142 offset:21504
	ds_read_b128 v[206:209], v142 offset:22528
	ds_read_b128 v[210:213], v142 offset:23552
	global_load_lds_dwordx4 v[236:237], off
	s_mov_b32 m0, s43
	v_lshl_add_u64 v[236:237], v[230:231], 0, s[58:59]
	global_load_lds_dwordx4 v[236:237], off
	s_barrier
	s_waitcnt lgkmcnt(0)
	v_mfma_f32_16x16x32_bf16 v[62:65], v[160:163], v[144:147], v[62:65]
	v_mfma_f32_16x16x32_bf16 v[58:61], v[160:163], v[152:155], v[58:61]
	v_mfma_f32_16x16x32_bf16 v[54:57], v[190:193], v[144:147], v[54:57]
	v_mfma_f32_16x16x32_bf16 v[50:53], v[190:193], v[152:155], v[50:53]
	v_mfma_f32_16x16x32_bf16 v[46:49], v[198:201], v[144:147], v[46:49]
	v_mfma_f32_16x16x32_bf16 v[42:45], v[198:201], v[152:155], v[42:45]
	v_mfma_f32_16x16x32_bf16 v[38:41], v[206:209], v[144:147], v[38:41]
	v_mfma_f32_16x16x32_bf16 v[34:37], v[206:209], v[152:155], v[34:37]
	v_mfma_f32_16x16x32_bf16 v[62:65], v[164:167], v[148:151], v[62:65]
	v_mfma_f32_16x16x32_bf16 v[58:61], v[164:167], v[156:159], v[58:61]
	v_mfma_f32_16x16x32_bf16 v[54:57], v[194:197], v[148:151], v[54:57]
	v_mfma_f32_16x16x32_bf16 v[50:53], v[194:197], v[156:159], v[50:53]
	v_mfma_f32_16x16x32_bf16 v[46:49], v[202:205], v[148:151], v[46:49]
	v_mfma_f32_16x16x32_bf16 v[42:45], v[202:205], v[156:159], v[42:45]
	v_mfma_f32_16x16x32_bf16 v[38:41], v[210:213], v[148:151], v[38:41]
	v_mfma_f32_16x16x32_bf16 v[34:37], v[210:213], v[156:159], v[34:37]
	s_barrier
;     __device__ __forceinline__ unsigned* BAR() const { return (unsigned*)(ws + OFF_BAR); }
; #define STAGE(bufoff, gbase, voff) do { _Pragma("unroll") for (int _i = 0; _i < 2; ++_i) \
;         __builtin_amdgcn_global_load_lds((const unsigned*)((const char*)(gbase) + voff[_i]), (LAS unsigned*)(lds + (bufoff) + ldsw + _i * 8192), 16, 0, 0); } while (0)
; #define LDA(dst, b, h) do { _Pragma("unroll") for (int m = 0; m < 4; ++m) _Pragma("unroll") for (int k = 0; k < 2; ++k) dst[m][k] = *(const LAS bf16x8*)(lds + SA(b, h) + aoff + m * 2048 + k * 1024); } while (0)
; #define LDB(dst, b, h) do { _Pragma("unroll") for (int n = 0; n < 2; ++n) _Pragma("unroll") for (int k = 0; k < 2; ++k) dst[n][k] = *(const LAS bf16x8*)(lds + SB(b, h) + boff + n * 2048 + k * 1024); } while (0)
; #define MMA(ai, bj, At, Bx) do { __builtin_amdgcn_s_setprio(1); _Pragma("unroll") for (int m = 0; m < 4; ++m) _Pragma("unroll") for (int n = 0; n < 2; ++n) _Pragma("unroll") for (int k = 0; k < 2; ++k) \
;       acc[ai][bj][m][n] = __builtin_amdgcn_mfma_f32_16x16x32_bf16(At[m][k], Bx[n][k], acc[ai][bj][m][n], 0, 0, 0); \
;     __builtin_amdgcn_s_setprio(0); } while (0)
;     ...
;     for (int t = 0; t < nt - 2; t += 2) {
;         if (KSEG && t > 0 && (t % (KSEG ? KSEG : 1)) == 0) hook(t / (KSEG ? KSEG : 1), acc);
;         const char* a1 = pA(t + 1); const char* a2 = pA(t + 2); const char* a3 = pA(t + 3);
;         const char* b2 = pB(t + 2); const char* b3 = pB(t + 3);
;         LDB(B0, 0, 0); SCHED; LDA(At, 0, 0); STAGE(SA(1, 1), a1 + hstepA, voffA);
;         WAIT_L(8); BAR; WAIT_L(0); MMA(0, 0, At, B0); BAR; SCHED;
;         LDB(B1, 0, 1); STAGE(SB(0, 0), b2, voffB);
;         BAR; WAIT_L(0); MMA(0, 1, At, B1); BAR;
;         LDA(At, 0, 1); STAGE(SA(0, 0), a2, voffA);
;         BAR; WAIT_L(0); MMA(1, 0, At, B0); BAR; SCHED;
;         STAGE(SB(0, 1), b2 + hstepB, voffB);
;         WAIT_V(6); BAR; MMA(1, 1, At, B1); BAR;
;         LDB(B0, 1, 0); SCHED; LDA(At, 1, 0); STAGE(SA(0, 1), a2 + hstepA, voffA);
;         WAIT_L(8); BAR; WAIT_L(0); MMA(0, 0, At, B0); BAR; SCHED;
;         LDB(B1, 1, 1); STAGE(SB(1, 0), b3, voffB);
;         BAR; WAIT_L(0); MMA(0, 1, At, B1); BAR;
;         LDA(At, 1, 1); STAGE(SA(1, 0), a3, voffA);
;         BAR; WAIT_L(0); MMA(1, 0, At, B0); BAR; SCHED;
;         STAGE(SB(1, 1), b3 + hstepB, voffB);
;         WAIT_V(6); BAR; MMA(1, 1, At, B1); BAR;
	s_add_i32 s16, s17, s15
	s_mov_b32 m0, s16
	v_lshl_add_u64 v[144:145], v[232:233], 0, s[82:83]
	global_load_lds_dwordx4 v[144:145], off
	v_lshl_add_u64 v[144:145], v[234:235], 0, s[82:83]
	s_add_i32 m0, s16, 0x2000
	s_nop 0
	global_load_lds_dwordx4 v[144:145], off
	s_waitcnt vmcnt(6)
	s_barrier
	v_mfma_f32_16x16x32_bf16 v[30:33], v[160:163], v[214:217], v[30:33]
	v_mfma_f32_16x16x32_bf16 v[26:29], v[160:163], v[222:225], v[26:29]
	v_mfma_f32_16x16x32_bf16 v[22:25], v[190:193], v[214:217], v[22:25]
	v_mfma_f32_16x16x32_bf16 v[18:21], v[190:193], v[222:225], v[18:21]
	v_mfma_f32_16x16x32_bf16 v[14:17], v[198:201], v[214:217], v[14:17]
	v_mfma_f32_16x16x32_bf16 v[10:13], v[198:201], v[222:225], v[10:13]
	v_mfma_f32_16x16x32_bf16 v[6:9], v[206:209], v[214:217], v[6:9]
	v_mfma_f32_16x16x32_bf16 v[2:5], v[206:209], v[222:225], v[2:5]
	v_mfma_f32_16x16x32_bf16 v[30:33], v[164:167], v[218:221], v[30:33]
	v_mfma_f32_16x16x32_bf16 v[26:29], v[164:167], v[226:229], v[26:29]
	v_mfma_f32_16x16x32_bf16 v[22:25], v[194:197], v[218:221], v[22:25]
	v_mfma_f32_16x16x32_bf16 v[18:21], v[194:197], v[226:229], v[18:21]
	v_mfma_f32_16x16x32_bf16 v[14:17], v[202:205], v[218:221], v[14:17]
	v_mfma_f32_16x16x32_bf16 v[10:13], v[202:205], v[226:229], v[10:13]
	v_mfma_f32_16x16x32_bf16 v[6:9], v[210:213], v[218:221], v[6:9]
	v_mfma_f32_16x16x32_bf16 v[2:5], v[210:213], v[226:229], v[2:5]
	s_barrier
	s_add_i32 s16, 0, 0x18000
	v_add_u32_e32 v156, s16, v143
	ds_read_b128 v[144:147], v156
	ds_read_b128 v[148:151], v156 offset:1024
	ds_read_b128 v[152:155], v156 offset:2048
	ds_read_b128 v[156:159], v156 offset:3072
	s_mov_b32 m0, s54
	v_lshl_add_u64 v[214:215], v[138:139], 0, s[96:97]
	ds_read_b128 v[160:163], v142 offset:32768
	ds_read_b128 v[164:167], v142 offset:33792
	ds_read_b128 v[190:193], v142 offset:34816
	ds_read_b128 v[194:197], v142 offset:35840
	ds_read_b128 v[198:201], v142 offset:36864
	ds_read_b128 v[202:205], v142 offset:37888
	ds_read_b128 v[206:209], v142 offset:38912
	ds_read_b128 v[210:213], v142 offset:39936
	global_load_lds_dwordx4 v[214:215], off
	s_mov_b32 m0, s55
	v_lshl_add_u64 v[214:215], v[230:231], 0, s[96:97]
	global_load_lds_dwordx4 v[214:215], off
	s_waitcnt lgkmcnt(8)
	s_barrier
	s_waitcnt lgkmcnt(0)
	v_mfma_f32_16x16x32_bf16 v[126:129], v[160:163], v[144:147], v[126:129]
	v_mfma_f32_16x16x32_bf16 v[122:125], v[160:163], v[152:155], v[122:125]
	v_mfma_f32_16x16x32_bf16 v[118:121], v[190:193], v[144:147], v[118:121]
	v_mfma_f32_16x16x32_bf16 v[114:117], v[190:193], v[152:155], v[114:117]
	v_mfma_f32_16x16x32_bf16 v[110:113], v[198:201], v[144:147], v[110:113]
	v_mfma_f32_16x16x32_bf16 v[106:109], v[198:201], v[152:155], v[106:109]
	v_mfma_f32_16x16x32_bf16 v[102:105], v[206:209], v[144:147], v[102:105]
	v_mfma_f32_16x16x32_bf16 v[98:101], v[206:209], v[152:155], v[98:101]
	v_mfma_f32_16x16x32_bf16 v[126:129], v[164:167], v[148:151], v[126:129]
	v_mfma_f32_16x16x32_bf16 v[122:125], v[164:167], v[156:159], v[122:125]
	v_mfma_f32_16x16x32_bf16 v[118:121], v[194:197], v[148:151], v[118:121]
	v_mfma_f32_16x16x32_bf16 v[114:117], v[194:197], v[156:159], v[114:117]
	v_mfma_f32_16x16x32_bf16 v[110:113], v[202:205], v[148:151], v[110:113]
	v_mfma_f32_16x16x32_bf16 v[106:109], v[202:205], v[156:159], v[106:109]
	v_mfma_f32_16x16x32_bf16 v[102:105], v[210:213], v[148:151], v[102:105]
	v_mfma_f32_16x16x32_bf16 v[98:101], v[210:213], v[156:159], v[98:101]
	s_barrier
	s_add_i32 s17, 0, 0x1c000
	s_add_i32 s16, s16, s15
	v_add_u32_e32 v226, s17, v143
	v_lshl_add_u64 v[236:237], v[232:233], 0, s[18:19]
	s_mov_b32 m0, s16
	ds_read_b128 v[214:217], v226
	ds_read_b128 v[218:221], v226 offset:1024
	ds_read_b128 v[222:225], v226 offset:2048
	ds_read_b128 v[226:229], v226 offset:3072
	global_load_lds_dwordx4 v[236:237], off
	v_lshl_add_u64 v[236:237], v[234:235], 0, s[18:19]
	s_add_i32 m0, s16, 0x2000
	s_nop 0
	global_load_lds_dwordx4 v[236:237], off
	s_barrier
	s_waitcnt lgkmcnt(0)
	v_mfma_f32_16x16x32_bf16 v[94:97], v[160:163], v[214:217], v[94:97]
	v_mfma_f32_16x16x32_bf16 v[90:93], v[160:163], v[222:225], v[90:93]
	v_mfma_f32_16x16x32_bf16 v[86:89], v[190:193], v[214:217], v[86:89]
	v_mfma_f32_16x16x32_bf16 v[82:85], v[190:193], v[222:225], v[82:85]
	v_mfma_f32_16x16x32_bf16 v[78:81], v[198:201], v[214:217], v[78:81]
	v_mfma_f32_16x16x32_bf16 v[74:77], v[198:201], v[222:225], v[74:77]
	v_mfma_f32_16x16x32_bf16 v[70:73], v[206:209], v[214:217], v[70:73]
	v_mfma_f32_16x16x32_bf16 v[66:69], v[206:209], v[222:225], v[66:69]
	v_mfma_f32_16x16x32_bf16 v[94:97], v[164:167], v[218:221], v[94:97]
	v_mfma_f32_16x16x32_bf16 v[90:93], v[164:167], v[226:229], v[90:93]
	v_mfma_f32_16x16x32_bf16 v[86:89], v[194:197], v[218:221], v[86:89]
	v_mfma_f32_16x16x32_bf16 v[82:85], v[194:197], v[226:229], v[82:85]
	v_mfma_f32_16x16x32_bf16 v[78:81], v[202:205], v[218:221], v[78:81]
	v_mfma_f32_16x16x32_bf16 v[74:77], v[202:205], v[226:229], v[74:77]
	v_mfma_f32_16x16x32_bf16 v[70:73], v[210:213], v[218:221], v[70:73]
	v_mfma_f32_16x16x32_bf16 v[66:69], v[210:213], v[226:229], v[66:69]
	s_barrier
	s_mov_b32 m0, s56
	v_lshl_add_u64 v[138:139], v[138:139], 0, s[34:35]
	ds_read_b128 v[160:163], v142 offset:49152
	ds_read_b128 v[164:167], v142 offset:50176
	ds_read_b128 v[190:193], v142 offset:51200
	ds_read_b128 v[194:197], v142 offset:52224
	ds_read_b128 v[198:201], v142 offset:53248
	ds_read_b128 v[202:205], v142 offset:54272
	ds_read_b128 v[206:209], v142 offset:55296
	ds_read_b128 v[210:213], v142 offset:56320
	global_load_lds_dwordx4 v[138:139], off
	s_mov_b32 m0, s57
	v_lshl_add_u64 v[138:139], v[230:231], 0, s[34:35]
	global_load_lds_dwordx4 v[138:139], off
	s_barrier
;     __device__ __forceinline__ unsigned* BAR() const { return (unsigned*)(ws + OFF_BAR); }
; #define STAGE(bufoff, gbase, voff) do { _Pragma("unroll") for (int _i = 0; _i < 2; ++_i) \
;         __builtin_amdgcn_global_load_lds((const unsigned*)((const char*)(gbase) + voff[_i]), (LAS unsigned*)(lds + (bufoff) + ldsw + _i * 8192), 16, 0, 0); } while (0)
; #define LDA(dst, b, h) do { _Pragma("unroll") for (int m = 0; m < 4; ++m) _Pragma("unroll") for (int k = 0; k < 2; ++k) dst[m][k] = *(const LAS bf16x8*)(lds + SA(b, h) + aoff + m * 2048 + k * 1024); } while (0)
; #define LDB(dst, b, h) do { _Pragma("unroll") for (int n = 0; n < 2; ++n) _Pragma("unroll") for (int k = 0; k < 2; ++k) dst[n][k] = *(const LAS bf16x8*)(lds + SB(b, h) + boff + n * 2048 + k * 1024); } while (0)
; #define WAIT_V(n) asm volatile("s_waitcnt vmcnt(" #n ")" ::: "memory")
;     ...
;     for (int t = 0; t < nt - 2; t += 2) {
;         if (KSEG && t > 0 && (t % (KSEG ? KSEG : 1)) == 0) hook(t / (KSEG ? KSEG : 1), acc);
;         const char* a1 = pA(t + 1); const char* a2 = pA(t + 2); const char* a3 = pA(t + 3);
;         const char* b2 = pB(t + 2); const char* b3 = pB(t + 3);
;         LDB(B0, 0, 0); SCHED; LDA(At, 0, 0); STAGE(SA(1, 1), a1 + hstepA, voffA);
;         WAIT_L(8); BAR; WAIT_L(0); MMA(0, 0, At, B0); BAR; SCHED;
;         LDB(B1, 0, 1); STAGE(SB(0, 0), b2, voffB);
;         BAR; WAIT_L(0); MMA(0, 1, At, B1); BAR;
;         LDA(At, 0, 1); STAGE(SA(0, 0), a2, voffA);
;         BAR; WAIT_L(0); MMA(1, 0, At, B0); BAR; SCHED;
;         STAGE(SB(0, 1), b2 + hstepB, voffB);
;         WAIT_V(6); BAR; MMA(1, 1, At, B1); BAR;
;         LDB(B0, 1, 0); SCHED; LDA(At, 1, 0); STAGE(SA(0, 1), a2 + hstepA, voffA);
;         WAIT_L(8); BAR; WAIT_L(0); MMA(0, 0, At, B0); BAR; SCHED;
;         LDB(B1, 1, 1); STAGE(SB(1, 0), b3, voffB);
;         BAR; WAIT_L(0); MMA(0, 1, At, B1); BAR;
;         LDA(At, 1, 1); STAGE(SA(1, 0), a3, voffA);
;         BAR; WAIT_L(0); MMA(1, 0, At, B0); BAR; SCHED;
;         STAGE(SB(1, 1), b3 + hstepB, voffB);
;         WAIT_V(6); BAR; MMA(1, 1, At, B1); BAR;
;     }
;     { LDB(B0, 0, 0); LDA(At, 0, 0); STAGE(SA(1, 1), pA(nt - 1) + hstepA, voffA);
;       BAR; WAIT_L(0); MMA(0, 0, At, B0); BAR;
;       LDB(B1, 0, 1); BAR; WAIT_L(0); MMA(0, 1, At, B1); BAR;
;       LDA(At, 0, 1); WAIT_V(4); BAR; WAIT_L(0); MMA(1, 0, At, B0); MMA(1, 1, At, B1); BAR; }
	s_waitcnt lgkmcnt(0)
	v_mfma_f32_16x16x32_bf16 v[62:65], v[160:163], v[144:147], v[62:65]
	v_mfma_f32_16x16x32_bf16 v[58:61], v[160:163], v[152:155], v[58:61]
	v_mfma_f32_16x16x32_bf16 v[54:57], v[190:193], v[144:147], v[54:57]
	v_mfma_f32_16x16x32_bf16 v[50:53], v[190:193], v[152:155], v[50:53]
	v_mfma_f32_16x16x32_bf16 v[46:49], v[198:201], v[144:147], v[46:49]
	v_mfma_f32_16x16x32_bf16 v[42:45], v[198:201], v[152:155], v[42:45]
	v_mfma_f32_16x16x32_bf16 v[38:41], v[206:209], v[144:147], v[38:41]
	v_mfma_f32_16x16x32_bf16 v[34:37], v[206:209], v[152:155], v[34:37]
	v_mfma_f32_16x16x32_bf16 v[62:65], v[164:167], v[148:151], v[62:65]
	v_mfma_f32_16x16x32_bf16 v[58:61], v[164:167], v[156:159], v[58:61]
	v_mfma_f32_16x16x32_bf16 v[54:57], v[194:197], v[148:151], v[54:57]
	v_mfma_f32_16x16x32_bf16 v[50:53], v[194:197], v[156:159], v[50:53]
	v_mfma_f32_16x16x32_bf16 v[46:49], v[202:205], v[148:151], v[46:49]
	v_mfma_f32_16x16x32_bf16 v[42:45], v[202:205], v[156:159], v[42:45]
	v_mfma_f32_16x16x32_bf16 v[38:41], v[210:213], v[148:151], v[38:41]
	v_mfma_f32_16x16x32_bf16 v[34:37], v[210:213], v[156:159], v[34:37]
	s_barrier
	s_add_i32 s16, s17, s15
	s_mov_b32 m0, s16
	v_lshl_add_u64 v[138:139], v[232:233], 0, s[86:87]
	global_load_lds_dwordx4 v[138:139], off
	v_lshl_add_u64 v[138:139], v[234:235], 0, s[86:87]
	s_add_i32 m0, s16, 0x2000
	s_nop 0
	global_load_lds_dwordx4 v[138:139], off
	s_waitcnt vmcnt(6)
	s_barrier
	v_mfma_f32_16x16x32_bf16 v[30:33], v[160:163], v[214:217], v[30:33]
	v_mfma_f32_16x16x32_bf16 v[26:29], v[160:163], v[222:225], v[26:29]
	v_mfma_f32_16x16x32_bf16 v[22:25], v[190:193], v[214:217], v[22:25]
	v_mfma_f32_16x16x32_bf16 v[18:21], v[190:193], v[222:225], v[18:21]
	v_mfma_f32_16x16x32_bf16 v[14:17], v[198:201], v[214:217], v[14:17]
	v_mfma_f32_16x16x32_bf16 v[10:13], v[198:201], v[222:225], v[10:13]
	v_mfma_f32_16x16x32_bf16 v[6:9], v[206:209], v[214:217], v[6:9]
	v_mfma_f32_16x16x32_bf16 v[2:5], v[206:209], v[222:225], v[2:5]
	v_mfma_f32_16x16x32_bf16 v[30:33], v[164:167], v[218:221], v[30:33]
	v_mfma_f32_16x16x32_bf16 v[26:29], v[164:167], v[226:229], v[26:29]
	v_mfma_f32_16x16x32_bf16 v[22:25], v[194:197], v[218:221], v[22:25]
	v_mfma_f32_16x16x32_bf16 v[18:21], v[194:197], v[226:229], v[18:21]
	v_mfma_f32_16x16x32_bf16 v[14:17], v[202:205], v[218:221], v[14:17]
	v_mfma_f32_16x16x32_bf16 v[10:13], v[202:205], v[226:229], v[10:13]
	v_mfma_f32_16x16x32_bf16 v[6:9], v[210:213], v[218:221], v[6:9]
	v_mfma_f32_16x16x32_bf16 v[2:5], v[210:213], v[226:229], v[2:5]
	s_barrier
	s_add_i32 s10, s10, 2
	s_add_u32 s8, s8, 0x100
	s_addc_u32 s9, s9, 0
	s_cmp_gt_u32 s10, 11
	s_cbranch_scc0 .LBB0_617
	v_add_u32_e32 v143, 0, v143
	s_add_u32 s6, s6, 0x40780
	v_add_u32_e32 v140, 0x10000, v143
	s_addc_u32 s7, s7, 0
	s_mov_b32 m0, s88
	ds_read_b128 v[132:135], v140
	ds_read_b128 v[136:139], v140 offset:1024
	ds_read_b128 v[144:147], v140 offset:2048
	ds_read_b128 v[148:151], v140 offset:3072
	ds_read_b128 v[152:155], v142
	ds_read_b128 v[156:159], v142 offset:1024
	ds_read_b128 v[160:163], v142 offset:2048
	ds_read_b128 v[164:167], v142 offset:3072
	ds_read_b128 v[190:193], v142 offset:4096
	ds_read_b128 v[194:197], v142 offset:5120
	ds_read_b128 v[198:201], v142 offset:6144
	ds_read_b128 v[202:205], v142 offset:7168
	v_lshl_add_u64 v[140:141], s[6:7], 0, v[0:1]
	global_load_lds_dwordx4 v[140:141], off
	s_mov_b32 m0, s11
	v_lshl_add_u64 v[130:131], s[6:7], 0, v[130:131]
	global_load_lds_dwordx4 v[130:131], off
	s_barrier
	s_waitcnt lgkmcnt(0)
	v_mfma_f32_16x16x32_bf16 v[126:129], v[152:155], v[132:135], v[126:129]
	v_mfma_f32_16x16x32_bf16 v[122:125], v[152:155], v[144:147], v[122:125]
	v_mfma_f32_16x16x32_bf16 v[118:121], v[160:163], v[132:135], v[118:121]
	v_mfma_f32_16x16x32_bf16 v[114:117], v[160:163], v[144:147], v[114:117]
	v_mfma_f32_16x16x32_bf16 v[110:113], v[190:193], v[132:135], v[110:113]
	v_mfma_f32_16x16x32_bf16 v[106:109], v[190:193], v[144:147], v[106:109]
	v_mfma_f32_16x16x32_bf16 v[102:105], v[198:201], v[132:135], v[102:105]
	v_mfma_f32_16x16x32_bf16 v[98:101], v[198:201], v[144:147], v[98:101]
	v_mfma_f32_16x16x32_bf16 v[126:129], v[156:159], v[136:139], v[126:129]
	v_mfma_f32_16x16x32_bf16 v[122:125], v[156:159], v[148:151], v[122:125]
	v_mfma_f32_16x16x32_bf16 v[118:121], v[164:167], v[136:139], v[118:121]
	v_mfma_f32_16x16x32_bf16 v[114:117], v[164:167], v[148:151], v[114:117]
	v_mfma_f32_16x16x32_bf16 v[110:113], v[194:197], v[136:139], v[110:113]
	v_mfma_f32_16x16x32_bf16 v[106:109], v[194:197], v[148:151], v[106:109]
	v_mfma_f32_16x16x32_bf16 v[102:105], v[202:205], v[136:139], v[102:105]
	v_mfma_f32_16x16x32_bf16 v[98:101], v[202:205], v[148:151], v[98:101]
	v_add_u32_e32 v0, 0x14000, v143
	s_barrier
	ds_read_b128 v[206:209], v0
	ds_read_b128 v[210:213], v0 offset:1024
	ds_read_b128 v[214:217], v0 offset:2048
	ds_read_b128 v[218:221], v0 offset:3072
	s_barrier
	s_waitcnt lgkmcnt(0)
	v_mfma_f32_16x16x32_bf16 v[66:69], v[198:201], v[214:217], v[66:69]
	v_mfma_f32_16x16x32_bf16 v[94:97], v[152:155], v[206:209], v[94:97]
	v_mfma_f32_16x16x32_bf16 v[90:93], v[152:155], v[214:217], v[90:93]
	v_mfma_f32_16x16x32_bf16 v[86:89], v[160:163], v[206:209], v[86:89]
	v_mfma_f32_16x16x32_bf16 v[82:85], v[160:163], v[214:217], v[82:85]
	v_mfma_f32_16x16x32_bf16 v[78:81], v[190:193], v[206:209], v[78:81]
	v_mfma_f32_16x16x32_bf16 v[74:77], v[190:193], v[214:217], v[74:77]
	v_mfma_f32_16x16x32_bf16 v[70:73], v[198:201], v[206:209], v[70:73]
	v_mfma_f32_16x16x32_bf16 v[66:69], v[202:205], v[218:221], v[66:69]
	v_mfma_f32_16x16x32_bf16 v[222:225], v[156:159], v[210:213], v[94:97]
	v_mfma_f32_16x16x32_bf16 v[152:155], v[156:159], v[218:221], v[90:93]
	v_mfma_f32_16x16x32_bf16 v[156:159], v[164:167], v[210:213], v[86:89]
	v_mfma_f32_16x16x32_bf16 v[160:163], v[164:167], v[218:221], v[82:85]
	v_mfma_f32_16x16x32_bf16 v[164:167], v[194:197], v[210:213], v[78:81]
	v_mfma_f32_16x16x32_bf16 v[190:193], v[194:197], v[218:221], v[74:77]
	v_mfma_f32_16x16x32_bf16 v[194:197], v[202:205], v[210:213], v[70:73]
	s_barrier
;     __device__ __forceinline__ unsigned* BAR() const { return (unsigned*)(ws + OFF_BAR); }
; #define LDA(dst, b, h) do { _Pragma("unroll") for (int m = 0; m < 4; ++m) _Pragma("unroll") for (int k = 0; k < 2; ++k) dst[m][k] = *(const LAS bf16x8*)(lds + SA(b, h) + aoff + m * 2048 + k * 1024); } while (0)
; #define LDB(dst, b, h) do { _Pragma("unroll") for (int n = 0; n < 2; ++n) _Pragma("unroll") for (int k = 0; k < 2; ++k) dst[n][k] = *(const LAS bf16x8*)(lds + SB(b, h) + boff + n * 2048 + k * 1024); } while (0)
; #define MMA(ai, bj, At, Bx) do { __builtin_amdgcn_s_setprio(1); _Pragma("unroll") for (int m = 0; m < 4; ++m) _Pragma("unroll") for (int n = 0; n < 2; ++n) _Pragma("unroll") for (int k = 0; k < 2; ++k) \
;       acc[ai][bj][m][n] = __builtin_amdgcn_mfma_f32_16x16x32_bf16(At[m][k], Bx[n][k], acc[ai][bj][m][n], 0, 0, 0); \
;     __builtin_amdgcn_s_setprio(0); } while (0)
; #define WAIT_V(n) asm volatile("s_waitcnt vmcnt(" #n ")" ::: "memory")
; #define WAIT_L(n) asm volatile("s_waitcnt lgkmcnt(" #n ")" ::: "memory")
; #define BAR __builtin_amdgcn_s_barrier()
;     ...
;     { LDB(B0, 1, 0); LDA(At, 1, 0); WAIT_V(2); BAR; WAIT_L(0); MMA(0, 0, At, B0); BAR;
;       LDB(B1, 1, 1); WAIT_V(0); BAR; WAIT_L(0); MMA(0, 1, At, B1); BAR;
;       LDA(At, 1, 1); BAR; WAIT_L(0); MMA(1, 0, At, B0); MMA(1, 1, At, B1); BAR; }
	s_nop 0
	ds_read_b128 v[70:73], v142 offset:16384
	ds_read_b128 v[74:77], v142 offset:17408
	ds_read_b128 v[78:81], v142 offset:18432
	ds_read_b128 v[82:85], v142 offset:19456
	ds_read_b128 v[86:89], v142 offset:20480
	ds_read_b128 v[90:93], v142 offset:21504
	ds_read_b128 v[94:97], v142 offset:22528
	ds_read_b128 v[198:201], v142 offset:23552
	s_waitcnt vmcnt(4)
	s_barrier
	s_waitcnt lgkmcnt(0)
	v_mfma_f32_16x16x32_bf16 v[62:65], v[70:73], v[132:135], v[62:65]
	v_mfma_f32_16x16x32_bf16 v[58:61], v[70:73], v[144:147], v[58:61]
	v_mfma_f32_16x16x32_bf16 v[54:57], v[78:81], v[132:135], v[54:57]
	v_mfma_f32_16x16x32_bf16 v[50:53], v[78:81], v[144:147], v[50:53]
	v_mfma_f32_16x16x32_bf16 v[34:37], v[94:97], v[144:147], v[34:37]
	v_mfma_f32_16x16x32_bf16 v[62:65], v[74:77], v[136:139], v[62:65]
	v_mfma_f32_16x16x32_bf16 v[58:61], v[74:77], v[148:151], v[58:61]
	v_mfma_f32_16x16x32_bf16 v[54:57], v[82:85], v[136:139], v[54:57]
	v_mfma_f32_16x16x32_bf16 v[50:53], v[82:85], v[148:151], v[50:53]
	v_mfma_f32_16x16x32_bf16 v[46:49], v[86:89], v[132:135], v[46:49]
	v_mfma_f32_16x16x32_bf16 v[42:45], v[86:89], v[144:147], v[42:45]
	v_mfma_f32_16x16x32_bf16 v[38:41], v[94:97], v[132:135], v[38:41]
	v_mfma_f32_16x16x32_bf16 v[34:37], v[198:201], v[148:151], v[34:37]
	v_mfma_f32_16x16x32_bf16 v[202:205], v[90:93], v[136:139], v[46:49]
	v_mfma_f32_16x16x32_bf16 v[226:229], v[90:93], v[148:151], v[42:45]
	v_mfma_f32_16x16x32_bf16 v[130:133], v[198:201], v[136:139], v[38:41]
	v_mfma_f32_16x16x32_bf16 v[30:33], v[70:73], v[206:209], v[30:33]
	v_mfma_f32_16x16x32_bf16 v[26:29], v[70:73], v[214:217], v[26:29]
	v_mfma_f32_16x16x32_bf16 v[22:25], v[78:81], v[206:209], v[22:25]
	v_mfma_f32_16x16x32_bf16 v[18:21], v[78:81], v[214:217], v[18:21]
	v_mfma_f32_16x16x32_bf16 v[2:5], v[94:97], v[214:217], v[2:5]
	v_mfma_f32_16x16x32_bf16 v[30:33], v[74:77], v[210:213], v[30:33]
	v_mfma_f32_16x16x32_bf16 v[26:29], v[74:77], v[218:221], v[26:29]
	v_mfma_f32_16x16x32_bf16 v[22:25], v[82:85], v[210:213], v[22:25]
	v_mfma_f32_16x16x32_bf16 v[18:21], v[82:85], v[218:221], v[18:21]
	v_mfma_f32_16x16x32_bf16 v[14:17], v[86:89], v[206:209], v[14:17]
	v_mfma_f32_16x16x32_bf16 v[10:13], v[86:89], v[214:217], v[10:13]
	v_mfma_f32_16x16x32_bf16 v[6:9], v[94:97], v[206:209], v[6:9]
	v_mfma_f32_16x16x32_bf16 v[2:5], v[198:201], v[218:221], v[2:5]
	v_mfma_f32_16x16x32_bf16 v[134:137], v[90:93], v[210:213], v[14:17]
	v_mfma_f32_16x16x32_bf16 v[138:141], v[90:93], v[218:221], v[10:13]
	v_mfma_f32_16x16x32_bf16 v[144:147], v[198:201], v[210:213], v[6:9]
	v_add_u32_e32 v0, 0x18000, v143
	s_barrier
	s_nop 0
	ds_read_b128 v[6:9], v0
	ds_read_b128 v[10:13], v0 offset:1024
	ds_read_b128 v[14:17], v0 offset:2048
	ds_read_b128 v[148:151], v0 offset:3072
	ds_read_b128 v[38:41], v142 offset:32768
	ds_read_b128 v[42:45], v142 offset:33792
	ds_read_b128 v[46:49], v142 offset:34816
	ds_read_b128 v[70:73], v142 offset:35840
	ds_read_b128 v[198:201], v142 offset:36864
	ds_read_b128 v[206:209], v142 offset:37888
	ds_read_b128 v[210:213], v142 offset:38912
	ds_read_b128 v[214:217], v142 offset:39936
	s_waitcnt vmcnt(2)
	s_barrier
	s_waitcnt lgkmcnt(0)
	v_mfma_f32_16x16x32_bf16 v[74:77], v[38:41], v[6:9], v[126:129]
	v_mfma_f32_16x16x32_bf16 v[126:129], v[42:45], v[10:13], v[74:77]
	v_mfma_f32_16x16x32_bf16 v[74:77], v[38:41], v[14:17], v[122:125]
	v_mfma_f32_16x16x32_bf16 v[94:97], v[42:45], v[148:151], v[74:77]
	v_mfma_f32_16x16x32_bf16 v[74:77], v[46:49], v[6:9], v[118:121]
	v_mfma_f32_16x16x32_bf16 v[122:125], v[70:73], v[10:13], v[74:77]
	v_mfma_f32_16x16x32_bf16 v[74:77], v[46:49], v[14:17], v[114:117]
	v_mfma_f32_16x16x32_bf16 v[90:93], v[70:73], v[148:151], v[74:77]
	v_mfma_f32_16x16x32_bf16 v[74:77], v[198:201], v[6:9], v[110:113]
	v_mfma_f32_16x16x32_bf16 v[118:121], v[206:209], v[10:13], v[74:77]
	v_mfma_f32_16x16x32_bf16 v[74:77], v[198:201], v[14:17], v[106:109]
	v_mfma_f32_16x16x32_bf16 v[86:89], v[206:209], v[148:151], v[74:77]
	v_mfma_f32_16x16x32_bf16 v[74:77], v[210:213], v[6:9], v[102:105]
	v_mfma_f32_16x16x32_bf16 v[114:117], v[214:217], v[10:13], v[74:77]
	v_mfma_f32_16x16x32_bf16 v[74:77], v[210:213], v[14:17], v[98:101]
	v_mfma_f32_16x16x32_bf16 v[82:85], v[214:217], v[148:151], v[74:77]
	v_add_u32_e32 v0, 0x1c000, v143
	s_barrier
;     __device__ __forceinline__ unsigned* BAR() const { return (unsigned*)(ws + OFF_BAR); }
; #define LDA(dst, b, h) do { _Pragma("unroll") for (int m = 0; m < 4; ++m) _Pragma("unroll") for (int k = 0; k < 2; ++k) dst[m][k] = *(const LAS bf16x8*)(lds + SA(b, h) + aoff + m * 2048 + k * 1024); } while (0)
; #define MMA(ai, bj, At, Bx) do { __builtin_amdgcn_s_setprio(1); _Pragma("unroll") for (int m = 0; m < 4; ++m) _Pragma("unroll") for (int n = 0; n < 2; ++n) _Pragma("unroll") for (int k = 0; k < 2; ++k) \
;       acc[ai][bj][m][n] = __builtin_amdgcn_mfma_f32_16x16x32_bf16(At[m][k], Bx[n][k], acc[ai][bj][m][n], 0, 0, 0); \
;     __builtin_amdgcn_s_setprio(0); } while (0)
; #define WAIT_L(n) asm volatile("s_waitcnt lgkmcnt(" #n ")" ::: "memory")
; #define BAR __builtin_amdgcn_s_barrier()
;     ...
;       LDA(At, 1, 1); BAR; WAIT_L(0); MMA(1, 0, At, B0); MMA(1, 1, At, B1); BAR; }
;     if (wr == 0) BAR;
; __device__ __forceinline__ void phase_gemm2(const Params& p, int layer, LAS unsigned char* lds) {
;     ...
;     for (int L = blockIdx.x; L < ntiles; L += gridDim.x) {
	ds_read_b128 v[218:221], v0
	ds_read_b128 v[230:233], v0 offset:1024
	ds_read_b128 v[234:237], v0 offset:2048
	ds_read_b128 v[238:241], v0 offset:3072
	s_waitcnt vmcnt(0)
	s_barrier
	s_waitcnt lgkmcnt(0)
	v_mfma_f32_16x16x32_bf16 v[74:77], v[38:41], v[218:221], v[222:225]
	v_mfma_f32_16x16x32_bf16 v[38:41], v[38:41], v[234:237], v[152:155]
	v_mfma_f32_16x16x32_bf16 v[78:81], v[42:45], v[238:241], v[38:41]
	v_mfma_f32_16x16x32_bf16 v[38:41], v[46:49], v[218:221], v[156:159]
	v_mfma_f32_16x16x32_bf16 v[106:109], v[70:73], v[230:233], v[38:41]
	v_mfma_f32_16x16x32_bf16 v[38:41], v[46:49], v[234:237], v[160:163]
	v_mfma_f32_16x16x32_bf16 v[110:113], v[42:45], v[230:233], v[74:77]
	v_mfma_f32_16x16x32_bf16 v[74:77], v[70:73], v[238:241], v[38:41]
	v_mfma_f32_16x16x32_bf16 v[38:41], v[198:201], v[218:221], v[164:167]
	v_mfma_f32_16x16x32_bf16 v[102:105], v[206:209], v[230:233], v[38:41]
	v_mfma_f32_16x16x32_bf16 v[38:41], v[198:201], v[234:237], v[190:193]
	v_mfma_f32_16x16x32_bf16 v[70:73], v[206:209], v[238:241], v[38:41]
	v_mfma_f32_16x16x32_bf16 v[38:41], v[210:213], v[218:221], v[194:197]
	v_mfma_f32_16x16x32_bf16 v[98:101], v[214:217], v[230:233], v[38:41]
	v_mfma_f32_16x16x32_bf16 v[38:41], v[210:213], v[234:237], v[66:69]
	v_mfma_f32_16x16x32_bf16 v[66:69], v[214:217], v[238:241], v[38:41]
	s_barrier
	ds_read_b128 v[152:155], v142 offset:49152
	ds_read_b128 v[156:159], v142 offset:50176
	ds_read_b128 v[160:163], v142 offset:51200
	ds_read_b128 v[164:167], v142 offset:52224
	ds_read_b128 v[190:193], v142 offset:53248
	ds_read_b128 v[194:197], v142 offset:54272
	ds_read_b128 v[198:201], v142 offset:55296
	ds_read_b128 v[206:209], v142 offset:56320
	s_barrier
	s_waitcnt lgkmcnt(0)
	v_mfma_f32_16x16x32_bf16 v[38:41], v[152:155], v[6:9], v[62:65]
	v_mfma_f32_16x16x32_bf16 v[62:65], v[156:159], v[10:13], v[38:41]
	v_mfma_f32_16x16x32_bf16 v[38:41], v[152:155], v[14:17], v[58:61]
	v_mfma_f32_16x16x32_bf16 v[46:49], v[156:159], v[148:151], v[38:41]
	v_mfma_f32_16x16x32_bf16 v[38:41], v[160:163], v[6:9], v[54:57]
	v_mfma_f32_16x16x32_bf16 v[58:61], v[164:167], v[10:13], v[38:41]
	v_mfma_f32_16x16x32_bf16 v[38:41], v[160:163], v[14:17], v[50:53]
	v_mfma_f32_16x16x32_bf16 v[42:45], v[164:167], v[148:151], v[38:41]
	v_mfma_f32_16x16x32_bf16 v[38:41], v[190:193], v[6:9], v[202:205]
	v_mfma_f32_16x16x32_bf16 v[6:9], v[198:201], v[6:9], v[130:133]
	v_mfma_f32_16x16x32_bf16 v[54:57], v[194:197], v[10:13], v[38:41]
	v_mfma_f32_16x16x32_bf16 v[38:41], v[190:193], v[14:17], v[226:229]
	v_mfma_f32_16x16x32_bf16 v[50:53], v[206:209], v[10:13], v[6:9]
	v_mfma_f32_16x16x32_bf16 v[6:9], v[198:201], v[14:17], v[34:37]
	v_mfma_f32_16x16x32_bf16 v[38:41], v[194:197], v[148:151], v[38:41]
	v_mfma_f32_16x16x32_bf16 v[34:37], v[206:209], v[148:151], v[6:9]
	v_mfma_f32_16x16x32_bf16 v[6:9], v[152:155], v[218:221], v[30:33]
	v_mfma_f32_16x16x32_bf16 v[30:33], v[156:159], v[230:233], v[6:9]
	v_mfma_f32_16x16x32_bf16 v[6:9], v[152:155], v[234:237], v[26:29]
	v_mfma_f32_16x16x32_bf16 v[14:17], v[156:159], v[238:241], v[6:9]
	v_mfma_f32_16x16x32_bf16 v[6:9], v[160:163], v[218:221], v[22:25]
	v_mfma_f32_16x16x32_bf16 v[26:29], v[164:167], v[230:233], v[6:9]
	v_mfma_f32_16x16x32_bf16 v[6:9], v[160:163], v[234:237], v[18:21]
	v_mfma_f32_16x16x32_bf16 v[10:13], v[164:167], v[238:241], v[6:9]
	v_mfma_f32_16x16x32_bf16 v[6:9], v[190:193], v[218:221], v[134:137]
	v_mfma_f32_16x16x32_bf16 v[22:25], v[194:197], v[230:233], v[6:9]
	v_mfma_f32_16x16x32_bf16 v[6:9], v[190:193], v[234:237], v[138:141]
	v_mfma_f32_16x16x32_bf16 v[18:21], v[198:201], v[218:221], v[144:147]
	v_mfma_f32_16x16x32_bf16 v[2:5], v[198:201], v[234:237], v[2:5]
	v_mfma_f32_16x16x32_bf16 v[6:9], v[194:197], v[238:241], v[6:9]
	v_mfma_f32_16x16x32_bf16 v[18:21], v[206:209], v[230:233], v[18:21]
	v_mfma_f32_16x16x32_bf16 v[2:5], v[206:209], v[238:241], v[2:5]
	s_cmpk_lt_u32 s14, 0x100
	s_barrier
	s_cbranch_scc0 .LBB0_620
	s_barrier
